# GEMM K-loops: loop-control SALU block moved in front of the loop-back barrier (back-edge rotation)
# baseline (speedup 1.0000x reference)
.LBB0_372:
	s_ashr_i32 s21, s20, 31
	s_lshl_b64 s[22:23], s[20:21], 19
	s_add_u32 s22, s96, s22
	s_addc_u32 s23, s97, s23
	s_and_b64 s[24:25], s[4:5], exec
	s_cselect_b32 s21, s23, s29
	s_cselect_b32 s27, s22, s28
	s_ashr_i32 s13, s12, 31
	s_lshl_b64 s[24:25], s[12:13], 19
	s_add_u32 s24, s14, s24
	s_addc_u32 s25, s15, s25
	s_and_b64 s[36:37], s[4:5], exec
	s_cselect_b32 s13, s25, s31
	s_cselect_b32 s48, s24, s30
	s_add_u32 s49, s30, 0x100
	s_addc_u32 s50, s31, 0
	s_mov_b32 s51, -2
	ds_read_b128 v[150:153], v180
	ds_read_b128 v[154:157], v180 offset:1024
	ds_read_b128 v[158:161], v180 offset:2048
	ds_read_b128 v[162:165], v180 offset:3072
	ds_read_b128 v[184:187], v181
	ds_read_b128 v[188:191], v181 offset:1024
	ds_read_b128 v[192:195], v181 offset:2048
	ds_read_b128 v[196:199], v181 offset:3072
	s_add_u32 s30, s28, 0x100
	s_addc_u32 s31, s29, 0
	s_cmp_eq_u32 s51, 12
	s_cselect_b32 s39, s21, s31
	s_cselect_b32 s38, s27, s30
	s_cselect_b32 s37, s13, s50
	s_cselect_b32 s36, s48, s49
	v_lshl_add_u64 v[166:167], s[28:29], 0, v[142:143]
	s_add_i32 m0, s17, 0xc000
	ds_read_b128 v[200:203], v182
	ds_read_b128 v[204:207], v182 offset:1024
	ds_read_b128 v[208:211], v182 offset:2048
	ds_read_b128 v[212:215], v182 offset:3072
	ds_read_b128 v[216:219], v182 offset:4096
	ds_read_b128 v[220:223], v182 offset:5120
	ds_read_b128 v[224:227], v182 offset:6144
	ds_read_b128 v[228:231], v182 offset:7168
	global_load_lds_dwordx4 v[166:167], off
	v_lshl_add_u64 v[166:167], s[28:29], 0, v[144:145]
	s_add_i32 m0, s17, 0xe000
	s_nop 0
	global_load_lds_dwordx4 v[166:167], off
	s_waitcnt vmcnt(8)
	s_waitcnt lgkmcnt(0)
	s_barrier
	s_setprio 1
	s_waitcnt lgkmcnt(0)
	v_mfma_f32_16x16x32_bf16 v[82:85], v[150:153], v[200:203], 0
	v_mfma_f32_16x16x32_bf16 v[78:81], v[158:161], v[200:203], 0
	v_mfma_f32_16x16x32_bf16 v[70:73], v[150:153], v[208:211], 0
	v_mfma_f32_16x16x32_bf16 v[66:69], v[158:161], v[208:211], 0
	v_mfma_f32_16x16x32_bf16 v[62:65], v[150:153], v[216:219], 0
	v_mfma_f32_16x16x32_bf16 v[58:61], v[158:161], v[216:219], 0
	v_mfma_f32_16x16x32_bf16 v[54:57], v[150:153], v[224:227], 0
	v_mfma_f32_16x16x32_bf16 v[50:53], v[158:161], v[224:227], 0
	v_mfma_f32_16x16x32_bf16 v[82:85], v[154:157], v[204:207], v[82:85]
	v_mfma_f32_16x16x32_bf16 v[78:81], v[162:165], v[204:207], v[78:81]
	v_mfma_f32_16x16x32_bf16 v[70:73], v[154:157], v[212:215], v[70:73]
	v_mfma_f32_16x16x32_bf16 v[66:69], v[162:165], v[212:215], v[66:69]
	v_mfma_f32_16x16x32_bf16 v[62:65], v[154:157], v[220:223], v[62:65]
	v_mfma_f32_16x16x32_bf16 v[58:61], v[162:165], v[220:223], v[58:61]
	v_mfma_f32_16x16x32_bf16 v[54:57], v[154:157], v[228:231], v[54:57]
	v_mfma_f32_16x16x32_bf16 v[50:53], v[162:165], v[228:231], v[50:53]
	s_setprio 0
	s_setprio 1
	v_mfma_f32_16x16x32_bf16 v[126:129], v[184:187], v[200:203], 0
	v_mfma_f32_16x16x32_bf16 v[122:125], v[192:195], v[200:203], 0
	v_mfma_f32_16x16x32_bf16 v[118:121], v[184:187], v[208:211], 0
	v_mfma_f32_16x16x32_bf16 v[114:117], v[192:195], v[208:211], 0
	v_mfma_f32_16x16x32_bf16 v[110:113], v[184:187], v[216:219], 0
	v_mfma_f32_16x16x32_bf16 v[106:109], v[192:195], v[216:219], 0
	v_mfma_f32_16x16x32_bf16 v[102:105], v[184:187], v[224:227], 0
	v_mfma_f32_16x16x32_bf16 v[98:101], v[192:195], v[224:227], 0
	v_mfma_f32_16x16x32_bf16 v[126:129], v[188:191], v[204:207], v[126:129]
	v_mfma_f32_16x16x32_bf16 v[122:125], v[196:199], v[204:207], v[122:125]
	v_mfma_f32_16x16x32_bf16 v[118:121], v[188:191], v[212:215], v[118:121]
	v_mfma_f32_16x16x32_bf16 v[114:117], v[196:199], v[212:215], v[114:117]
	v_mfma_f32_16x16x32_bf16 v[110:113], v[188:191], v[220:223], v[110:113]
	v_mfma_f32_16x16x32_bf16 v[106:109], v[196:199], v[220:223], v[106:109]
	v_mfma_f32_16x16x32_bf16 v[102:105], v[188:191], v[228:231], v[102:105]
	v_mfma_f32_16x16x32_bf16 v[98:101], v[196:199], v[228:231], v[98:101]
	s_setprio 0
	s_barrier
	s_add_i32 s28, s45, s16
	v_lshl_add_u64 v[166:167], s[36:37], 0, v[134:135]
	s_mov_b32 m0, s28
	ds_read_b128 v[200:203], v182 offset:16384
	ds_read_b128 v[204:207], v182 offset:17408
	ds_read_b128 v[208:211], v182 offset:18432
	ds_read_b128 v[212:215], v182 offset:19456
	ds_read_b128 v[216:219], v182 offset:20480
	ds_read_b128 v[220:223], v182 offset:21504
	ds_read_b128 v[224:227], v182 offset:22528
	ds_read_b128 v[228:231], v182 offset:23552
	global_load_lds_dwordx4 v[166:167], off
	s_add_i32 m0, s28, 0x2000
	s_add_u32 s28, s36, 0x40000
	v_lshl_add_u64 v[232:233], s[36:37], 0, v[136:137]
	s_addc_u32 s29, s37, 0
	s_add_i32 s52, s46, s16
	global_load_lds_dwordx4 v[232:233], off
	v_lshl_add_u64 v[234:235], s[28:29], 0, v[134:135]
	s_mov_b32 m0, s52
	v_lshl_add_u64 v[236:237], s[38:39], 0, v[130:131]
	global_load_lds_dwordx4 v[234:235], off
	v_lshl_add_u64 v[234:235], s[28:29], 0, v[136:137]
	s_add_i32 m0, s52, 0x2000
	s_nop 0
	global_load_lds_dwordx4 v[234:235], off
	v_lshl_add_u64 v[234:235], s[38:39], 0, v[132:133]
	s_mov_b32 m0, s17
	s_nop 0
	global_load_lds_dwordx4 v[234:235], off
	s_mov_b32 m0, s34
	s_nop 0
	global_load_lds_dwordx4 v[236:237], off
	s_waitcnt vmcnt(8)
	s_waitcnt lgkmcnt(0)
	s_barrier
	s_setprio 1
	s_waitcnt lgkmcnt(0)
	v_mfma_f32_16x16x32_bf16 v[38:41], v[150:153], v[200:203], 0
	v_mfma_f32_16x16x32_bf16 v[34:37], v[158:161], v[200:203], 0
	v_mfma_f32_16x16x32_bf16 v[26:29], v[150:153], v[208:211], 0
	v_mfma_f32_16x16x32_bf16 v[22:25], v[158:161], v[208:211], 0
	v_mfma_f32_16x16x32_bf16 v[14:17], v[150:153], v[216:219], 0
	v_mfma_f32_16x16x32_bf16 v[10:13], v[158:161], v[216:219], 0
	v_mfma_f32_16x16x32_bf16 v[6:9], v[150:153], v[224:227], 0
	v_mfma_f32_16x16x32_bf16 v[2:5], v[158:161], v[224:227], 0
	v_mfma_f32_16x16x32_bf16 v[38:41], v[154:157], v[204:207], v[38:41]
	v_mfma_f32_16x16x32_bf16 v[34:37], v[162:165], v[204:207], v[34:37]
	v_mfma_f32_16x16x32_bf16 v[26:29], v[154:157], v[212:215], v[26:29]
	v_mfma_f32_16x16x32_bf16 v[22:25], v[162:165], v[212:215], v[22:25]
	v_mfma_f32_16x16x32_bf16 v[14:17], v[154:157], v[220:223], v[14:17]
	v_mfma_f32_16x16x32_bf16 v[10:13], v[162:165], v[220:223], v[10:13]
	v_mfma_f32_16x16x32_bf16 v[6:9], v[154:157], v[228:231], v[6:9]
	v_mfma_f32_16x16x32_bf16 v[2:5], v[162:165], v[228:231], v[2:5]
	s_setprio 0
	s_setprio 1
	v_mfma_f32_16x16x32_bf16 v[94:97], v[184:187], v[200:203], 0
	v_mfma_f32_16x16x32_bf16 v[90:93], v[192:195], v[200:203], 0
	v_mfma_f32_16x16x32_bf16 v[86:89], v[184:187], v[208:211], 0
	v_mfma_f32_16x16x32_bf16 v[74:77], v[192:195], v[208:211], 0
	v_mfma_f32_16x16x32_bf16 v[46:49], v[184:187], v[216:219], 0
	v_mfma_f32_16x16x32_bf16 v[42:45], v[192:195], v[216:219], 0
	v_mfma_f32_16x16x32_bf16 v[30:33], v[184:187], v[224:227], 0
	v_mfma_f32_16x16x32_bf16 v[18:21], v[192:195], v[224:227], 0
	v_mfma_f32_16x16x32_bf16 v[94:97], v[188:191], v[204:207], v[94:97]
	v_mfma_f32_16x16x32_bf16 v[90:93], v[196:199], v[204:207], v[90:93]
	v_mfma_f32_16x16x32_bf16 v[86:89], v[188:191], v[212:215], v[86:89]
	v_mfma_f32_16x16x32_bf16 v[74:77], v[196:199], v[212:215], v[74:77]
	v_mfma_f32_16x16x32_bf16 v[46:49], v[188:191], v[220:223], v[46:49]
	v_mfma_f32_16x16x32_bf16 v[42:45], v[196:199], v[220:223], v[42:45]
	v_mfma_f32_16x16x32_bf16 v[30:33], v[188:191], v[228:231], v[30:33]
	v_mfma_f32_16x16x32_bf16 v[18:21], v[196:199], v[228:231], v[18:21]
	s_setprio 0
	s_barrier
	s_add_i32 s52, 0, 0x18000
	v_add_u32_e32 v138, s52, v178
	s_add_i32 s53, 0, 0x1c000
	ds_read_b128 v[150:153], v138
	ds_read_b128 v[154:157], v138 offset:1024
	ds_read_b128 v[158:161], v138 offset:2048
	ds_read_b128 v[162:165], v138 offset:3072
	v_add_u32_e32 v138, s53, v178
	ds_read_b128 v[184:187], v138
	ds_read_b128 v[188:191], v138 offset:1024
	ds_read_b128 v[192:195], v138 offset:2048
	ds_read_b128 v[196:199], v138 offset:3072
	s_add_u32 s28, s38, 0x40000
	s_addc_u32 s29, s39, 0
	s_mov_b32 m0, s35
	v_lshl_add_u64 v[238:239], s[28:29], 0, v[132:133]
	ds_read_b128 v[200:203], v182 offset:32768
	ds_read_b128 v[204:207], v182 offset:33792
	ds_read_b128 v[208:211], v182 offset:34816
	ds_read_b128 v[212:215], v182 offset:35840
	ds_read_b128 v[216:219], v182 offset:36864
	ds_read_b128 v[220:223], v182 offset:37888
	ds_read_b128 v[224:227], v182 offset:38912
	ds_read_b128 v[228:231], v182 offset:39936
	global_load_lds_dwordx4 v[238:239], off
	v_lshl_add_u64 v[238:239], s[28:29], 0, v[130:131]
	s_mov_b32 m0, s40
	s_nop 0
	global_load_lds_dwordx4 v[238:239], off
	s_waitcnt vmcnt(8)
	s_waitcnt lgkmcnt(0)
	s_barrier
	s_setprio 1
	s_waitcnt lgkmcnt(0)
	v_mfma_f32_16x16x32_bf16 v[82:85], v[150:153], v[200:203], v[82:85]
	v_mfma_f32_16x16x32_bf16 v[78:81], v[158:161], v[200:203], v[78:81]
	v_mfma_f32_16x16x32_bf16 v[70:73], v[150:153], v[208:211], v[70:73]
	v_mfma_f32_16x16x32_bf16 v[66:69], v[158:161], v[208:211], v[66:69]
	v_mfma_f32_16x16x32_bf16 v[62:65], v[150:153], v[216:219], v[62:65]
	v_mfma_f32_16x16x32_bf16 v[58:61], v[158:161], v[216:219], v[58:61]
	v_mfma_f32_16x16x32_bf16 v[54:57], v[150:153], v[224:227], v[54:57]
	v_mfma_f32_16x16x32_bf16 v[50:53], v[158:161], v[224:227], v[50:53]
	v_mfma_f32_16x16x32_bf16 v[82:85], v[154:157], v[204:207], v[82:85]
	v_mfma_f32_16x16x32_bf16 v[78:81], v[162:165], v[204:207], v[78:81]
	v_mfma_f32_16x16x32_bf16 v[70:73], v[154:157], v[212:215], v[70:73]
	v_mfma_f32_16x16x32_bf16 v[66:69], v[162:165], v[212:215], v[66:69]
	v_mfma_f32_16x16x32_bf16 v[62:65], v[154:157], v[220:223], v[62:65]
	v_mfma_f32_16x16x32_bf16 v[58:61], v[162:165], v[220:223], v[58:61]
	v_mfma_f32_16x16x32_bf16 v[54:57], v[154:157], v[228:231], v[54:57]
	v_mfma_f32_16x16x32_bf16 v[50:53], v[162:165], v[228:231], v[50:53]
	s_setprio 0
	s_setprio 1
	v_mfma_f32_16x16x32_bf16 v[126:129], v[184:187], v[200:203], v[126:129]
	v_mfma_f32_16x16x32_bf16 v[122:125], v[192:195], v[200:203], v[122:125]
	v_mfma_f32_16x16x32_bf16 v[118:121], v[184:187], v[208:211], v[118:121]
	v_mfma_f32_16x16x32_bf16 v[114:117], v[192:195], v[208:211], v[114:117]
	v_mfma_f32_16x16x32_bf16 v[110:113], v[184:187], v[216:219], v[110:113]
	v_mfma_f32_16x16x32_bf16 v[106:109], v[192:195], v[216:219], v[106:109]
	v_mfma_f32_16x16x32_bf16 v[102:105], v[184:187], v[224:227], v[102:105]
	v_mfma_f32_16x16x32_bf16 v[98:101], v[192:195], v[224:227], v[98:101]
	v_mfma_f32_16x16x32_bf16 v[126:129], v[188:191], v[204:207], v[126:129]
	v_mfma_f32_16x16x32_bf16 v[122:125], v[196:199], v[204:207], v[122:125]
	v_mfma_f32_16x16x32_bf16 v[118:121], v[188:191], v[212:215], v[118:121]
	v_mfma_f32_16x16x32_bf16 v[114:117], v[196:199], v[212:215], v[114:117]
	v_mfma_f32_16x16x32_bf16 v[110:113], v[188:191], v[220:223], v[110:113]
	v_mfma_f32_16x16x32_bf16 v[106:109], v[196:199], v[220:223], v[106:109]
	v_mfma_f32_16x16x32_bf16 v[102:105], v[188:191], v[228:231], v[102:105]
	v_mfma_f32_16x16x32_bf16 v[98:101], v[196:199], v[228:231], v[98:101]
	s_setprio 0
	s_barrier
	s_add_i32 s28, s52, s16
	v_lshl_add_u64 v[166:167], v[166:167], 0, s[6:7]
	s_mov_b32 m0, s28
	ds_read_b128 v[200:203], v182 offset:49152
	ds_read_b128 v[204:207], v182 offset:50176
	ds_read_b128 v[208:211], v182 offset:51200
	ds_read_b128 v[212:215], v182 offset:52224
	ds_read_b128 v[216:219], v182 offset:53248
	ds_read_b128 v[220:223], v182 offset:54272
	ds_read_b128 v[224:227], v182 offset:55296
	ds_read_b128 v[228:231], v182 offset:56320
	global_load_lds_dwordx4 v[166:167], off
	s_add_i32 m0, s28, 0x2000
	s_add_u32 s28, s36, 0x40080
	v_lshl_add_u64 v[166:167], v[232:233], 0, s[6:7]
	s_addc_u32 s29, s37, 0
	s_add_i32 s36, s53, s16
	global_load_lds_dwordx4 v[166:167], off
	v_lshl_add_u64 v[166:167], s[28:29], 0, v[134:135]
	s_mov_b32 m0, s36
	s_nop 0
	global_load_lds_dwordx4 v[166:167], off
	v_lshl_add_u64 v[166:167], s[28:29], 0, v[136:137]
	s_add_i32 m0, s36, 0x2000
	s_nop 0
	global_load_lds_dwordx4 v[166:167], off
	v_lshl_add_u64 v[166:167], v[234:235], 0, s[6:7]
	s_mov_b32 m0, s42
	s_nop 0
	global_load_lds_dwordx4 v[166:167], off
	v_lshl_add_u64 v[166:167], v[236:237], 0, s[6:7]
	s_mov_b32 m0, s43
	s_nop 0
	global_load_lds_dwordx4 v[166:167], off
	s_waitcnt vmcnt(8)
	s_waitcnt lgkmcnt(0)
	s_barrier
	s_setprio 1
	s_waitcnt lgkmcnt(0)
	v_mfma_f32_16x16x32_bf16 v[38:41], v[150:153], v[200:203], v[38:41]
	v_mfma_f32_16x16x32_bf16 v[34:37], v[158:161], v[200:203], v[34:37]
	v_mfma_f32_16x16x32_bf16 v[26:29], v[150:153], v[208:211], v[26:29]
	v_mfma_f32_16x16x32_bf16 v[22:25], v[158:161], v[208:211], v[22:25]
	v_mfma_f32_16x16x32_bf16 v[14:17], v[150:153], v[216:219], v[14:17]
	v_mfma_f32_16x16x32_bf16 v[10:13], v[158:161], v[216:219], v[10:13]
	v_mfma_f32_16x16x32_bf16 v[6:9], v[150:153], v[224:227], v[6:9]
	v_mfma_f32_16x16x32_bf16 v[2:5], v[158:161], v[224:227], v[2:5]
	v_mfma_f32_16x16x32_bf16 v[38:41], v[154:157], v[204:207], v[38:41]
	v_mfma_f32_16x16x32_bf16 v[34:37], v[162:165], v[204:207], v[34:37]
	v_mfma_f32_16x16x32_bf16 v[26:29], v[154:157], v[212:215], v[26:29]
	v_mfma_f32_16x16x32_bf16 v[22:25], v[162:165], v[212:215], v[22:25]
	v_mfma_f32_16x16x32_bf16 v[14:17], v[154:157], v[220:223], v[14:17]
	v_mfma_f32_16x16x32_bf16 v[10:13], v[162:165], v[220:223], v[10:13]
	v_mfma_f32_16x16x32_bf16 v[6:9], v[154:157], v[228:231], v[6:9]
	v_mfma_f32_16x16x32_bf16 v[2:5], v[162:165], v[228:231], v[2:5]
	s_setprio 0
	s_setprio 1
	v_mfma_f32_16x16x32_bf16 v[94:97], v[184:187], v[200:203], v[94:97]
	v_mfma_f32_16x16x32_bf16 v[90:93], v[192:195], v[200:203], v[90:93]
	v_mfma_f32_16x16x32_bf16 v[86:89], v[184:187], v[208:211], v[86:89]
	v_mfma_f32_16x16x32_bf16 v[74:77], v[192:195], v[208:211], v[74:77]
	v_mfma_f32_16x16x32_bf16 v[46:49], v[184:187], v[216:219], v[46:49]
	v_mfma_f32_16x16x32_bf16 v[42:45], v[192:195], v[216:219], v[42:45]
	v_mfma_f32_16x16x32_bf16 v[30:33], v[184:187], v[224:227], v[30:33]
	v_mfma_f32_16x16x32_bf16 v[18:21], v[192:195], v[224:227], v[18:21]
	v_mfma_f32_16x16x32_bf16 v[94:97], v[188:191], v[204:207], v[94:97]
	v_mfma_f32_16x16x32_bf16 v[90:93], v[196:199], v[204:207], v[90:93]
	v_mfma_f32_16x16x32_bf16 v[86:89], v[188:191], v[212:215], v[86:89]
	v_mfma_f32_16x16x32_bf16 v[74:77], v[196:199], v[212:215], v[74:77]
	v_mfma_f32_16x16x32_bf16 v[46:49], v[188:191], v[220:223], v[46:49]
	v_mfma_f32_16x16x32_bf16 v[42:45], v[196:199], v[220:223], v[42:45]
	v_mfma_f32_16x16x32_bf16 v[30:33], v[188:191], v[228:231], v[30:33]
	v_mfma_f32_16x16x32_bf16 v[18:21], v[196:199], v[228:231], v[18:21]
	s_setprio 0
	s_add_i32 s51, s51, 2
	s_add_u32 s49, s49, 0x100
	s_addc_u32 s50, s50, 0
	s_cmp_gt_u32 s51, 13
	s_mov_b64 s[28:29], s[30:31]
	s_barrier
	s_cbranch_scc0 .LBB0_373
	s_branch .Lpeel_exit_373
.LBB0_373:
	ds_read_b128 v[150:153], v180
	ds_read_b128 v[154:157], v180 offset:1024
	ds_read_b128 v[158:161], v180 offset:2048
	ds_read_b128 v[162:165], v180 offset:3072
	ds_read_b128 v[184:187], v181
	ds_read_b128 v[188:191], v181 offset:1024
	ds_read_b128 v[192:195], v181 offset:2048
	ds_read_b128 v[196:199], v181 offset:3072
	s_add_u32 s30, s28, 0x100
	s_addc_u32 s31, s29, 0
	s_cmp_eq_u32 s51, 12
	s_cselect_b32 s39, s21, s31
	s_cselect_b32 s38, s27, s30
	s_cselect_b32 s37, s13, s50
	s_cselect_b32 s36, s48, s49
	v_lshl_add_u64 v[166:167], s[28:29], 0, v[142:143]
	s_add_i32 m0, s17, 0xc000
	ds_read_b128 v[200:203], v182
	ds_read_b128 v[204:207], v182 offset:1024
	ds_read_b128 v[208:211], v182 offset:2048
	ds_read_b128 v[212:215], v182 offset:3072
	ds_read_b128 v[216:219], v182 offset:4096
	ds_read_b128 v[220:223], v182 offset:5120
	ds_read_b128 v[224:227], v182 offset:6144
	ds_read_b128 v[228:231], v182 offset:7168
	global_load_lds_dwordx4 v[166:167], off
	v_lshl_add_u64 v[166:167], s[28:29], 0, v[144:145]
	s_add_i32 m0, s17, 0xe000
	s_nop 0
	global_load_lds_dwordx4 v[166:167], off
	s_waitcnt vmcnt(8)
	s_waitcnt lgkmcnt(0)
	s_barrier
	s_setprio 1
	s_waitcnt lgkmcnt(0)
	v_mfma_f32_16x16x32_bf16 v[82:85], v[150:153], v[200:203], v[82:85]
	v_mfma_f32_16x16x32_bf16 v[78:81], v[158:161], v[200:203], v[78:81]
	v_mfma_f32_16x16x32_bf16 v[70:73], v[150:153], v[208:211], v[70:73]
	v_mfma_f32_16x16x32_bf16 v[66:69], v[158:161], v[208:211], v[66:69]
	v_mfma_f32_16x16x32_bf16 v[62:65], v[150:153], v[216:219], v[62:65]
	v_mfma_f32_16x16x32_bf16 v[58:61], v[158:161], v[216:219], v[58:61]
	v_mfma_f32_16x16x32_bf16 v[54:57], v[150:153], v[224:227], v[54:57]
	v_mfma_f32_16x16x32_bf16 v[50:53], v[158:161], v[224:227], v[50:53]
	v_mfma_f32_16x16x32_bf16 v[82:85], v[154:157], v[204:207], v[82:85]
	v_mfma_f32_16x16x32_bf16 v[78:81], v[162:165], v[204:207], v[78:81]
	v_mfma_f32_16x16x32_bf16 v[70:73], v[154:157], v[212:215], v[70:73]
	v_mfma_f32_16x16x32_bf16 v[66:69], v[162:165], v[212:215], v[66:69]
	v_mfma_f32_16x16x32_bf16 v[62:65], v[154:157], v[220:223], v[62:65]
	v_mfma_f32_16x16x32_bf16 v[58:61], v[162:165], v[220:223], v[58:61]
	v_mfma_f32_16x16x32_bf16 v[54:57], v[154:157], v[228:231], v[54:57]
	v_mfma_f32_16x16x32_bf16 v[50:53], v[162:165], v[228:231], v[50:53]
	s_setprio 0
	s_setprio 1
	v_mfma_f32_16x16x32_bf16 v[126:129], v[184:187], v[200:203], v[126:129]
	v_mfma_f32_16x16x32_bf16 v[122:125], v[192:195], v[200:203], v[122:125]
	v_mfma_f32_16x16x32_bf16 v[118:121], v[184:187], v[208:211], v[118:121]
	v_mfma_f32_16x16x32_bf16 v[114:117], v[192:195], v[208:211], v[114:117]
	v_mfma_f32_16x16x32_bf16 v[110:113], v[184:187], v[216:219], v[110:113]
	v_mfma_f32_16x16x32_bf16 v[106:109], v[192:195], v[216:219], v[106:109]
	v_mfma_f32_16x16x32_bf16 v[102:105], v[184:187], v[224:227], v[102:105]
	v_mfma_f32_16x16x32_bf16 v[98:101], v[192:195], v[224:227], v[98:101]
	v_mfma_f32_16x16x32_bf16 v[126:129], v[188:191], v[204:207], v[126:129]
	v_mfma_f32_16x16x32_bf16 v[122:125], v[196:199], v[204:207], v[122:125]
	v_mfma_f32_16x16x32_bf16 v[118:121], v[188:191], v[212:215], v[118:121]
	v_mfma_f32_16x16x32_bf16 v[114:117], v[196:199], v[212:215], v[114:117]
	v_mfma_f32_16x16x32_bf16 v[110:113], v[188:191], v[220:223], v[110:113]
	v_mfma_f32_16x16x32_bf16 v[106:109], v[196:199], v[220:223], v[106:109]
	v_mfma_f32_16x16x32_bf16 v[102:105], v[188:191], v[228:231], v[102:105]
	v_mfma_f32_16x16x32_bf16 v[98:101], v[196:199], v[228:231], v[98:101]
	s_setprio 0
	s_barrier
	s_add_i32 s28, s45, s16
	v_lshl_add_u64 v[166:167], s[36:37], 0, v[134:135]
	s_mov_b32 m0, s28
	ds_read_b128 v[200:203], v182 offset:16384
	ds_read_b128 v[204:207], v182 offset:17408
	ds_read_b128 v[208:211], v182 offset:18432
	ds_read_b128 v[212:215], v182 offset:19456
	ds_read_b128 v[216:219], v182 offset:20480
	ds_read_b128 v[220:223], v182 offset:21504
	ds_read_b128 v[224:227], v182 offset:22528
	ds_read_b128 v[228:231], v182 offset:23552
	global_load_lds_dwordx4 v[166:167], off
	s_add_i32 m0, s28, 0x2000
	s_add_u32 s28, s36, 0x40000
	v_lshl_add_u64 v[232:233], s[36:37], 0, v[136:137]
	s_addc_u32 s29, s37, 0
	s_add_i32 s52, s46, s16
	global_load_lds_dwordx4 v[232:233], off
	v_lshl_add_u64 v[234:235], s[28:29], 0, v[134:135]
	s_mov_b32 m0, s52
	v_lshl_add_u64 v[236:237], s[38:39], 0, v[130:131]
	global_load_lds_dwordx4 v[234:235], off
	v_lshl_add_u64 v[234:235], s[28:29], 0, v[136:137]
	s_add_i32 m0, s52, 0x2000
	s_nop 0
	global_load_lds_dwordx4 v[234:235], off
	v_lshl_add_u64 v[234:235], s[38:39], 0, v[132:133]
	s_mov_b32 m0, s17
	s_nop 0
	global_load_lds_dwordx4 v[234:235], off
	s_mov_b32 m0, s34
	s_nop 0
	global_load_lds_dwordx4 v[236:237], off
	s_waitcnt vmcnt(8)
	s_waitcnt lgkmcnt(0)
	s_barrier
	s_setprio 1
	s_waitcnt lgkmcnt(0)
	v_mfma_f32_16x16x32_bf16 v[38:41], v[150:153], v[200:203], v[38:41]
	v_mfma_f32_16x16x32_bf16 v[34:37], v[158:161], v[200:203], v[34:37]
	v_mfma_f32_16x16x32_bf16 v[26:29], v[150:153], v[208:211], v[26:29]
	v_mfma_f32_16x16x32_bf16 v[22:25], v[158:161], v[208:211], v[22:25]
	v_mfma_f32_16x16x32_bf16 v[14:17], v[150:153], v[216:219], v[14:17]
	v_mfma_f32_16x16x32_bf16 v[10:13], v[158:161], v[216:219], v[10:13]
	v_mfma_f32_16x16x32_bf16 v[6:9], v[150:153], v[224:227], v[6:9]
	v_mfma_f32_16x16x32_bf16 v[2:5], v[158:161], v[224:227], v[2:5]
	v_mfma_f32_16x16x32_bf16 v[38:41], v[154:157], v[204:207], v[38:41]
	v_mfma_f32_16x16x32_bf16 v[34:37], v[162:165], v[204:207], v[34:37]
	v_mfma_f32_16x16x32_bf16 v[26:29], v[154:157], v[212:215], v[26:29]
	v_mfma_f32_16x16x32_bf16 v[22:25], v[162:165], v[212:215], v[22:25]
	v_mfma_f32_16x16x32_bf16 v[14:17], v[154:157], v[220:223], v[14:17]
	v_mfma_f32_16x16x32_bf16 v[10:13], v[162:165], v[220:223], v[10:13]
	v_mfma_f32_16x16x32_bf16 v[6:9], v[154:157], v[228:231], v[6:9]
	v_mfma_f32_16x16x32_bf16 v[2:5], v[162:165], v[228:231], v[2:5]
	s_setprio 0
	s_setprio 1
	v_mfma_f32_16x16x32_bf16 v[94:97], v[184:187], v[200:203], v[94:97]
	v_mfma_f32_16x16x32_bf16 v[90:93], v[192:195], v[200:203], v[90:93]
	v_mfma_f32_16x16x32_bf16 v[86:89], v[184:187], v[208:211], v[86:89]
	v_mfma_f32_16x16x32_bf16 v[74:77], v[192:195], v[208:211], v[74:77]
	v_mfma_f32_16x16x32_bf16 v[46:49], v[184:187], v[216:219], v[46:49]
	v_mfma_f32_16x16x32_bf16 v[42:45], v[192:195], v[216:219], v[42:45]
	v_mfma_f32_16x16x32_bf16 v[30:33], v[184:187], v[224:227], v[30:33]
	v_mfma_f32_16x16x32_bf16 v[18:21], v[192:195], v[224:227], v[18:21]
	v_mfma_f32_16x16x32_bf16 v[94:97], v[188:191], v[204:207], v[94:97]
	v_mfma_f32_16x16x32_bf16 v[90:93], v[196:199], v[204:207], v[90:93]
	v_mfma_f32_16x16x32_bf16 v[86:89], v[188:191], v[212:215], v[86:89]
	v_mfma_f32_16x16x32_bf16 v[74:77], v[196:199], v[212:215], v[74:77]
	v_mfma_f32_16x16x32_bf16 v[46:49], v[188:191], v[220:223], v[46:49]
	v_mfma_f32_16x16x32_bf16 v[42:45], v[196:199], v[220:223], v[42:45]
	v_mfma_f32_16x16x32_bf16 v[30:33], v[188:191], v[228:231], v[30:33]
	v_mfma_f32_16x16x32_bf16 v[18:21], v[196:199], v[228:231], v[18:21]
	s_setprio 0
	s_barrier
	s_add_i32 s52, 0, 0x18000
	v_add_u32_e32 v138, s52, v178
	s_add_i32 s53, 0, 0x1c000
	ds_read_b128 v[150:153], v138
	ds_read_b128 v[154:157], v138 offset:1024
	ds_read_b128 v[158:161], v138 offset:2048
	ds_read_b128 v[162:165], v138 offset:3072
	v_add_u32_e32 v138, s53, v178
	ds_read_b128 v[184:187], v138
	ds_read_b128 v[188:191], v138 offset:1024
	ds_read_b128 v[192:195], v138 offset:2048
	ds_read_b128 v[196:199], v138 offset:3072
	s_add_u32 s28, s38, 0x40000
	s_addc_u32 s29, s39, 0
	s_mov_b32 m0, s35
	v_lshl_add_u64 v[238:239], s[28:29], 0, v[132:133]
	ds_read_b128 v[200:203], v182 offset:32768
	ds_read_b128 v[204:207], v182 offset:33792
	ds_read_b128 v[208:211], v182 offset:34816
	ds_read_b128 v[212:215], v182 offset:35840
	ds_read_b128 v[216:219], v182 offset:36864
	ds_read_b128 v[220:223], v182 offset:37888
	ds_read_b128 v[224:227], v182 offset:38912
	ds_read_b128 v[228:231], v182 offset:39936
	global_load_lds_dwordx4 v[238:239], off
	v_lshl_add_u64 v[238:239], s[28:29], 0, v[130:131]
	s_mov_b32 m0, s40
	s_nop 0
	global_load_lds_dwordx4 v[238:239], off
	s_waitcnt vmcnt(8)
	s_waitcnt lgkmcnt(0)
	s_barrier
	s_setprio 1
	s_waitcnt lgkmcnt(0)
	v_mfma_f32_16x16x32_bf16 v[82:85], v[150:153], v[200:203], v[82:85]
	v_mfma_f32_16x16x32_bf16 v[78:81], v[158:161], v[200:203], v[78:81]
	v_mfma_f32_16x16x32_bf16 v[70:73], v[150:153], v[208:211], v[70:73]
	v_mfma_f32_16x16x32_bf16 v[66:69], v[158:161], v[208:211], v[66:69]
	v_mfma_f32_16x16x32_bf16 v[62:65], v[150:153], v[216:219], v[62:65]
	v_mfma_f32_16x16x32_bf16 v[58:61], v[158:161], v[216:219], v[58:61]
	v_mfma_f32_16x16x32_bf16 v[54:57], v[150:153], v[224:227], v[54:57]
	v_mfma_f32_16x16x32_bf16 v[50:53], v[158:161], v[224:227], v[50:53]
	v_mfma_f32_16x16x32_bf16 v[82:85], v[154:157], v[204:207], v[82:85]
	v_mfma_f32_16x16x32_bf16 v[78:81], v[162:165], v[204:207], v[78:81]
	v_mfma_f32_16x16x32_bf16 v[70:73], v[154:157], v[212:215], v[70:73]
	v_mfma_f32_16x16x32_bf16 v[66:69], v[162:165], v[212:215], v[66:69]
	v_mfma_f32_16x16x32_bf16 v[62:65], v[154:157], v[220:223], v[62:65]
	v_mfma_f32_16x16x32_bf16 v[58:61], v[162:165], v[220:223], v[58:61]
	v_mfma_f32_16x16x32_bf16 v[54:57], v[154:157], v[228:231], v[54:57]
	v_mfma_f32_16x16x32_bf16 v[50:53], v[162:165], v[228:231], v[50:53]
	s_setprio 0
	s_setprio 1
	v_mfma_f32_16x16x32_bf16 v[126:129], v[184:187], v[200:203], v[126:129]
	v_mfma_f32_16x16x32_bf16 v[122:125], v[192:195], v[200:203], v[122:125]
	v_mfma_f32_16x16x32_bf16 v[118:121], v[184:187], v[208:211], v[118:121]
	v_mfma_f32_16x16x32_bf16 v[114:117], v[192:195], v[208:211], v[114:117]
	v_mfma_f32_16x16x32_bf16 v[110:113], v[184:187], v[216:219], v[110:113]
	v_mfma_f32_16x16x32_bf16 v[106:109], v[192:195], v[216:219], v[106:109]
	v_mfma_f32_16x16x32_bf16 v[102:105], v[184:187], v[224:227], v[102:105]
	v_mfma_f32_16x16x32_bf16 v[98:101], v[192:195], v[224:227], v[98:101]
	v_mfma_f32_16x16x32_bf16 v[126:129], v[188:191], v[204:207], v[126:129]
	v_mfma_f32_16x16x32_bf16 v[122:125], v[196:199], v[204:207], v[122:125]
	v_mfma_f32_16x16x32_bf16 v[118:121], v[188:191], v[212:215], v[118:121]
	v_mfma_f32_16x16x32_bf16 v[114:117], v[196:199], v[212:215], v[114:117]
	v_mfma_f32_16x16x32_bf16 v[110:113], v[188:191], v[220:223], v[110:113]
	v_mfma_f32_16x16x32_bf16 v[106:109], v[196:199], v[220:223], v[106:109]
	v_mfma_f32_16x16x32_bf16 v[102:105], v[188:191], v[228:231], v[102:105]
	v_mfma_f32_16x16x32_bf16 v[98:101], v[196:199], v[228:231], v[98:101]
	s_setprio 0
	s_barrier
	s_add_i32 s28, s52, s16
	v_lshl_add_u64 v[166:167], v[166:167], 0, s[6:7]
	s_mov_b32 m0, s28
	ds_read_b128 v[200:203], v182 offset:49152
	ds_read_b128 v[204:207], v182 offset:50176
	ds_read_b128 v[208:211], v182 offset:51200
	ds_read_b128 v[212:215], v182 offset:52224
	ds_read_b128 v[216:219], v182 offset:53248
	ds_read_b128 v[220:223], v182 offset:54272
	ds_read_b128 v[224:227], v182 offset:55296
	ds_read_b128 v[228:231], v182 offset:56320
	global_load_lds_dwordx4 v[166:167], off
	s_add_i32 m0, s28, 0x2000
	s_add_u32 s28, s36, 0x40080
	v_lshl_add_u64 v[166:167], v[232:233], 0, s[6:7]
	s_addc_u32 s29, s37, 0
	s_add_i32 s36, s53, s16
	global_load_lds_dwordx4 v[166:167], off
	v_lshl_add_u64 v[166:167], s[28:29], 0, v[134:135]
	s_mov_b32 m0, s36
	s_nop 0
	global_load_lds_dwordx4 v[166:167], off
	v_lshl_add_u64 v[166:167], s[28:29], 0, v[136:137]
	s_add_i32 m0, s36, 0x2000
	s_nop 0
	global_load_lds_dwordx4 v[166:167], off
	v_lshl_add_u64 v[166:167], v[234:235], 0, s[6:7]
	s_mov_b32 m0, s42
	s_nop 0
	global_load_lds_dwordx4 v[166:167], off
	v_lshl_add_u64 v[166:167], v[236:237], 0, s[6:7]
	s_mov_b32 m0, s43
	s_nop 0
	global_load_lds_dwordx4 v[166:167], off
	s_waitcnt vmcnt(8)
	s_waitcnt lgkmcnt(0)
	s_barrier
	s_setprio 1
	s_waitcnt lgkmcnt(0)
	v_mfma_f32_16x16x32_bf16 v[38:41], v[150:153], v[200:203], v[38:41]
	v_mfma_f32_16x16x32_bf16 v[34:37], v[158:161], v[200:203], v[34:37]
	v_mfma_f32_16x16x32_bf16 v[26:29], v[150:153], v[208:211], v[26:29]
	v_mfma_f32_16x16x32_bf16 v[22:25], v[158:161], v[208:211], v[22:25]
	v_mfma_f32_16x16x32_bf16 v[14:17], v[150:153], v[216:219], v[14:17]
	v_mfma_f32_16x16x32_bf16 v[10:13], v[158:161], v[216:219], v[10:13]
	v_mfma_f32_16x16x32_bf16 v[6:9], v[150:153], v[224:227], v[6:9]
	v_mfma_f32_16x16x32_bf16 v[2:5], v[158:161], v[224:227], v[2:5]
	v_mfma_f32_16x16x32_bf16 v[38:41], v[154:157], v[204:207], v[38:41]
	v_mfma_f32_16x16x32_bf16 v[34:37], v[162:165], v[204:207], v[34:37]
	v_mfma_f32_16x16x32_bf16 v[26:29], v[154:157], v[212:215], v[26:29]
	v_mfma_f32_16x16x32_bf16 v[22:25], v[162:165], v[212:215], v[22:25]
	v_mfma_f32_16x16x32_bf16 v[14:17], v[154:157], v[220:223], v[14:17]
	v_mfma_f32_16x16x32_bf16 v[10:13], v[162:165], v[220:223], v[10:13]
	v_mfma_f32_16x16x32_bf16 v[6:9], v[154:157], v[228:231], v[6:9]
	v_mfma_f32_16x16x32_bf16 v[2:5], v[162:165], v[228:231], v[2:5]
	s_setprio 0
	s_setprio 1
	v_mfma_f32_16x16x32_bf16 v[94:97], v[184:187], v[200:203], v[94:97]
	v_mfma_f32_16x16x32_bf16 v[90:93], v[192:195], v[200:203], v[90:93]
	v_mfma_f32_16x16x32_bf16 v[86:89], v[184:187], v[208:211], v[86:89]
	v_mfma_f32_16x16x32_bf16 v[74:77], v[192:195], v[208:211], v[74:77]
	v_mfma_f32_16x16x32_bf16 v[46:49], v[184:187], v[216:219], v[46:49]
	v_mfma_f32_16x16x32_bf16 v[42:45], v[192:195], v[216:219], v[42:45]
	v_mfma_f32_16x16x32_bf16 v[30:33], v[184:187], v[224:227], v[30:33]
	v_mfma_f32_16x16x32_bf16 v[18:21], v[192:195], v[224:227], v[18:21]
	v_mfma_f32_16x16x32_bf16 v[94:97], v[188:191], v[204:207], v[94:97]
	v_mfma_f32_16x16x32_bf16 v[90:93], v[196:199], v[204:207], v[90:93]
	v_mfma_f32_16x16x32_bf16 v[86:89], v[188:191], v[212:215], v[86:89]
	v_mfma_f32_16x16x32_bf16 v[74:77], v[196:199], v[212:215], v[74:77]
	v_mfma_f32_16x16x32_bf16 v[46:49], v[188:191], v[220:223], v[46:49]
	v_mfma_f32_16x16x32_bf16 v[42:45], v[196:199], v[220:223], v[42:45]
	v_mfma_f32_16x16x32_bf16 v[30:33], v[188:191], v[228:231], v[30:33]
	v_mfma_f32_16x16x32_bf16 v[18:21], v[196:199], v[228:231], v[18:21]
	s_setprio 0
	s_add_i32 s51, s51, 2
	s_add_u32 s49, s49, 0x100
	s_addc_u32 s50, s50, 0
	s_cmp_gt_u32 s51, 13
	s_mov_b64 s[28:29], s[30:31]
	s_barrier
	s_cbranch_scc0 .LBB0_373

.LBB0_404:
	s_ashr_i32 s29, s28, 31
	s_lshl_b64 s[30:31], s[28:29], 19
	s_add_u32 s30, s14, s30
	s_addc_u32 s31, s15, s31
	s_and_b64 s[34:35], s[24:25], exec
	s_cselect_b32 s5, s31, s41
	s_cselect_b32 s29, s30, s40
	s_ashr_i32 s27, s26, 31
	s_lshl_b64 s[34:35], s[26:27], 19
	s_add_u32 s36, s16, s34
	s_addc_u32 s37, s17, s35
	s_and_b64 s[34:35], s[24:25], exec
	s_cselect_b32 s27, s37, s43
	s_cselect_b32 s34, s36, s42
	s_add_u32 s35, s42, 0x100
	s_addc_u32 s39, s43, 0
	s_mov_b32 s61, -2
	ds_read_b128 v[140:143], v156
	ds_read_b128 v[144:147], v156 offset:1024
	ds_read_b128 v[148:151], v156 offset:2048
	ds_read_b128 v[164:167], v156 offset:3072
	ds_read_b128 v[168:171], v157
	ds_read_b128 v[178:181], v157 offset:1024
	ds_read_b128 v[182:185], v157 offset:2048
	ds_read_b128 v[186:189], v157 offset:3072
	s_add_u32 s42, s40, 0x100
	s_addc_u32 s43, s41, 0
	s_cmp_eq_u32 s61, 12
	s_cselect_b32 s47, s5, s43
	s_cselect_b32 s46, s29, s42
	s_cselect_b32 s45, s27, s39
	s_cselect_b32 s44, s34, s35
	v_lshl_add_u64 v[152:153], s[40:41], 0, v[136:137]
	s_add_i32 m0, s49, 0xc000
	ds_read_b128 v[190:193], v158
	ds_read_b128 v[194:197], v158 offset:1024
	ds_read_b128 v[198:201], v158 offset:2048
	ds_read_b128 v[202:205], v158 offset:3072
	ds_read_b128 v[206:209], v158 offset:4096
	ds_read_b128 v[210:213], v158 offset:5120
	ds_read_b128 v[214:217], v158 offset:6144
	ds_read_b128 v[218:221], v158 offset:7168
	global_load_lds_dwordx4 v[152:153], off
	v_lshl_add_u64 v[152:153], s[40:41], 0, v[138:139]
	s_add_i32 m0, s49, 0xe000
	s_nop 0
	global_load_lds_dwordx4 v[152:153], off
	s_waitcnt vmcnt(8)
	s_waitcnt lgkmcnt(0)
	s_barrier
	s_setprio 1
	s_waitcnt lgkmcnt(0)
	v_mfma_f32_16x16x32_bf16 v[126:129], v[140:143], v[190:193], 0
	v_mfma_f32_16x16x32_bf16 v[122:125], v[148:151], v[190:193], 0
	v_mfma_f32_16x16x32_bf16 v[110:113], v[140:143], v[198:201], 0
	v_mfma_f32_16x16x32_bf16 v[106:109], v[148:151], v[198:201], 0
	v_mfma_f32_16x16x32_bf16 v[94:97], v[140:143], v[206:209], 0
	v_mfma_f32_16x16x32_bf16 v[90:93], v[148:151], v[206:209], 0
	v_mfma_f32_16x16x32_bf16 v[78:81], v[140:143], v[214:217], 0
	v_mfma_f32_16x16x32_bf16 v[74:77], v[148:151], v[214:217], 0
	v_mfma_f32_16x16x32_bf16 v[126:129], v[144:147], v[194:197], v[126:129]
	v_mfma_f32_16x16x32_bf16 v[122:125], v[164:167], v[194:197], v[122:125]
	v_mfma_f32_16x16x32_bf16 v[110:113], v[144:147], v[202:205], v[110:113]
	v_mfma_f32_16x16x32_bf16 v[106:109], v[164:167], v[202:205], v[106:109]
	v_mfma_f32_16x16x32_bf16 v[94:97], v[144:147], v[210:213], v[94:97]
	v_mfma_f32_16x16x32_bf16 v[90:93], v[164:167], v[210:213], v[90:93]
	v_mfma_f32_16x16x32_bf16 v[78:81], v[144:147], v[218:221], v[78:81]
	v_mfma_f32_16x16x32_bf16 v[74:77], v[164:167], v[218:221], v[74:77]
	s_setprio 0
	s_setprio 1
	v_mfma_f32_16x16x32_bf16 v[118:121], v[168:171], v[190:193], 0
	v_mfma_f32_16x16x32_bf16 v[114:117], v[182:185], v[190:193], 0
	v_mfma_f32_16x16x32_bf16 v[102:105], v[168:171], v[198:201], 0
	v_mfma_f32_16x16x32_bf16 v[98:101], v[182:185], v[198:201], 0
	v_mfma_f32_16x16x32_bf16 v[86:89], v[168:171], v[206:209], 0
	v_mfma_f32_16x16x32_bf16 v[82:85], v[182:185], v[206:209], 0
	v_mfma_f32_16x16x32_bf16 v[70:73], v[168:171], v[214:217], 0
	v_mfma_f32_16x16x32_bf16 v[66:69], v[182:185], v[214:217], 0
	v_mfma_f32_16x16x32_bf16 v[118:121], v[178:181], v[194:197], v[118:121]
	v_mfma_f32_16x16x32_bf16 v[114:117], v[186:189], v[194:197], v[114:117]
	v_mfma_f32_16x16x32_bf16 v[102:105], v[178:181], v[202:205], v[102:105]
	v_mfma_f32_16x16x32_bf16 v[98:101], v[186:189], v[202:205], v[98:101]
	v_mfma_f32_16x16x32_bf16 v[86:89], v[178:181], v[210:213], v[86:89]
	v_mfma_f32_16x16x32_bf16 v[82:85], v[186:189], v[210:213], v[82:85]
	v_mfma_f32_16x16x32_bf16 v[70:73], v[178:181], v[218:221], v[70:73]
	v_mfma_f32_16x16x32_bf16 v[66:69], v[186:189], v[218:221], v[66:69]
	s_setprio 0
	s_barrier
	s_add_i32 s40, s59, s48
	v_lshl_add_u64 v[152:153], s[44:45], 0, v[132:133]
	s_mov_b32 m0, s40
	ds_read_b128 v[190:193], v158 offset:16384
	ds_read_b128 v[194:197], v158 offset:17408
	ds_read_b128 v[198:201], v158 offset:18432
	ds_read_b128 v[202:205], v158 offset:19456
	ds_read_b128 v[206:209], v158 offset:20480
	ds_read_b128 v[210:213], v158 offset:21504
	ds_read_b128 v[214:217], v158 offset:22528
	ds_read_b128 v[218:221], v158 offset:23552
	global_load_lds_dwordx4 v[152:153], off
	s_add_i32 m0, s40, 0x2000
	s_add_u32 s40, s44, 0x40000
	v_lshl_add_u64 v[172:173], s[44:45], 0, v[130:131]
	s_addc_u32 s41, s45, 0
	s_add_i32 s62, s60, s48
	global_load_lds_dwordx4 v[172:173], off
	v_lshl_add_u64 v[222:223], s[40:41], 0, v[132:133]
	s_mov_b32 m0, s62
	v_lshl_add_u64 v[224:225], s[46:47], 0, v[130:131]
	global_load_lds_dwordx4 v[222:223], off
	v_lshl_add_u64 v[222:223], s[40:41], 0, v[130:131]
	s_add_i32 m0, s62, 0x2000
	s_nop 0
	global_load_lds_dwordx4 v[222:223], off
	v_lshl_add_u64 v[222:223], s[46:47], 0, v[132:133]
	s_mov_b32 m0, s49
	s_nop 0
	global_load_lds_dwordx4 v[222:223], off
	s_mov_b32 m0, s50
	s_nop 0
	global_load_lds_dwordx4 v[224:225], off
	s_waitcnt vmcnt(8)
	s_waitcnt lgkmcnt(0)
	s_barrier
	s_setprio 1
	s_waitcnt lgkmcnt(0)
	v_mfma_f32_16x16x32_bf16 v[62:65], v[140:143], v[190:193], 0
	v_mfma_f32_16x16x32_bf16 v[58:61], v[148:151], v[190:193], 0
	v_mfma_f32_16x16x32_bf16 v[46:49], v[140:143], v[198:201], 0
	v_mfma_f32_16x16x32_bf16 v[42:45], v[148:151], v[198:201], 0
	v_mfma_f32_16x16x32_bf16 v[30:33], v[140:143], v[206:209], 0
	v_mfma_f32_16x16x32_bf16 v[26:29], v[148:151], v[206:209], 0
	v_mfma_f32_16x16x32_bf16 v[14:17], v[140:143], v[214:217], 0
	v_mfma_f32_16x16x32_bf16 v[10:13], v[148:151], v[214:217], 0
	v_mfma_f32_16x16x32_bf16 v[62:65], v[144:147], v[194:197], v[62:65]
	v_mfma_f32_16x16x32_bf16 v[58:61], v[164:167], v[194:197], v[58:61]
	v_mfma_f32_16x16x32_bf16 v[46:49], v[144:147], v[202:205], v[46:49]
	v_mfma_f32_16x16x32_bf16 v[42:45], v[164:167], v[202:205], v[42:45]
	v_mfma_f32_16x16x32_bf16 v[30:33], v[144:147], v[210:213], v[30:33]
	v_mfma_f32_16x16x32_bf16 v[26:29], v[164:167], v[210:213], v[26:29]
	v_mfma_f32_16x16x32_bf16 v[14:17], v[144:147], v[218:221], v[14:17]
	v_mfma_f32_16x16x32_bf16 v[10:13], v[164:167], v[218:221], v[10:13]
	s_setprio 0
	s_setprio 1
	v_mfma_f32_16x16x32_bf16 v[54:57], v[168:171], v[190:193], 0
	v_mfma_f32_16x16x32_bf16 v[50:53], v[182:185], v[190:193], 0
	v_mfma_f32_16x16x32_bf16 v[38:41], v[168:171], v[198:201], 0
	v_mfma_f32_16x16x32_bf16 v[34:37], v[182:185], v[198:201], 0
	v_mfma_f32_16x16x32_bf16 v[22:25], v[168:171], v[206:209], 0
	v_mfma_f32_16x16x32_bf16 v[18:21], v[182:185], v[206:209], 0
	v_mfma_f32_16x16x32_bf16 v[6:9], v[168:171], v[214:217], 0
	v_mfma_f32_16x16x32_bf16 v[2:5], v[182:185], v[214:217], 0
	v_mfma_f32_16x16x32_bf16 v[54:57], v[178:181], v[194:197], v[54:57]
	v_mfma_f32_16x16x32_bf16 v[50:53], v[186:189], v[194:197], v[50:53]
	v_mfma_f32_16x16x32_bf16 v[38:41], v[178:181], v[202:205], v[38:41]
	v_mfma_f32_16x16x32_bf16 v[34:37], v[186:189], v[202:205], v[34:37]
	v_mfma_f32_16x16x32_bf16 v[22:25], v[178:181], v[210:213], v[22:25]
	v_mfma_f32_16x16x32_bf16 v[18:21], v[186:189], v[210:213], v[18:21]
	v_mfma_f32_16x16x32_bf16 v[6:9], v[178:181], v[218:221], v[6:9]
	v_mfma_f32_16x16x32_bf16 v[2:5], v[186:189], v[218:221], v[2:5]
	s_setprio 0
	s_barrier
	s_add_i32 s62, 0, 0x18000
	v_add_u32_e32 v134, s62, v154
	s_add_i32 s63, 0, 0x1c000
	ds_read_b128 v[140:143], v134
	ds_read_b128 v[144:147], v134 offset:1024
	ds_read_b128 v[148:151], v134 offset:2048
	ds_read_b128 v[164:167], v134 offset:3072
	v_add_u32_e32 v134, s63, v154
	ds_read_b128 v[168:171], v134
	ds_read_b128 v[178:181], v134 offset:1024
	ds_read_b128 v[182:185], v134 offset:2048
	ds_read_b128 v[186:189], v134 offset:3072
	s_add_u32 s40, s46, 0x40000
	s_addc_u32 s41, s47, 0
	s_mov_b32 m0, s51
	v_lshl_add_u64 v[226:227], s[40:41], 0, v[132:133]
	ds_read_b128 v[190:193], v158 offset:32768
	ds_read_b128 v[194:197], v158 offset:33792
	ds_read_b128 v[198:201], v158 offset:34816
	ds_read_b128 v[202:205], v158 offset:35840
	ds_read_b128 v[206:209], v158 offset:36864
	ds_read_b128 v[210:213], v158 offset:37888
	ds_read_b128 v[214:217], v158 offset:38912
	ds_read_b128 v[218:221], v158 offset:39936
	global_load_lds_dwordx4 v[226:227], off
	v_lshl_add_u64 v[226:227], s[40:41], 0, v[130:131]
	s_mov_b32 m0, s52
	s_nop 0
	global_load_lds_dwordx4 v[226:227], off
	s_waitcnt vmcnt(8)
	s_waitcnt lgkmcnt(0)
	s_barrier
	s_setprio 1
	s_waitcnt lgkmcnt(0)
	v_mfma_f32_16x16x32_bf16 v[126:129], v[140:143], v[190:193], v[126:129]
	v_mfma_f32_16x16x32_bf16 v[122:125], v[148:151], v[190:193], v[122:125]
	v_mfma_f32_16x16x32_bf16 v[110:113], v[140:143], v[198:201], v[110:113]
	v_mfma_f32_16x16x32_bf16 v[106:109], v[148:151], v[198:201], v[106:109]
	v_mfma_f32_16x16x32_bf16 v[94:97], v[140:143], v[206:209], v[94:97]
	v_mfma_f32_16x16x32_bf16 v[90:93], v[148:151], v[206:209], v[90:93]
	v_mfma_f32_16x16x32_bf16 v[78:81], v[140:143], v[214:217], v[78:81]
	v_mfma_f32_16x16x32_bf16 v[74:77], v[148:151], v[214:217], v[74:77]
	v_mfma_f32_16x16x32_bf16 v[126:129], v[144:147], v[194:197], v[126:129]
	v_mfma_f32_16x16x32_bf16 v[122:125], v[164:167], v[194:197], v[122:125]
	v_mfma_f32_16x16x32_bf16 v[110:113], v[144:147], v[202:205], v[110:113]
	v_mfma_f32_16x16x32_bf16 v[106:109], v[164:167], v[202:205], v[106:109]
	v_mfma_f32_16x16x32_bf16 v[94:97], v[144:147], v[210:213], v[94:97]
	v_mfma_f32_16x16x32_bf16 v[90:93], v[164:167], v[210:213], v[90:93]
	v_mfma_f32_16x16x32_bf16 v[78:81], v[144:147], v[218:221], v[78:81]
	v_mfma_f32_16x16x32_bf16 v[74:77], v[164:167], v[218:221], v[74:77]
	s_setprio 0
	s_setprio 1
	v_mfma_f32_16x16x32_bf16 v[118:121], v[168:171], v[190:193], v[118:121]
	v_mfma_f32_16x16x32_bf16 v[114:117], v[182:185], v[190:193], v[114:117]
	v_mfma_f32_16x16x32_bf16 v[102:105], v[168:171], v[198:201], v[102:105]
	v_mfma_f32_16x16x32_bf16 v[98:101], v[182:185], v[198:201], v[98:101]
	v_mfma_f32_16x16x32_bf16 v[86:89], v[168:171], v[206:209], v[86:89]
	v_mfma_f32_16x16x32_bf16 v[82:85], v[182:185], v[206:209], v[82:85]
	v_mfma_f32_16x16x32_bf16 v[70:73], v[168:171], v[214:217], v[70:73]
	v_mfma_f32_16x16x32_bf16 v[66:69], v[182:185], v[214:217], v[66:69]
	v_mfma_f32_16x16x32_bf16 v[118:121], v[178:181], v[194:197], v[118:121]
	v_mfma_f32_16x16x32_bf16 v[114:117], v[186:189], v[194:197], v[114:117]
	v_mfma_f32_16x16x32_bf16 v[102:105], v[178:181], v[202:205], v[102:105]
	v_mfma_f32_16x16x32_bf16 v[98:101], v[186:189], v[202:205], v[98:101]
	v_mfma_f32_16x16x32_bf16 v[86:89], v[178:181], v[210:213], v[86:89]
	v_mfma_f32_16x16x32_bf16 v[82:85], v[186:189], v[210:213], v[82:85]
	v_mfma_f32_16x16x32_bf16 v[70:73], v[178:181], v[218:221], v[70:73]
	v_mfma_f32_16x16x32_bf16 v[66:69], v[186:189], v[218:221], v[66:69]
	s_setprio 0
	s_barrier
	s_add_i32 s40, s62, s48
	v_lshl_add_u64 v[152:153], v[152:153], 0, s[20:21]
	s_mov_b32 m0, s40
	ds_read_b128 v[190:193], v158 offset:49152
	ds_read_b128 v[194:197], v158 offset:50176
	ds_read_b128 v[198:201], v158 offset:51200
	ds_read_b128 v[202:205], v158 offset:52224
	ds_read_b128 v[206:209], v158 offset:53248
	ds_read_b128 v[210:213], v158 offset:54272
	ds_read_b128 v[214:217], v158 offset:55296
	ds_read_b128 v[218:221], v158 offset:56320
	global_load_lds_dwordx4 v[152:153], off
	s_add_i32 m0, s40, 0x2000
	s_add_u32 s40, s44, 0x40080
	v_lshl_add_u64 v[152:153], v[172:173], 0, s[20:21]
	s_addc_u32 s41, s45, 0
	s_add_i32 s44, s63, s48
	global_load_lds_dwordx4 v[152:153], off
	v_lshl_add_u64 v[152:153], s[40:41], 0, v[132:133]
	s_mov_b32 m0, s44
	s_nop 0
	global_load_lds_dwordx4 v[152:153], off
	v_lshl_add_u64 v[152:153], s[40:41], 0, v[130:131]
	s_add_i32 m0, s44, 0x2000
	s_nop 0
	global_load_lds_dwordx4 v[152:153], off
	v_lshl_add_u64 v[152:153], v[222:223], 0, s[20:21]
	s_mov_b32 m0, s55
	s_nop 0
	global_load_lds_dwordx4 v[152:153], off
	v_lshl_add_u64 v[152:153], v[224:225], 0, s[20:21]
	s_mov_b32 m0, s56
	s_nop 0
	global_load_lds_dwordx4 v[152:153], off
	s_waitcnt vmcnt(8)
	s_waitcnt lgkmcnt(0)
	s_barrier
	s_setprio 1
	s_waitcnt lgkmcnt(0)
	v_mfma_f32_16x16x32_bf16 v[62:65], v[140:143], v[190:193], v[62:65]
	v_mfma_f32_16x16x32_bf16 v[58:61], v[148:151], v[190:193], v[58:61]
	v_mfma_f32_16x16x32_bf16 v[46:49], v[140:143], v[198:201], v[46:49]
	v_mfma_f32_16x16x32_bf16 v[42:45], v[148:151], v[198:201], v[42:45]
	v_mfma_f32_16x16x32_bf16 v[30:33], v[140:143], v[206:209], v[30:33]
	v_mfma_f32_16x16x32_bf16 v[26:29], v[148:151], v[206:209], v[26:29]
	v_mfma_f32_16x16x32_bf16 v[14:17], v[140:143], v[214:217], v[14:17]
	v_mfma_f32_16x16x32_bf16 v[10:13], v[148:151], v[214:217], v[10:13]
	v_mfma_f32_16x16x32_bf16 v[62:65], v[144:147], v[194:197], v[62:65]
	v_mfma_f32_16x16x32_bf16 v[58:61], v[164:167], v[194:197], v[58:61]
	v_mfma_f32_16x16x32_bf16 v[46:49], v[144:147], v[202:205], v[46:49]
	v_mfma_f32_16x16x32_bf16 v[42:45], v[164:167], v[202:205], v[42:45]
	v_mfma_f32_16x16x32_bf16 v[30:33], v[144:147], v[210:213], v[30:33]
	v_mfma_f32_16x16x32_bf16 v[26:29], v[164:167], v[210:213], v[26:29]
	v_mfma_f32_16x16x32_bf16 v[14:17], v[144:147], v[218:221], v[14:17]
	v_mfma_f32_16x16x32_bf16 v[10:13], v[164:167], v[218:221], v[10:13]
	s_setprio 0
	s_setprio 1
	v_mfma_f32_16x16x32_bf16 v[54:57], v[168:171], v[190:193], v[54:57]
	v_mfma_f32_16x16x32_bf16 v[50:53], v[182:185], v[190:193], v[50:53]
	v_mfma_f32_16x16x32_bf16 v[38:41], v[168:171], v[198:201], v[38:41]
	v_mfma_f32_16x16x32_bf16 v[34:37], v[182:185], v[198:201], v[34:37]
	v_mfma_f32_16x16x32_bf16 v[22:25], v[168:171], v[206:209], v[22:25]
	v_mfma_f32_16x16x32_bf16 v[18:21], v[182:185], v[206:209], v[18:21]
	v_mfma_f32_16x16x32_bf16 v[6:9], v[168:171], v[214:217], v[6:9]
	v_mfma_f32_16x16x32_bf16 v[2:5], v[182:185], v[214:217], v[2:5]
	v_mfma_f32_16x16x32_bf16 v[54:57], v[178:181], v[194:197], v[54:57]
	v_mfma_f32_16x16x32_bf16 v[50:53], v[186:189], v[194:197], v[50:53]
	v_mfma_f32_16x16x32_bf16 v[38:41], v[178:181], v[202:205], v[38:41]
	v_mfma_f32_16x16x32_bf16 v[34:37], v[186:189], v[202:205], v[34:37]
	v_mfma_f32_16x16x32_bf16 v[22:25], v[178:181], v[210:213], v[22:25]
	v_mfma_f32_16x16x32_bf16 v[18:21], v[186:189], v[210:213], v[18:21]
	v_mfma_f32_16x16x32_bf16 v[6:9], v[178:181], v[218:221], v[6:9]
	v_mfma_f32_16x16x32_bf16 v[2:5], v[186:189], v[218:221], v[2:5]
	s_setprio 0
	s_add_i32 s61, s61, 2
	s_add_u32 s35, s35, 0x100
	s_addc_u32 s39, s39, 0
	s_cmp_gt_u32 s61, 13
	s_mov_b64 s[40:41], s[42:43]
	s_barrier
	s_cbranch_scc0 .LBB0_405
	s_branch .Lpeel_exit_405
.LBB0_405:
	ds_read_b128 v[140:143], v156
	ds_read_b128 v[144:147], v156 offset:1024
	ds_read_b128 v[148:151], v156 offset:2048
	ds_read_b128 v[164:167], v156 offset:3072
	ds_read_b128 v[168:171], v157
	ds_read_b128 v[178:181], v157 offset:1024
	ds_read_b128 v[182:185], v157 offset:2048
	ds_read_b128 v[186:189], v157 offset:3072
	s_add_u32 s42, s40, 0x100
	s_addc_u32 s43, s41, 0
	s_cmp_eq_u32 s61, 12
	s_cselect_b32 s47, s5, s43
	s_cselect_b32 s46, s29, s42
	s_cselect_b32 s45, s27, s39
	s_cselect_b32 s44, s34, s35
	v_lshl_add_u64 v[152:153], s[40:41], 0, v[136:137]
	s_add_i32 m0, s49, 0xc000
	ds_read_b128 v[190:193], v158
	ds_read_b128 v[194:197], v158 offset:1024
	ds_read_b128 v[198:201], v158 offset:2048
	ds_read_b128 v[202:205], v158 offset:3072
	ds_read_b128 v[206:209], v158 offset:4096
	ds_read_b128 v[210:213], v158 offset:5120
	ds_read_b128 v[214:217], v158 offset:6144
	ds_read_b128 v[218:221], v158 offset:7168
	global_load_lds_dwordx4 v[152:153], off
	v_lshl_add_u64 v[152:153], s[40:41], 0, v[138:139]
	s_add_i32 m0, s49, 0xe000
	s_nop 0
	global_load_lds_dwordx4 v[152:153], off
	s_waitcnt vmcnt(8)
	s_waitcnt lgkmcnt(0)
	s_barrier
	s_setprio 1
	s_waitcnt lgkmcnt(0)
	v_mfma_f32_16x16x32_bf16 v[126:129], v[140:143], v[190:193], v[126:129]
	v_mfma_f32_16x16x32_bf16 v[122:125], v[148:151], v[190:193], v[122:125]
	v_mfma_f32_16x16x32_bf16 v[110:113], v[140:143], v[198:201], v[110:113]
	v_mfma_f32_16x16x32_bf16 v[106:109], v[148:151], v[198:201], v[106:109]
	v_mfma_f32_16x16x32_bf16 v[94:97], v[140:143], v[206:209], v[94:97]
	v_mfma_f32_16x16x32_bf16 v[90:93], v[148:151], v[206:209], v[90:93]
	v_mfma_f32_16x16x32_bf16 v[78:81], v[140:143], v[214:217], v[78:81]
	v_mfma_f32_16x16x32_bf16 v[74:77], v[148:151], v[214:217], v[74:77]
	v_mfma_f32_16x16x32_bf16 v[126:129], v[144:147], v[194:197], v[126:129]
	v_mfma_f32_16x16x32_bf16 v[122:125], v[164:167], v[194:197], v[122:125]
	v_mfma_f32_16x16x32_bf16 v[110:113], v[144:147], v[202:205], v[110:113]
	v_mfma_f32_16x16x32_bf16 v[106:109], v[164:167], v[202:205], v[106:109]
	v_mfma_f32_16x16x32_bf16 v[94:97], v[144:147], v[210:213], v[94:97]
	v_mfma_f32_16x16x32_bf16 v[90:93], v[164:167], v[210:213], v[90:93]
	v_mfma_f32_16x16x32_bf16 v[78:81], v[144:147], v[218:221], v[78:81]
	v_mfma_f32_16x16x32_bf16 v[74:77], v[164:167], v[218:221], v[74:77]
	s_setprio 0
	s_setprio 1
	v_mfma_f32_16x16x32_bf16 v[118:121], v[168:171], v[190:193], v[118:121]
	v_mfma_f32_16x16x32_bf16 v[114:117], v[182:185], v[190:193], v[114:117]
	v_mfma_f32_16x16x32_bf16 v[102:105], v[168:171], v[198:201], v[102:105]
	v_mfma_f32_16x16x32_bf16 v[98:101], v[182:185], v[198:201], v[98:101]
	v_mfma_f32_16x16x32_bf16 v[86:89], v[168:171], v[206:209], v[86:89]
	v_mfma_f32_16x16x32_bf16 v[82:85], v[182:185], v[206:209], v[82:85]
	v_mfma_f32_16x16x32_bf16 v[70:73], v[168:171], v[214:217], v[70:73]
	v_mfma_f32_16x16x32_bf16 v[66:69], v[182:185], v[214:217], v[66:69]
	v_mfma_f32_16x16x32_bf16 v[118:121], v[178:181], v[194:197], v[118:121]
	v_mfma_f32_16x16x32_bf16 v[114:117], v[186:189], v[194:197], v[114:117]
	v_mfma_f32_16x16x32_bf16 v[102:105], v[178:181], v[202:205], v[102:105]
	v_mfma_f32_16x16x32_bf16 v[98:101], v[186:189], v[202:205], v[98:101]
	v_mfma_f32_16x16x32_bf16 v[86:89], v[178:181], v[210:213], v[86:89]
	v_mfma_f32_16x16x32_bf16 v[82:85], v[186:189], v[210:213], v[82:85]
	v_mfma_f32_16x16x32_bf16 v[70:73], v[178:181], v[218:221], v[70:73]
	v_mfma_f32_16x16x32_bf16 v[66:69], v[186:189], v[218:221], v[66:69]
	s_setprio 0
	s_barrier
	s_add_i32 s40, s59, s48
	v_lshl_add_u64 v[152:153], s[44:45], 0, v[132:133]
	s_mov_b32 m0, s40
	ds_read_b128 v[190:193], v158 offset:16384
	ds_read_b128 v[194:197], v158 offset:17408
	ds_read_b128 v[198:201], v158 offset:18432
	ds_read_b128 v[202:205], v158 offset:19456
	ds_read_b128 v[206:209], v158 offset:20480
	ds_read_b128 v[210:213], v158 offset:21504
	ds_read_b128 v[214:217], v158 offset:22528
	ds_read_b128 v[218:221], v158 offset:23552
	global_load_lds_dwordx4 v[152:153], off
	s_add_i32 m0, s40, 0x2000
	s_add_u32 s40, s44, 0x40000
	v_lshl_add_u64 v[172:173], s[44:45], 0, v[130:131]
	s_addc_u32 s41, s45, 0
	s_add_i32 s62, s60, s48
	global_load_lds_dwordx4 v[172:173], off
	v_lshl_add_u64 v[222:223], s[40:41], 0, v[132:133]
	s_mov_b32 m0, s62
	v_lshl_add_u64 v[224:225], s[46:47], 0, v[130:131]
	global_load_lds_dwordx4 v[222:223], off
	v_lshl_add_u64 v[222:223], s[40:41], 0, v[130:131]
	s_add_i32 m0, s62, 0x2000
	s_nop 0
	global_load_lds_dwordx4 v[222:223], off
	v_lshl_add_u64 v[222:223], s[46:47], 0, v[132:133]
	s_mov_b32 m0, s49
	s_nop 0
	global_load_lds_dwordx4 v[222:223], off
	s_mov_b32 m0, s50
	s_nop 0
	global_load_lds_dwordx4 v[224:225], off
	s_waitcnt vmcnt(8)
	s_waitcnt lgkmcnt(0)
	s_barrier
	s_setprio 1
	s_waitcnt lgkmcnt(0)
	v_mfma_f32_16x16x32_bf16 v[62:65], v[140:143], v[190:193], v[62:65]
	v_mfma_f32_16x16x32_bf16 v[58:61], v[148:151], v[190:193], v[58:61]
	v_mfma_f32_16x16x32_bf16 v[46:49], v[140:143], v[198:201], v[46:49]
	v_mfma_f32_16x16x32_bf16 v[42:45], v[148:151], v[198:201], v[42:45]
	v_mfma_f32_16x16x32_bf16 v[30:33], v[140:143], v[206:209], v[30:33]
	v_mfma_f32_16x16x32_bf16 v[26:29], v[148:151], v[206:209], v[26:29]
	v_mfma_f32_16x16x32_bf16 v[14:17], v[140:143], v[214:217], v[14:17]
	v_mfma_f32_16x16x32_bf16 v[10:13], v[148:151], v[214:217], v[10:13]
	v_mfma_f32_16x16x32_bf16 v[62:65], v[144:147], v[194:197], v[62:65]
	v_mfma_f32_16x16x32_bf16 v[58:61], v[164:167], v[194:197], v[58:61]
	v_mfma_f32_16x16x32_bf16 v[46:49], v[144:147], v[202:205], v[46:49]
	v_mfma_f32_16x16x32_bf16 v[42:45], v[164:167], v[202:205], v[42:45]
	v_mfma_f32_16x16x32_bf16 v[30:33], v[144:147], v[210:213], v[30:33]
	v_mfma_f32_16x16x32_bf16 v[26:29], v[164:167], v[210:213], v[26:29]
	v_mfma_f32_16x16x32_bf16 v[14:17], v[144:147], v[218:221], v[14:17]
	v_mfma_f32_16x16x32_bf16 v[10:13], v[164:167], v[218:221], v[10:13]
	s_setprio 0
	s_setprio 1
	v_mfma_f32_16x16x32_bf16 v[54:57], v[168:171], v[190:193], v[54:57]
	v_mfma_f32_16x16x32_bf16 v[50:53], v[182:185], v[190:193], v[50:53]
	v_mfma_f32_16x16x32_bf16 v[38:41], v[168:171], v[198:201], v[38:41]
	v_mfma_f32_16x16x32_bf16 v[34:37], v[182:185], v[198:201], v[34:37]
	v_mfma_f32_16x16x32_bf16 v[22:25], v[168:171], v[206:209], v[22:25]
	v_mfma_f32_16x16x32_bf16 v[18:21], v[182:185], v[206:209], v[18:21]
	v_mfma_f32_16x16x32_bf16 v[6:9], v[168:171], v[214:217], v[6:9]
	v_mfma_f32_16x16x32_bf16 v[2:5], v[182:185], v[214:217], v[2:5]
	v_mfma_f32_16x16x32_bf16 v[54:57], v[178:181], v[194:197], v[54:57]
	v_mfma_f32_16x16x32_bf16 v[50:53], v[186:189], v[194:197], v[50:53]
	v_mfma_f32_16x16x32_bf16 v[38:41], v[178:181], v[202:205], v[38:41]
	v_mfma_f32_16x16x32_bf16 v[34:37], v[186:189], v[202:205], v[34:37]
	v_mfma_f32_16x16x32_bf16 v[22:25], v[178:181], v[210:213], v[22:25]
	v_mfma_f32_16x16x32_bf16 v[18:21], v[186:189], v[210:213], v[18:21]
	v_mfma_f32_16x16x32_bf16 v[6:9], v[178:181], v[218:221], v[6:9]
	v_mfma_f32_16x16x32_bf16 v[2:5], v[186:189], v[218:221], v[2:5]
	s_setprio 0
	s_barrier
	s_add_i32 s62, 0, 0x18000
	v_add_u32_e32 v134, s62, v154
	s_add_i32 s63, 0, 0x1c000
	ds_read_b128 v[140:143], v134
	ds_read_b128 v[144:147], v134 offset:1024
	ds_read_b128 v[148:151], v134 offset:2048
	ds_read_b128 v[164:167], v134 offset:3072
	v_add_u32_e32 v134, s63, v154
	ds_read_b128 v[168:171], v134
	ds_read_b128 v[178:181], v134 offset:1024
	ds_read_b128 v[182:185], v134 offset:2048
	ds_read_b128 v[186:189], v134 offset:3072
	s_add_u32 s40, s46, 0x40000
	s_addc_u32 s41, s47, 0
	s_mov_b32 m0, s51
	v_lshl_add_u64 v[226:227], s[40:41], 0, v[132:133]
	ds_read_b128 v[190:193], v158 offset:32768
	ds_read_b128 v[194:197], v158 offset:33792
	ds_read_b128 v[198:201], v158 offset:34816
	ds_read_b128 v[202:205], v158 offset:35840
	ds_read_b128 v[206:209], v158 offset:36864
	ds_read_b128 v[210:213], v158 offset:37888
	ds_read_b128 v[214:217], v158 offset:38912
	ds_read_b128 v[218:221], v158 offset:39936
	global_load_lds_dwordx4 v[226:227], off
	v_lshl_add_u64 v[226:227], s[40:41], 0, v[130:131]
	s_mov_b32 m0, s52
	s_nop 0
	global_load_lds_dwordx4 v[226:227], off
	s_waitcnt vmcnt(8)
	s_waitcnt lgkmcnt(0)
	s_barrier
	s_setprio 1
	s_waitcnt lgkmcnt(0)
	v_mfma_f32_16x16x32_bf16 v[126:129], v[140:143], v[190:193], v[126:129]
	v_mfma_f32_16x16x32_bf16 v[122:125], v[148:151], v[190:193], v[122:125]
	v_mfma_f32_16x16x32_bf16 v[110:113], v[140:143], v[198:201], v[110:113]
	v_mfma_f32_16x16x32_bf16 v[106:109], v[148:151], v[198:201], v[106:109]
	v_mfma_f32_16x16x32_bf16 v[94:97], v[140:143], v[206:209], v[94:97]
	v_mfma_f32_16x16x32_bf16 v[90:93], v[148:151], v[206:209], v[90:93]
	v_mfma_f32_16x16x32_bf16 v[78:81], v[140:143], v[214:217], v[78:81]
	v_mfma_f32_16x16x32_bf16 v[74:77], v[148:151], v[214:217], v[74:77]
	v_mfma_f32_16x16x32_bf16 v[126:129], v[144:147], v[194:197], v[126:129]
	v_mfma_f32_16x16x32_bf16 v[122:125], v[164:167], v[194:197], v[122:125]
	v_mfma_f32_16x16x32_bf16 v[110:113], v[144:147], v[202:205], v[110:113]
	v_mfma_f32_16x16x32_bf16 v[106:109], v[164:167], v[202:205], v[106:109]
	v_mfma_f32_16x16x32_bf16 v[94:97], v[144:147], v[210:213], v[94:97]
	v_mfma_f32_16x16x32_bf16 v[90:93], v[164:167], v[210:213], v[90:93]
	v_mfma_f32_16x16x32_bf16 v[78:81], v[144:147], v[218:221], v[78:81]
	v_mfma_f32_16x16x32_bf16 v[74:77], v[164:167], v[218:221], v[74:77]
	s_setprio 0
	s_setprio 1
	v_mfma_f32_16x16x32_bf16 v[118:121], v[168:171], v[190:193], v[118:121]
	v_mfma_f32_16x16x32_bf16 v[114:117], v[182:185], v[190:193], v[114:117]
	v_mfma_f32_16x16x32_bf16 v[102:105], v[168:171], v[198:201], v[102:105]
	v_mfma_f32_16x16x32_bf16 v[98:101], v[182:185], v[198:201], v[98:101]
	v_mfma_f32_16x16x32_bf16 v[86:89], v[168:171], v[206:209], v[86:89]
	v_mfma_f32_16x16x32_bf16 v[82:85], v[182:185], v[206:209], v[82:85]
	v_mfma_f32_16x16x32_bf16 v[70:73], v[168:171], v[214:217], v[70:73]
	v_mfma_f32_16x16x32_bf16 v[66:69], v[182:185], v[214:217], v[66:69]
	v_mfma_f32_16x16x32_bf16 v[118:121], v[178:181], v[194:197], v[118:121]
	v_mfma_f32_16x16x32_bf16 v[114:117], v[186:189], v[194:197], v[114:117]
	v_mfma_f32_16x16x32_bf16 v[102:105], v[178:181], v[202:205], v[102:105]
	v_mfma_f32_16x16x32_bf16 v[98:101], v[186:189], v[202:205], v[98:101]
	v_mfma_f32_16x16x32_bf16 v[86:89], v[178:181], v[210:213], v[86:89]
	v_mfma_f32_16x16x32_bf16 v[82:85], v[186:189], v[210:213], v[82:85]
	v_mfma_f32_16x16x32_bf16 v[70:73], v[178:181], v[218:221], v[70:73]
	v_mfma_f32_16x16x32_bf16 v[66:69], v[186:189], v[218:221], v[66:69]
	s_setprio 0
	s_barrier
	s_add_i32 s40, s62, s48
	v_lshl_add_u64 v[152:153], v[152:153], 0, s[20:21]
	s_mov_b32 m0, s40
	ds_read_b128 v[190:193], v158 offset:49152
	ds_read_b128 v[194:197], v158 offset:50176
	ds_read_b128 v[198:201], v158 offset:51200
	ds_read_b128 v[202:205], v158 offset:52224
	ds_read_b128 v[206:209], v158 offset:53248
	ds_read_b128 v[210:213], v158 offset:54272
	ds_read_b128 v[214:217], v158 offset:55296
	ds_read_b128 v[218:221], v158 offset:56320
	global_load_lds_dwordx4 v[152:153], off
	s_add_i32 m0, s40, 0x2000
	s_add_u32 s40, s44, 0x40080
	v_lshl_add_u64 v[152:153], v[172:173], 0, s[20:21]
	s_addc_u32 s41, s45, 0
	s_add_i32 s44, s63, s48
	global_load_lds_dwordx4 v[152:153], off
	v_lshl_add_u64 v[152:153], s[40:41], 0, v[132:133]
	s_mov_b32 m0, s44
	s_nop 0
	global_load_lds_dwordx4 v[152:153], off
	v_lshl_add_u64 v[152:153], s[40:41], 0, v[130:131]
	s_add_i32 m0, s44, 0x2000
	s_nop 0
	global_load_lds_dwordx4 v[152:153], off
	v_lshl_add_u64 v[152:153], v[222:223], 0, s[20:21]
	s_mov_b32 m0, s55
	s_nop 0
	global_load_lds_dwordx4 v[152:153], off
	v_lshl_add_u64 v[152:153], v[224:225], 0, s[20:21]
	s_mov_b32 m0, s56
	s_nop 0
	global_load_lds_dwordx4 v[152:153], off
	s_waitcnt vmcnt(8)
	s_waitcnt lgkmcnt(0)
	s_barrier
	s_setprio 1
	s_waitcnt lgkmcnt(0)
	v_mfma_f32_16x16x32_bf16 v[62:65], v[140:143], v[190:193], v[62:65]
	v_mfma_f32_16x16x32_bf16 v[58:61], v[148:151], v[190:193], v[58:61]
	v_mfma_f32_16x16x32_bf16 v[46:49], v[140:143], v[198:201], v[46:49]
	v_mfma_f32_16x16x32_bf16 v[42:45], v[148:151], v[198:201], v[42:45]
	v_mfma_f32_16x16x32_bf16 v[30:33], v[140:143], v[206:209], v[30:33]
	v_mfma_f32_16x16x32_bf16 v[26:29], v[148:151], v[206:209], v[26:29]
	v_mfma_f32_16x16x32_bf16 v[14:17], v[140:143], v[214:217], v[14:17]
	v_mfma_f32_16x16x32_bf16 v[10:13], v[148:151], v[214:217], v[10:13]
	v_mfma_f32_16x16x32_bf16 v[62:65], v[144:147], v[194:197], v[62:65]
	v_mfma_f32_16x16x32_bf16 v[58:61], v[164:167], v[194:197], v[58:61]
	v_mfma_f32_16x16x32_bf16 v[46:49], v[144:147], v[202:205], v[46:49]
	v_mfma_f32_16x16x32_bf16 v[42:45], v[164:167], v[202:205], v[42:45]
	v_mfma_f32_16x16x32_bf16 v[30:33], v[144:147], v[210:213], v[30:33]
	v_mfma_f32_16x16x32_bf16 v[26:29], v[164:167], v[210:213], v[26:29]
	v_mfma_f32_16x16x32_bf16 v[14:17], v[144:147], v[218:221], v[14:17]
	v_mfma_f32_16x16x32_bf16 v[10:13], v[164:167], v[218:221], v[10:13]
	s_setprio 0
	s_setprio 1
	v_mfma_f32_16x16x32_bf16 v[54:57], v[168:171], v[190:193], v[54:57]
	v_mfma_f32_16x16x32_bf16 v[50:53], v[182:185], v[190:193], v[50:53]
	v_mfma_f32_16x16x32_bf16 v[38:41], v[168:171], v[198:201], v[38:41]
	v_mfma_f32_16x16x32_bf16 v[34:37], v[182:185], v[198:201], v[34:37]
	v_mfma_f32_16x16x32_bf16 v[22:25], v[168:171], v[206:209], v[22:25]
	v_mfma_f32_16x16x32_bf16 v[18:21], v[182:185], v[206:209], v[18:21]
	v_mfma_f32_16x16x32_bf16 v[6:9], v[168:171], v[214:217], v[6:9]
	v_mfma_f32_16x16x32_bf16 v[2:5], v[182:185], v[214:217], v[2:5]
	v_mfma_f32_16x16x32_bf16 v[54:57], v[178:181], v[194:197], v[54:57]
	v_mfma_f32_16x16x32_bf16 v[50:53], v[186:189], v[194:197], v[50:53]
	v_mfma_f32_16x16x32_bf16 v[38:41], v[178:181], v[202:205], v[38:41]
	v_mfma_f32_16x16x32_bf16 v[34:37], v[186:189], v[202:205], v[34:37]
	v_mfma_f32_16x16x32_bf16 v[22:25], v[178:181], v[210:213], v[22:25]
	v_mfma_f32_16x16x32_bf16 v[18:21], v[186:189], v[210:213], v[18:21]
	v_mfma_f32_16x16x32_bf16 v[6:9], v[178:181], v[218:221], v[6:9]
	v_mfma_f32_16x16x32_bf16 v[2:5], v[186:189], v[218:221], v[2:5]
	s_setprio 0
	s_add_i32 s61, s61, 2
	s_add_u32 s35, s35, 0x100
	s_addc_u32 s39, s39, 0
	s_cmp_gt_u32 s61, 13
	s_mov_b64 s[40:41], s[42:43]
	s_barrier
	s_cbranch_scc0 .LBB0_405

.LBB0_1029:
	v_add_u32_e32 v179, s28, v1
	ds_read_b128 v[180:183], v179
	ds_read_b128 v[184:187], v179 offset:1024
	ds_read_b128 v[188:191], v179 offset:2048
	ds_read_b128 v[192:195], v179 offset:3072
	v_add_u32_e32 v179, s29, v1
	ds_read_b128 v[196:199], v179
	ds_read_b128 v[200:203], v179 offset:1024
	ds_read_b128 v[204:207], v179 offset:2048
	ds_read_b128 v[208:211], v179 offset:3072
	s_add_u32 s22, s20, 0xfff80080
	s_addc_u32 s23, s21, -1
	s_cmp_eq_u32 s46, 4
	s_cselect_b32 s25, s7, s23
	s_cselect_b32 s24, s6, s22
	s_cselect_b32 s23, s1, s45
	s_cselect_b32 s22, s0, s44
	s_mov_b32 m0, s30
	v_lshl_add_u64 v[244:245], s[20:21], 0, v[170:171]
	ds_read_b128 v[212:215], v178
	ds_read_b128 v[216:219], v178 offset:1024
	ds_read_b128 v[220:223], v178 offset:2048
	ds_read_b128 v[224:227], v178 offset:3072
	ds_read_b128 v[228:231], v178 offset:4096
	ds_read_b128 v[232:235], v178 offset:5120
	ds_read_b128 v[236:239], v178 offset:6144
	ds_read_b128 v[240:243], v178 offset:7168
	global_load_lds_dwordx4 v[244:245], off
	v_lshl_add_u64 v[244:245], s[20:21], 0, v[172:173]
	s_mov_b32 m0, s31
	s_nop 0
	global_load_lds_dwordx4 v[244:245], off
	s_waitcnt vmcnt(8)
	s_waitcnt lgkmcnt(0)
	s_barrier
	s_setprio 1
	s_waitcnt lgkmcnt(0)
	v_mfma_f32_16x16x32_bf16 v[126:129], v[180:183], v[212:215], v[126:129]
	v_mfma_f32_16x16x32_bf16 v[122:125], v[188:191], v[212:215], v[122:125]
	v_mfma_f32_16x16x32_bf16 v[118:121], v[180:183], v[220:223], v[118:121]
	v_mfma_f32_16x16x32_bf16 v[114:117], v[188:191], v[220:223], v[114:117]
	v_mfma_f32_16x16x32_bf16 v[110:113], v[180:183], v[228:231], v[110:113]
	v_mfma_f32_16x16x32_bf16 v[106:109], v[188:191], v[228:231], v[106:109]
	v_mfma_f32_16x16x32_bf16 v[102:105], v[180:183], v[236:239], v[102:105]
	v_mfma_f32_16x16x32_bf16 v[98:101], v[188:191], v[236:239], v[98:101]
	v_mfma_f32_16x16x32_bf16 v[126:129], v[184:187], v[216:219], v[126:129]
	v_mfma_f32_16x16x32_bf16 v[122:125], v[192:195], v[216:219], v[122:125]
	v_mfma_f32_16x16x32_bf16 v[118:121], v[184:187], v[224:227], v[118:121]
	v_mfma_f32_16x16x32_bf16 v[114:117], v[192:195], v[224:227], v[114:117]
	v_mfma_f32_16x16x32_bf16 v[110:113], v[184:187], v[232:235], v[110:113]
	v_mfma_f32_16x16x32_bf16 v[106:109], v[192:195], v[232:235], v[106:109]
	v_mfma_f32_16x16x32_bf16 v[102:105], v[184:187], v[240:243], v[102:105]
	v_mfma_f32_16x16x32_bf16 v[98:101], v[192:195], v[240:243], v[98:101]
	s_setprio 0
	s_setprio 1
	v_mfma_f32_16x16x32_bf16 v[94:97], v[196:199], v[212:215], v[94:97]
	v_mfma_f32_16x16x32_bf16 v[90:93], v[204:207], v[212:215], v[90:93]
	v_mfma_f32_16x16x32_bf16 v[86:89], v[196:199], v[220:223], v[86:89]
	v_mfma_f32_16x16x32_bf16 v[82:85], v[204:207], v[220:223], v[82:85]
	v_mfma_f32_16x16x32_bf16 v[78:81], v[196:199], v[228:231], v[78:81]
	v_mfma_f32_16x16x32_bf16 v[74:77], v[204:207], v[228:231], v[74:77]
	v_mfma_f32_16x16x32_bf16 v[70:73], v[196:199], v[236:239], v[70:73]
	v_mfma_f32_16x16x32_bf16 v[66:69], v[204:207], v[236:239], v[66:69]
	v_mfma_f32_16x16x32_bf16 v[94:97], v[200:203], v[216:219], v[94:97]
	v_mfma_f32_16x16x32_bf16 v[90:93], v[208:211], v[216:219], v[90:93]
	v_mfma_f32_16x16x32_bf16 v[86:89], v[200:203], v[224:227], v[86:89]
	v_mfma_f32_16x16x32_bf16 v[82:85], v[208:211], v[224:227], v[82:85]
	v_mfma_f32_16x16x32_bf16 v[78:81], v[200:203], v[232:235], v[78:81]
	v_mfma_f32_16x16x32_bf16 v[74:77], v[208:211], v[232:235], v[74:77]
	v_mfma_f32_16x16x32_bf16 v[70:73], v[200:203], v[240:243], v[70:73]
	v_mfma_f32_16x16x32_bf16 v[66:69], v[208:211], v[240:243], v[66:69]
	s_setprio 0
	s_barrier
	s_mov_b32 m0, s34
	v_lshl_add_u64 v[244:245], s[22:23], 0, v[132:133]
	s_add_u32 s48, s22, 0x80000
	ds_read_b128 v[212:215], v178 offset:16384
	ds_read_b128 v[216:219], v178 offset:17408
	ds_read_b128 v[220:223], v178 offset:18432
	ds_read_b128 v[224:227], v178 offset:19456
	ds_read_b128 v[228:231], v178 offset:20480
	ds_read_b128 v[232:235], v178 offset:21504
	ds_read_b128 v[236:239], v178 offset:22528
	ds_read_b128 v[240:243], v178 offset:23552
	global_load_lds_dwordx4 v[244:245], off
	v_lshl_add_u64 v[246:247], s[22:23], 0, v[136:137]
	s_mov_b32 m0, s35
	s_addc_u32 s49, s23, 0
	global_load_lds_dwordx4 v[246:247], off
	v_lshl_add_u64 v[248:249], s[48:49], 0, v[132:133]
	s_mov_b32 m0, s36
	v_lshl_add_u64 v[250:251], s[24:25], 0, v[134:135]
	global_load_lds_dwordx4 v[248:249], off
	v_lshl_add_u64 v[248:249], s[48:49], 0, v[136:137]
	s_mov_b32 m0, s37
	s_nop 0
	global_load_lds_dwordx4 v[248:249], off
	v_lshl_add_u64 v[248:249], s[24:25], 0, v[130:131]
	s_mov_b32 m0, s3
	s_nop 0
	global_load_lds_dwordx4 v[248:249], off
	s_mov_b32 m0, s14
	s_nop 0
	global_load_lds_dwordx4 v[250:251], off
	s_waitcnt vmcnt(8)
	s_waitcnt lgkmcnt(0)
	s_barrier
	s_setprio 1
	s_waitcnt lgkmcnt(0)
	v_mfma_f32_16x16x32_bf16 v[62:65], v[180:183], v[212:215], v[62:65]
	v_mfma_f32_16x16x32_bf16 v[58:61], v[188:191], v[212:215], v[58:61]
	v_mfma_f32_16x16x32_bf16 v[54:57], v[180:183], v[220:223], v[54:57]
	v_mfma_f32_16x16x32_bf16 v[50:53], v[188:191], v[220:223], v[50:53]
	v_mfma_f32_16x16x32_bf16 v[46:49], v[180:183], v[228:231], v[46:49]
	v_mfma_f32_16x16x32_bf16 v[42:45], v[188:191], v[228:231], v[42:45]
	v_mfma_f32_16x16x32_bf16 v[38:41], v[180:183], v[236:239], v[38:41]
	v_mfma_f32_16x16x32_bf16 v[34:37], v[188:191], v[236:239], v[34:37]
	v_mfma_f32_16x16x32_bf16 v[62:65], v[184:187], v[216:219], v[62:65]
	v_mfma_f32_16x16x32_bf16 v[58:61], v[192:195], v[216:219], v[58:61]
	v_mfma_f32_16x16x32_bf16 v[54:57], v[184:187], v[224:227], v[54:57]
	v_mfma_f32_16x16x32_bf16 v[50:53], v[192:195], v[224:227], v[50:53]
	v_mfma_f32_16x16x32_bf16 v[46:49], v[184:187], v[232:235], v[46:49]
	v_mfma_f32_16x16x32_bf16 v[42:45], v[192:195], v[232:235], v[42:45]
	v_mfma_f32_16x16x32_bf16 v[38:41], v[184:187], v[240:243], v[38:41]
	v_mfma_f32_16x16x32_bf16 v[34:37], v[192:195], v[240:243], v[34:37]
	s_setprio 0
	s_setprio 1
	v_mfma_f32_16x16x32_bf16 v[30:33], v[196:199], v[212:215], v[30:33]
	v_mfma_f32_16x16x32_bf16 v[26:29], v[204:207], v[212:215], v[26:29]
	v_mfma_f32_16x16x32_bf16 v[22:25], v[196:199], v[220:223], v[22:25]
	v_mfma_f32_16x16x32_bf16 v[18:21], v[204:207], v[220:223], v[18:21]
	v_mfma_f32_16x16x32_bf16 v[14:17], v[196:199], v[228:231], v[14:17]
	v_mfma_f32_16x16x32_bf16 v[10:13], v[204:207], v[228:231], v[10:13]
	v_mfma_f32_16x16x32_bf16 v[6:9], v[196:199], v[236:239], v[6:9]
	v_mfma_f32_16x16x32_bf16 v[2:5], v[204:207], v[236:239], v[2:5]
	v_mfma_f32_16x16x32_bf16 v[30:33], v[200:203], v[216:219], v[30:33]
	v_mfma_f32_16x16x32_bf16 v[26:29], v[208:211], v[216:219], v[26:29]
	v_mfma_f32_16x16x32_bf16 v[22:25], v[200:203], v[224:227], v[22:25]
	v_mfma_f32_16x16x32_bf16 v[18:21], v[208:211], v[224:227], v[18:21]
	v_mfma_f32_16x16x32_bf16 v[14:17], v[200:203], v[232:235], v[14:17]
	v_mfma_f32_16x16x32_bf16 v[10:13], v[208:211], v[232:235], v[10:13]
	v_mfma_f32_16x16x32_bf16 v[6:9], v[200:203], v[240:243], v[6:9]
	v_mfma_f32_16x16x32_bf16 v[2:5], v[208:211], v[240:243], v[2:5]
	s_setprio 0
	s_barrier
	v_add_u32_e32 v179, s38, v1
	ds_read_b128 v[180:183], v179
	ds_read_b128 v[184:187], v179 offset:1024
	ds_read_b128 v[188:191], v179 offset:2048
	ds_read_b128 v[192:195], v179 offset:3072
	v_add_u32_e32 v179, s39, v1
	ds_read_b128 v[196:199], v179
	ds_read_b128 v[200:203], v179 offset:1024
	ds_read_b128 v[204:207], v179 offset:2048
	ds_read_b128 v[208:211], v179 offset:3072
	s_add_u32 s24, s24, 0x80000
	s_addc_u32 s25, s25, 0
	s_mov_b32 m0, s15
	v_lshl_add_u64 v[252:253], s[24:25], 0, v[130:131]
	ds_read_b128 v[212:215], v178 offset:32768
	ds_read_b128 v[216:219], v178 offset:33792
	ds_read_b128 v[220:223], v178 offset:34816
	ds_read_b128 v[224:227], v178 offset:35840
	ds_read_b128 v[228:231], v178 offset:36864
	ds_read_b128 v[232:235], v178 offset:37888
	ds_read_b128 v[236:239], v178 offset:38912
	ds_read_b128 v[240:243], v178 offset:39936
	global_load_lds_dwordx4 v[252:253], off
	v_lshl_add_u64 v[252:253], s[24:25], 0, v[134:135]
	s_mov_b32 m0, s16
	s_nop 0
	global_load_lds_dwordx4 v[252:253], off
	s_waitcnt vmcnt(8)
	s_waitcnt lgkmcnt(0)
	s_barrier
	s_setprio 1
	s_waitcnt lgkmcnt(0)
	v_mfma_f32_16x16x32_bf16 v[126:129], v[180:183], v[212:215], v[126:129]
	v_mfma_f32_16x16x32_bf16 v[122:125], v[188:191], v[212:215], v[122:125]
	v_mfma_f32_16x16x32_bf16 v[118:121], v[180:183], v[220:223], v[118:121]
	v_mfma_f32_16x16x32_bf16 v[114:117], v[188:191], v[220:223], v[114:117]
	v_mfma_f32_16x16x32_bf16 v[110:113], v[180:183], v[228:231], v[110:113]
	v_mfma_f32_16x16x32_bf16 v[106:109], v[188:191], v[228:231], v[106:109]
	v_mfma_f32_16x16x32_bf16 v[102:105], v[180:183], v[236:239], v[102:105]
	v_mfma_f32_16x16x32_bf16 v[98:101], v[188:191], v[236:239], v[98:101]
	v_mfma_f32_16x16x32_bf16 v[126:129], v[184:187], v[216:219], v[126:129]
	v_mfma_f32_16x16x32_bf16 v[122:125], v[192:195], v[216:219], v[122:125]
	v_mfma_f32_16x16x32_bf16 v[118:121], v[184:187], v[224:227], v[118:121]
	v_mfma_f32_16x16x32_bf16 v[114:117], v[192:195], v[224:227], v[114:117]
	v_mfma_f32_16x16x32_bf16 v[110:113], v[184:187], v[232:235], v[110:113]
	v_mfma_f32_16x16x32_bf16 v[106:109], v[192:195], v[232:235], v[106:109]
	v_mfma_f32_16x16x32_bf16 v[102:105], v[184:187], v[240:243], v[102:105]
	v_mfma_f32_16x16x32_bf16 v[98:101], v[192:195], v[240:243], v[98:101]
	s_setprio 0
	s_setprio 1
	v_mfma_f32_16x16x32_bf16 v[94:97], v[196:199], v[212:215], v[94:97]
	v_mfma_f32_16x16x32_bf16 v[90:93], v[204:207], v[212:215], v[90:93]
	v_mfma_f32_16x16x32_bf16 v[86:89], v[196:199], v[220:223], v[86:89]
	v_mfma_f32_16x16x32_bf16 v[82:85], v[204:207], v[220:223], v[82:85]
	v_mfma_f32_16x16x32_bf16 v[78:81], v[196:199], v[228:231], v[78:81]
	v_mfma_f32_16x16x32_bf16 v[74:77], v[204:207], v[228:231], v[74:77]
	v_mfma_f32_16x16x32_bf16 v[70:73], v[196:199], v[236:239], v[70:73]
	v_mfma_f32_16x16x32_bf16 v[66:69], v[204:207], v[236:239], v[66:69]
	v_mfma_f32_16x16x32_bf16 v[94:97], v[200:203], v[216:219], v[94:97]
	v_mfma_f32_16x16x32_bf16 v[90:93], v[208:211], v[216:219], v[90:93]
	v_mfma_f32_16x16x32_bf16 v[86:89], v[200:203], v[224:227], v[86:89]
	v_mfma_f32_16x16x32_bf16 v[82:85], v[208:211], v[224:227], v[82:85]
	v_mfma_f32_16x16x32_bf16 v[78:81], v[200:203], v[232:235], v[78:81]
	v_mfma_f32_16x16x32_bf16 v[74:77], v[208:211], v[232:235], v[74:77]
	v_mfma_f32_16x16x32_bf16 v[70:73], v[200:203], v[240:243], v[70:73]
	v_mfma_f32_16x16x32_bf16 v[66:69], v[208:211], v[240:243], v[66:69]
	s_setprio 0
	s_barrier
	s_mov_b32 m0, s40
	v_lshl_add_u64 v[244:245], v[244:245], 0, s[8:9]
	s_add_u32 s22, s22, 0x80080
	ds_read_b128 v[212:215], v178 offset:49152
	ds_read_b128 v[216:219], v178 offset:50176
	ds_read_b128 v[220:223], v178 offset:51200
	ds_read_b128 v[224:227], v178 offset:52224
	ds_read_b128 v[228:231], v178 offset:53248
	ds_read_b128 v[232:235], v178 offset:54272
	ds_read_b128 v[236:239], v178 offset:55296
	ds_read_b128 v[240:243], v178 offset:56320
	global_load_lds_dwordx4 v[244:245], off
	v_lshl_add_u64 v[244:245], v[246:247], 0, s[8:9]
	s_mov_b32 m0, s41
	s_addc_u32 s23, s23, 0
	global_load_lds_dwordx4 v[244:245], off
	v_lshl_add_u64 v[244:245], s[22:23], 0, v[132:133]
	s_mov_b32 m0, s42
	s_nop 0
	global_load_lds_dwordx4 v[244:245], off
	v_lshl_add_u64 v[244:245], s[22:23], 0, v[136:137]
	s_mov_b32 m0, s43
	s_nop 0
	global_load_lds_dwordx4 v[244:245], off
	v_lshl_add_u64 v[244:245], v[248:249], 0, s[8:9]
	s_mov_b32 m0, s17
	s_nop 0
	global_load_lds_dwordx4 v[244:245], off
	v_lshl_add_u64 v[244:245], v[250:251], 0, s[8:9]
	s_mov_b32 m0, s26
	s_nop 0
	global_load_lds_dwordx4 v[244:245], off
	s_waitcnt vmcnt(8)
	s_waitcnt lgkmcnt(0)
	s_barrier
	s_setprio 1
	s_waitcnt lgkmcnt(0)
	v_mfma_f32_16x16x32_bf16 v[62:65], v[180:183], v[212:215], v[62:65]
	v_mfma_f32_16x16x32_bf16 v[58:61], v[188:191], v[212:215], v[58:61]
	v_mfma_f32_16x16x32_bf16 v[54:57], v[180:183], v[220:223], v[54:57]
	v_mfma_f32_16x16x32_bf16 v[50:53], v[188:191], v[220:223], v[50:53]
	v_mfma_f32_16x16x32_bf16 v[46:49], v[180:183], v[228:231], v[46:49]
	v_mfma_f32_16x16x32_bf16 v[42:45], v[188:191], v[228:231], v[42:45]
	v_mfma_f32_16x16x32_bf16 v[38:41], v[180:183], v[236:239], v[38:41]
	v_mfma_f32_16x16x32_bf16 v[34:37], v[188:191], v[236:239], v[34:37]
	v_mfma_f32_16x16x32_bf16 v[62:65], v[184:187], v[216:219], v[62:65]
	v_mfma_f32_16x16x32_bf16 v[58:61], v[192:195], v[216:219], v[58:61]
	v_mfma_f32_16x16x32_bf16 v[54:57], v[184:187], v[224:227], v[54:57]
	v_mfma_f32_16x16x32_bf16 v[50:53], v[192:195], v[224:227], v[50:53]
	v_mfma_f32_16x16x32_bf16 v[46:49], v[184:187], v[232:235], v[46:49]
	v_mfma_f32_16x16x32_bf16 v[42:45], v[192:195], v[232:235], v[42:45]
	v_mfma_f32_16x16x32_bf16 v[38:41], v[184:187], v[240:243], v[38:41]
	v_mfma_f32_16x16x32_bf16 v[34:37], v[192:195], v[240:243], v[34:37]
	s_setprio 0
	s_setprio 1
	v_mfma_f32_16x16x32_bf16 v[30:33], v[196:199], v[212:215], v[30:33]
	v_mfma_f32_16x16x32_bf16 v[26:29], v[204:207], v[212:215], v[26:29]
	v_mfma_f32_16x16x32_bf16 v[22:25], v[196:199], v[220:223], v[22:25]
	v_mfma_f32_16x16x32_bf16 v[18:21], v[204:207], v[220:223], v[18:21]
	v_mfma_f32_16x16x32_bf16 v[14:17], v[196:199], v[228:231], v[14:17]
	v_mfma_f32_16x16x32_bf16 v[10:13], v[204:207], v[228:231], v[10:13]
	v_mfma_f32_16x16x32_bf16 v[6:9], v[196:199], v[236:239], v[6:9]
	v_mfma_f32_16x16x32_bf16 v[2:5], v[204:207], v[236:239], v[2:5]
	v_mfma_f32_16x16x32_bf16 v[30:33], v[200:203], v[216:219], v[30:33]
	v_mfma_f32_16x16x32_bf16 v[26:29], v[208:211], v[216:219], v[26:29]
	v_mfma_f32_16x16x32_bf16 v[22:25], v[200:203], v[224:227], v[22:25]
	v_mfma_f32_16x16x32_bf16 v[18:21], v[208:211], v[224:227], v[18:21]
	v_mfma_f32_16x16x32_bf16 v[14:17], v[200:203], v[232:235], v[14:17]
	v_mfma_f32_16x16x32_bf16 v[10:13], v[208:211], v[232:235], v[10:13]
	v_mfma_f32_16x16x32_bf16 v[6:9], v[200:203], v[240:243], v[6:9]
	v_mfma_f32_16x16x32_bf16 v[2:5], v[208:211], v[240:243], v[2:5]
	s_setprio 0
	s_add_i32 s46, s46, 2
	s_add_u32 s20, s20, 0x100
	s_addc_u32 s21, s21, 0
	s_add_u32 s44, s44, 0x100
	s_addc_u32 s45, s45, 0
	s_cmp_gt_u32 s46, 5
	s_barrier
	s_cbranch_scc0 .LBB0_1029
	s_and_b64 vcc, exec, s[10:11]
	s_cbranch_vccnz .LBB0_1034
	s_mov_b64 s[20:21], -1
	s_and_b64 vcc, exec, s[18:19]
	s_cbranch_vccnz .LBB0_1035

.LBB0_1134:
	s_ashr_i32 s29, s28, 31
	s_lshl_b64 s[30:31], s[28:29], 19
	s_add_u32 s30, s3, s30
	s_addc_u32 s31, s14, s31
	s_and_b64 s[34:35], s[0:1], exec
	s_cselect_b32 s29, s31, s39
	s_cselect_b32 s57, s30, s38
	s_ashr_i32 s27, s26, 31
	s_lshl_b64 s[34:35], s[26:27], 19
	s_add_u32 s34, s15, s34
	s_addc_u32 s35, s16, s35
	s_and_b64 s[42:43], s[0:1], exec
	s_cselect_b32 s27, s35, s41
	s_cselect_b32 s58, s34, s40
	s_add_u32 s59, s40, 0x100
	s_addc_u32 s60, s41, 0
	s_mov_b32 s61, -2
	ds_read_b128 v[146:149], v156
	ds_read_b128 v[150:153], v156 offset:1024
	ds_read_b128 v[160:163], v156 offset:2048
	ds_read_b128 v[164:167], v156 offset:3072
	ds_read_b128 v[168:171], v157
	ds_read_b128 v[178:181], v157 offset:1024
	ds_read_b128 v[182:185], v157 offset:2048
	ds_read_b128 v[186:189], v157 offset:3072
	s_add_u32 s40, s38, 0x100
	s_addc_u32 s41, s39, 0
	s_cmp_eq_u32 s61, 12
	s_cselect_b32 s45, s29, s41
	s_cselect_b32 s44, s57, s40
	s_cselect_b32 s43, s27, s60
	s_cselect_b32 s42, s58, s59
	v_lshl_add_u64 v[172:173], s[38:39], 0, v[138:139]
	s_add_i32 m0, s37, 0xc000
	ds_read_b128 v[190:193], v158
	ds_read_b128 v[194:197], v158 offset:1024
	ds_read_b128 v[198:201], v158 offset:2048
	ds_read_b128 v[202:205], v158 offset:3072
	ds_read_b128 v[206:209], v158 offset:4096
	ds_read_b128 v[210:213], v158 offset:5120
	ds_read_b128 v[214:217], v158 offset:6144
	ds_read_b128 v[218:221], v158 offset:7168
	global_load_lds_dwordx4 v[172:173], off
	v_lshl_add_u64 v[172:173], s[38:39], 0, v[140:141]
	s_add_i32 m0, s37, 0xe000
	s_nop 0
	global_load_lds_dwordx4 v[172:173], off
	s_waitcnt vmcnt(8)
	s_waitcnt lgkmcnt(0)
	s_barrier
	s_setprio 1
	s_waitcnt lgkmcnt(0)
	v_mfma_f32_16x16x32_bf16 v[126:129], v[146:149], v[190:193], 0
	v_mfma_f32_16x16x32_bf16 v[122:125], v[160:163], v[190:193], 0
	v_mfma_f32_16x16x32_bf16 v[110:113], v[146:149], v[198:201], 0
	v_mfma_f32_16x16x32_bf16 v[106:109], v[160:163], v[198:201], 0
	v_mfma_f32_16x16x32_bf16 v[94:97], v[146:149], v[206:209], 0
	v_mfma_f32_16x16x32_bf16 v[90:93], v[160:163], v[206:209], 0
	v_mfma_f32_16x16x32_bf16 v[78:81], v[146:149], v[214:217], 0
	v_mfma_f32_16x16x32_bf16 v[74:77], v[160:163], v[214:217], 0
	v_mfma_f32_16x16x32_bf16 v[126:129], v[150:153], v[194:197], v[126:129]
	v_mfma_f32_16x16x32_bf16 v[122:125], v[164:167], v[194:197], v[122:125]
	v_mfma_f32_16x16x32_bf16 v[110:113], v[150:153], v[202:205], v[110:113]
	v_mfma_f32_16x16x32_bf16 v[106:109], v[164:167], v[202:205], v[106:109]
	v_mfma_f32_16x16x32_bf16 v[94:97], v[150:153], v[210:213], v[94:97]
	v_mfma_f32_16x16x32_bf16 v[90:93], v[164:167], v[210:213], v[90:93]
	v_mfma_f32_16x16x32_bf16 v[78:81], v[150:153], v[218:221], v[78:81]
	v_mfma_f32_16x16x32_bf16 v[74:77], v[164:167], v[218:221], v[74:77]
	s_setprio 0
	s_setprio 1
	v_mfma_f32_16x16x32_bf16 v[118:121], v[168:171], v[190:193], 0
	v_mfma_f32_16x16x32_bf16 v[114:117], v[182:185], v[190:193], 0
	v_mfma_f32_16x16x32_bf16 v[102:105], v[168:171], v[198:201], 0
	v_mfma_f32_16x16x32_bf16 v[98:101], v[182:185], v[198:201], 0
	v_mfma_f32_16x16x32_bf16 v[86:89], v[168:171], v[206:209], 0
	v_mfma_f32_16x16x32_bf16 v[82:85], v[182:185], v[206:209], 0
	v_mfma_f32_16x16x32_bf16 v[70:73], v[168:171], v[214:217], 0
	v_mfma_f32_16x16x32_bf16 v[66:69], v[182:185], v[214:217], 0
	v_mfma_f32_16x16x32_bf16 v[118:121], v[178:181], v[194:197], v[118:121]
	v_mfma_f32_16x16x32_bf16 v[114:117], v[186:189], v[194:197], v[114:117]
	v_mfma_f32_16x16x32_bf16 v[102:105], v[178:181], v[202:205], v[102:105]
	v_mfma_f32_16x16x32_bf16 v[98:101], v[186:189], v[202:205], v[98:101]
	v_mfma_f32_16x16x32_bf16 v[86:89], v[178:181], v[210:213], v[86:89]
	v_mfma_f32_16x16x32_bf16 v[82:85], v[186:189], v[210:213], v[82:85]
	v_mfma_f32_16x16x32_bf16 v[70:73], v[178:181], v[218:221], v[70:73]
	v_mfma_f32_16x16x32_bf16 v[66:69], v[186:189], v[218:221], v[66:69]
	s_setprio 0
	s_barrier
	s_add_i32 s38, s54, s46
	v_lshl_add_u64 v[172:173], s[42:43], 0, v[132:133]
	s_mov_b32 m0, s38
	ds_read_b128 v[190:193], v158 offset:16384
	ds_read_b128 v[194:197], v158 offset:17408
	ds_read_b128 v[198:201], v158 offset:18432
	ds_read_b128 v[202:205], v158 offset:19456
	ds_read_b128 v[206:209], v158 offset:20480
	ds_read_b128 v[210:213], v158 offset:21504
	ds_read_b128 v[214:217], v158 offset:22528
	ds_read_b128 v[218:221], v158 offset:23552
	global_load_lds_dwordx4 v[172:173], off
	s_add_i32 m0, s38, 0x2000
	s_add_u32 s38, s42, 0x40000
	v_lshl_add_u64 v[222:223], s[42:43], 0, v[136:137]
	s_addc_u32 s39, s43, 0
	s_add_i32 s62, s55, s46
	global_load_lds_dwordx4 v[222:223], off
	v_lshl_add_u64 v[224:225], s[38:39], 0, v[132:133]
	s_mov_b32 m0, s62
	v_lshl_add_u64 v[226:227], s[44:45], 0, v[134:135]
	global_load_lds_dwordx4 v[224:225], off
	v_lshl_add_u64 v[224:225], s[38:39], 0, v[136:137]
	s_add_i32 m0, s62, 0x2000
	s_nop 0
	global_load_lds_dwordx4 v[224:225], off
	v_lshl_add_u64 v[224:225], s[44:45], 0, v[130:131]
	s_mov_b32 m0, s37
	s_nop 0
	global_load_lds_dwordx4 v[224:225], off
	s_mov_b32 m0, s47
	s_nop 0
	global_load_lds_dwordx4 v[226:227], off
	s_waitcnt vmcnt(8)
	s_waitcnt lgkmcnt(0)
	s_barrier
	s_setprio 1
	s_waitcnt lgkmcnt(0)
	v_mfma_f32_16x16x32_bf16 v[62:65], v[146:149], v[190:193], 0
	v_mfma_f32_16x16x32_bf16 v[58:61], v[160:163], v[190:193], 0
	v_mfma_f32_16x16x32_bf16 v[46:49], v[146:149], v[198:201], 0
	v_mfma_f32_16x16x32_bf16 v[42:45], v[160:163], v[198:201], 0
	v_mfma_f32_16x16x32_bf16 v[30:33], v[146:149], v[206:209], 0
	v_mfma_f32_16x16x32_bf16 v[26:29], v[160:163], v[206:209], 0
	v_mfma_f32_16x16x32_bf16 v[14:17], v[146:149], v[214:217], 0
	v_mfma_f32_16x16x32_bf16 v[10:13], v[160:163], v[214:217], 0
	v_mfma_f32_16x16x32_bf16 v[62:65], v[150:153], v[194:197], v[62:65]
	v_mfma_f32_16x16x32_bf16 v[58:61], v[164:167], v[194:197], v[58:61]
	v_mfma_f32_16x16x32_bf16 v[46:49], v[150:153], v[202:205], v[46:49]
	v_mfma_f32_16x16x32_bf16 v[42:45], v[164:167], v[202:205], v[42:45]
	v_mfma_f32_16x16x32_bf16 v[30:33], v[150:153], v[210:213], v[30:33]
	v_mfma_f32_16x16x32_bf16 v[26:29], v[164:167], v[210:213], v[26:29]
	v_mfma_f32_16x16x32_bf16 v[14:17], v[150:153], v[218:221], v[14:17]
	v_mfma_f32_16x16x32_bf16 v[10:13], v[164:167], v[218:221], v[10:13]
	s_setprio 0
	s_setprio 1
	v_mfma_f32_16x16x32_bf16 v[54:57], v[168:171], v[190:193], 0
	v_mfma_f32_16x16x32_bf16 v[50:53], v[182:185], v[190:193], 0
	v_mfma_f32_16x16x32_bf16 v[38:41], v[168:171], v[198:201], 0
	v_mfma_f32_16x16x32_bf16 v[34:37], v[182:185], v[198:201], 0
	v_mfma_f32_16x16x32_bf16 v[22:25], v[168:171], v[206:209], 0
	v_mfma_f32_16x16x32_bf16 v[18:21], v[182:185], v[206:209], 0
	v_mfma_f32_16x16x32_bf16 v[6:9], v[168:171], v[214:217], 0
	v_mfma_f32_16x16x32_bf16 v[2:5], v[182:185], v[214:217], 0
	v_mfma_f32_16x16x32_bf16 v[54:57], v[178:181], v[194:197], v[54:57]
	v_mfma_f32_16x16x32_bf16 v[50:53], v[186:189], v[194:197], v[50:53]
	v_mfma_f32_16x16x32_bf16 v[38:41], v[178:181], v[202:205], v[38:41]
	v_mfma_f32_16x16x32_bf16 v[34:37], v[186:189], v[202:205], v[34:37]
	v_mfma_f32_16x16x32_bf16 v[22:25], v[178:181], v[210:213], v[22:25]
	v_mfma_f32_16x16x32_bf16 v[18:21], v[186:189], v[210:213], v[18:21]
	v_mfma_f32_16x16x32_bf16 v[6:9], v[178:181], v[218:221], v[6:9]
	v_mfma_f32_16x16x32_bf16 v[2:5], v[186:189], v[218:221], v[2:5]
	s_setprio 0
	s_barrier
	s_add_i32 s62, 0, 0x18000
	v_add_u32_e32 v159, s62, v154
	s_add_i32 s63, 0, 0x1c000
	ds_read_b128 v[146:149], v159
	ds_read_b128 v[150:153], v159 offset:1024
	ds_read_b128 v[160:163], v159 offset:2048
	ds_read_b128 v[164:167], v159 offset:3072
	v_add_u32_e32 v159, s63, v154
	ds_read_b128 v[168:171], v159
	ds_read_b128 v[178:181], v159 offset:1024
	ds_read_b128 v[182:185], v159 offset:2048
	ds_read_b128 v[186:189], v159 offset:3072
	s_add_u32 s38, s44, 0x40000
	s_addc_u32 s39, s45, 0
	s_mov_b32 m0, s48
	v_lshl_add_u64 v[228:229], s[38:39], 0, v[130:131]
	ds_read_b128 v[190:193], v158 offset:32768
	ds_read_b128 v[194:197], v158 offset:33792
	ds_read_b128 v[198:201], v158 offset:34816
	ds_read_b128 v[202:205], v158 offset:35840
	ds_read_b128 v[206:209], v158 offset:36864
	ds_read_b128 v[210:213], v158 offset:37888
	ds_read_b128 v[214:217], v158 offset:38912
	ds_read_b128 v[218:221], v158 offset:39936
	global_load_lds_dwordx4 v[228:229], off
	v_lshl_add_u64 v[228:229], s[38:39], 0, v[134:135]
	s_mov_b32 m0, s49
	s_nop 0
	global_load_lds_dwordx4 v[228:229], off
	s_waitcnt vmcnt(8)
	s_waitcnt lgkmcnt(0)
	s_barrier
	s_setprio 1
	s_waitcnt lgkmcnt(0)
	v_mfma_f32_16x16x32_bf16 v[126:129], v[146:149], v[190:193], v[126:129]
	v_mfma_f32_16x16x32_bf16 v[122:125], v[160:163], v[190:193], v[122:125]
	v_mfma_f32_16x16x32_bf16 v[110:113], v[146:149], v[198:201], v[110:113]
	v_mfma_f32_16x16x32_bf16 v[106:109], v[160:163], v[198:201], v[106:109]
	v_mfma_f32_16x16x32_bf16 v[94:97], v[146:149], v[206:209], v[94:97]
	v_mfma_f32_16x16x32_bf16 v[90:93], v[160:163], v[206:209], v[90:93]
	v_mfma_f32_16x16x32_bf16 v[78:81], v[146:149], v[214:217], v[78:81]
	v_mfma_f32_16x16x32_bf16 v[74:77], v[160:163], v[214:217], v[74:77]
	v_mfma_f32_16x16x32_bf16 v[126:129], v[150:153], v[194:197], v[126:129]
	v_mfma_f32_16x16x32_bf16 v[122:125], v[164:167], v[194:197], v[122:125]
	v_mfma_f32_16x16x32_bf16 v[110:113], v[150:153], v[202:205], v[110:113]
	v_mfma_f32_16x16x32_bf16 v[106:109], v[164:167], v[202:205], v[106:109]
	v_mfma_f32_16x16x32_bf16 v[94:97], v[150:153], v[210:213], v[94:97]
	v_mfma_f32_16x16x32_bf16 v[90:93], v[164:167], v[210:213], v[90:93]
	v_mfma_f32_16x16x32_bf16 v[78:81], v[150:153], v[218:221], v[78:81]
	v_mfma_f32_16x16x32_bf16 v[74:77], v[164:167], v[218:221], v[74:77]
	s_setprio 0
	s_setprio 1
	v_mfma_f32_16x16x32_bf16 v[118:121], v[168:171], v[190:193], v[118:121]
	v_mfma_f32_16x16x32_bf16 v[114:117], v[182:185], v[190:193], v[114:117]
	v_mfma_f32_16x16x32_bf16 v[102:105], v[168:171], v[198:201], v[102:105]
	v_mfma_f32_16x16x32_bf16 v[98:101], v[182:185], v[198:201], v[98:101]
	v_mfma_f32_16x16x32_bf16 v[86:89], v[168:171], v[206:209], v[86:89]
	v_mfma_f32_16x16x32_bf16 v[82:85], v[182:185], v[206:209], v[82:85]
	v_mfma_f32_16x16x32_bf16 v[70:73], v[168:171], v[214:217], v[70:73]
	v_mfma_f32_16x16x32_bf16 v[66:69], v[182:185], v[214:217], v[66:69]
	v_mfma_f32_16x16x32_bf16 v[118:121], v[178:181], v[194:197], v[118:121]
	v_mfma_f32_16x16x32_bf16 v[114:117], v[186:189], v[194:197], v[114:117]
	v_mfma_f32_16x16x32_bf16 v[102:105], v[178:181], v[202:205], v[102:105]
	v_mfma_f32_16x16x32_bf16 v[98:101], v[186:189], v[202:205], v[98:101]
	v_mfma_f32_16x16x32_bf16 v[86:89], v[178:181], v[210:213], v[86:89]
	v_mfma_f32_16x16x32_bf16 v[82:85], v[186:189], v[210:213], v[82:85]
	v_mfma_f32_16x16x32_bf16 v[70:73], v[178:181], v[218:221], v[70:73]
	v_mfma_f32_16x16x32_bf16 v[66:69], v[186:189], v[218:221], v[66:69]
	s_setprio 0
	s_barrier
	s_add_i32 s38, s62, s46
	v_lshl_add_u64 v[172:173], v[172:173], 0, s[12:13]
	s_mov_b32 m0, s38
	ds_read_b128 v[190:193], v158 offset:49152
	ds_read_b128 v[194:197], v158 offset:50176
	ds_read_b128 v[198:201], v158 offset:51200
	ds_read_b128 v[202:205], v158 offset:52224
	ds_read_b128 v[206:209], v158 offset:53248
	ds_read_b128 v[210:213], v158 offset:54272
	ds_read_b128 v[214:217], v158 offset:55296
	ds_read_b128 v[218:221], v158 offset:56320
	global_load_lds_dwordx4 v[172:173], off
	s_add_i32 m0, s38, 0x2000
	s_add_u32 s38, s42, 0x40080
	v_lshl_add_u64 v[172:173], v[222:223], 0, s[12:13]
	s_addc_u32 s39, s43, 0
	s_add_i32 s42, s63, s46
	global_load_lds_dwordx4 v[172:173], off
	v_lshl_add_u64 v[172:173], s[38:39], 0, v[132:133]
	s_mov_b32 m0, s42
	s_nop 0
	global_load_lds_dwordx4 v[172:173], off
	v_lshl_add_u64 v[172:173], s[38:39], 0, v[136:137]
	s_add_i32 m0, s42, 0x2000
	s_nop 0
	global_load_lds_dwordx4 v[172:173], off
	v_lshl_add_u64 v[172:173], v[224:225], 0, s[12:13]
	s_mov_b32 m0, s51
	s_nop 0
	global_load_lds_dwordx4 v[172:173], off
	v_lshl_add_u64 v[172:173], v[226:227], 0, s[12:13]
	s_mov_b32 m0, s52
	s_nop 0
	global_load_lds_dwordx4 v[172:173], off
	s_waitcnt vmcnt(8)
	s_waitcnt lgkmcnt(0)
	s_barrier
	s_setprio 1
	s_waitcnt lgkmcnt(0)
	v_mfma_f32_16x16x32_bf16 v[62:65], v[146:149], v[190:193], v[62:65]
	v_mfma_f32_16x16x32_bf16 v[58:61], v[160:163], v[190:193], v[58:61]
	v_mfma_f32_16x16x32_bf16 v[46:49], v[146:149], v[198:201], v[46:49]
	v_mfma_f32_16x16x32_bf16 v[42:45], v[160:163], v[198:201], v[42:45]
	v_mfma_f32_16x16x32_bf16 v[30:33], v[146:149], v[206:209], v[30:33]
	v_mfma_f32_16x16x32_bf16 v[26:29], v[160:163], v[206:209], v[26:29]
	v_mfma_f32_16x16x32_bf16 v[14:17], v[146:149], v[214:217], v[14:17]
	v_mfma_f32_16x16x32_bf16 v[10:13], v[160:163], v[214:217], v[10:13]
	v_mfma_f32_16x16x32_bf16 v[62:65], v[150:153], v[194:197], v[62:65]
	v_mfma_f32_16x16x32_bf16 v[58:61], v[164:167], v[194:197], v[58:61]
	v_mfma_f32_16x16x32_bf16 v[46:49], v[150:153], v[202:205], v[46:49]
	v_mfma_f32_16x16x32_bf16 v[42:45], v[164:167], v[202:205], v[42:45]
	v_mfma_f32_16x16x32_bf16 v[30:33], v[150:153], v[210:213], v[30:33]
	v_mfma_f32_16x16x32_bf16 v[26:29], v[164:167], v[210:213], v[26:29]
	v_mfma_f32_16x16x32_bf16 v[14:17], v[150:153], v[218:221], v[14:17]
	v_mfma_f32_16x16x32_bf16 v[10:13], v[164:167], v[218:221], v[10:13]
	s_setprio 0
	s_setprio 1
	v_mfma_f32_16x16x32_bf16 v[54:57], v[168:171], v[190:193], v[54:57]
	v_mfma_f32_16x16x32_bf16 v[50:53], v[182:185], v[190:193], v[50:53]
	v_mfma_f32_16x16x32_bf16 v[38:41], v[168:171], v[198:201], v[38:41]
	v_mfma_f32_16x16x32_bf16 v[34:37], v[182:185], v[198:201], v[34:37]
	v_mfma_f32_16x16x32_bf16 v[22:25], v[168:171], v[206:209], v[22:25]
	v_mfma_f32_16x16x32_bf16 v[18:21], v[182:185], v[206:209], v[18:21]
	v_mfma_f32_16x16x32_bf16 v[6:9], v[168:171], v[214:217], v[6:9]
	v_mfma_f32_16x16x32_bf16 v[2:5], v[182:185], v[214:217], v[2:5]
	v_mfma_f32_16x16x32_bf16 v[54:57], v[178:181], v[194:197], v[54:57]
	v_mfma_f32_16x16x32_bf16 v[50:53], v[186:189], v[194:197], v[50:53]
	v_mfma_f32_16x16x32_bf16 v[38:41], v[178:181], v[202:205], v[38:41]
	v_mfma_f32_16x16x32_bf16 v[34:37], v[186:189], v[202:205], v[34:37]
	v_mfma_f32_16x16x32_bf16 v[22:25], v[178:181], v[210:213], v[22:25]
	v_mfma_f32_16x16x32_bf16 v[18:21], v[186:189], v[210:213], v[18:21]
	v_mfma_f32_16x16x32_bf16 v[6:9], v[178:181], v[218:221], v[6:9]
	v_mfma_f32_16x16x32_bf16 v[2:5], v[186:189], v[218:221], v[2:5]
	s_setprio 0
	s_add_i32 s61, s61, 2
	s_add_u32 s59, s59, 0x100
	s_addc_u32 s60, s60, 0
	s_cmp_gt_u32 s61, 13
	s_mov_b64 s[38:39], s[40:41]
	s_barrier
	s_cbranch_scc0 .LBB0_1135
	s_branch .Lpeel_exit_1135
.LBB0_1135:
	ds_read_b128 v[146:149], v156
	ds_read_b128 v[150:153], v156 offset:1024
	ds_read_b128 v[160:163], v156 offset:2048
	ds_read_b128 v[164:167], v156 offset:3072
	ds_read_b128 v[168:171], v157
	ds_read_b128 v[178:181], v157 offset:1024
	ds_read_b128 v[182:185], v157 offset:2048
	ds_read_b128 v[186:189], v157 offset:3072
	s_add_u32 s40, s38, 0x100
	s_addc_u32 s41, s39, 0
	s_cmp_eq_u32 s61, 12
	s_cselect_b32 s45, s29, s41
	s_cselect_b32 s44, s57, s40
	s_cselect_b32 s43, s27, s60
	s_cselect_b32 s42, s58, s59
	v_lshl_add_u64 v[172:173], s[38:39], 0, v[138:139]
	s_add_i32 m0, s37, 0xc000
	ds_read_b128 v[190:193], v158
	ds_read_b128 v[194:197], v158 offset:1024
	ds_read_b128 v[198:201], v158 offset:2048
	ds_read_b128 v[202:205], v158 offset:3072
	ds_read_b128 v[206:209], v158 offset:4096
	ds_read_b128 v[210:213], v158 offset:5120
	ds_read_b128 v[214:217], v158 offset:6144
	ds_read_b128 v[218:221], v158 offset:7168
	global_load_lds_dwordx4 v[172:173], off
	v_lshl_add_u64 v[172:173], s[38:39], 0, v[140:141]
	s_add_i32 m0, s37, 0xe000
	s_nop 0
	global_load_lds_dwordx4 v[172:173], off
	s_waitcnt vmcnt(8)
	s_waitcnt lgkmcnt(0)
	s_barrier
	s_setprio 1
	s_waitcnt lgkmcnt(0)
	v_mfma_f32_16x16x32_bf16 v[126:129], v[146:149], v[190:193], v[126:129]
	v_mfma_f32_16x16x32_bf16 v[122:125], v[160:163], v[190:193], v[122:125]
	v_mfma_f32_16x16x32_bf16 v[110:113], v[146:149], v[198:201], v[110:113]
	v_mfma_f32_16x16x32_bf16 v[106:109], v[160:163], v[198:201], v[106:109]
	v_mfma_f32_16x16x32_bf16 v[94:97], v[146:149], v[206:209], v[94:97]
	v_mfma_f32_16x16x32_bf16 v[90:93], v[160:163], v[206:209], v[90:93]
	v_mfma_f32_16x16x32_bf16 v[78:81], v[146:149], v[214:217], v[78:81]
	v_mfma_f32_16x16x32_bf16 v[74:77], v[160:163], v[214:217], v[74:77]
	v_mfma_f32_16x16x32_bf16 v[126:129], v[150:153], v[194:197], v[126:129]
	v_mfma_f32_16x16x32_bf16 v[122:125], v[164:167], v[194:197], v[122:125]
	v_mfma_f32_16x16x32_bf16 v[110:113], v[150:153], v[202:205], v[110:113]
	v_mfma_f32_16x16x32_bf16 v[106:109], v[164:167], v[202:205], v[106:109]
	v_mfma_f32_16x16x32_bf16 v[94:97], v[150:153], v[210:213], v[94:97]
	v_mfma_f32_16x16x32_bf16 v[90:93], v[164:167], v[210:213], v[90:93]
	v_mfma_f32_16x16x32_bf16 v[78:81], v[150:153], v[218:221], v[78:81]
	v_mfma_f32_16x16x32_bf16 v[74:77], v[164:167], v[218:221], v[74:77]
	s_setprio 0
	s_setprio 1
	v_mfma_f32_16x16x32_bf16 v[118:121], v[168:171], v[190:193], v[118:121]
	v_mfma_f32_16x16x32_bf16 v[114:117], v[182:185], v[190:193], v[114:117]
	v_mfma_f32_16x16x32_bf16 v[102:105], v[168:171], v[198:201], v[102:105]
	v_mfma_f32_16x16x32_bf16 v[98:101], v[182:185], v[198:201], v[98:101]
	v_mfma_f32_16x16x32_bf16 v[86:89], v[168:171], v[206:209], v[86:89]
	v_mfma_f32_16x16x32_bf16 v[82:85], v[182:185], v[206:209], v[82:85]
	v_mfma_f32_16x16x32_bf16 v[70:73], v[168:171], v[214:217], v[70:73]
	v_mfma_f32_16x16x32_bf16 v[66:69], v[182:185], v[214:217], v[66:69]
	v_mfma_f32_16x16x32_bf16 v[118:121], v[178:181], v[194:197], v[118:121]
	v_mfma_f32_16x16x32_bf16 v[114:117], v[186:189], v[194:197], v[114:117]
	v_mfma_f32_16x16x32_bf16 v[102:105], v[178:181], v[202:205], v[102:105]
	v_mfma_f32_16x16x32_bf16 v[98:101], v[186:189], v[202:205], v[98:101]
	v_mfma_f32_16x16x32_bf16 v[86:89], v[178:181], v[210:213], v[86:89]
	v_mfma_f32_16x16x32_bf16 v[82:85], v[186:189], v[210:213], v[82:85]
	v_mfma_f32_16x16x32_bf16 v[70:73], v[178:181], v[218:221], v[70:73]
	v_mfma_f32_16x16x32_bf16 v[66:69], v[186:189], v[218:221], v[66:69]
	s_setprio 0
	s_barrier
	s_add_i32 s38, s54, s46
	v_lshl_add_u64 v[172:173], s[42:43], 0, v[132:133]
	s_mov_b32 m0, s38
	ds_read_b128 v[190:193], v158 offset:16384
	ds_read_b128 v[194:197], v158 offset:17408
	ds_read_b128 v[198:201], v158 offset:18432
	ds_read_b128 v[202:205], v158 offset:19456
	ds_read_b128 v[206:209], v158 offset:20480
	ds_read_b128 v[210:213], v158 offset:21504
	ds_read_b128 v[214:217], v158 offset:22528
	ds_read_b128 v[218:221], v158 offset:23552
	global_load_lds_dwordx4 v[172:173], off
	s_add_i32 m0, s38, 0x2000
	s_add_u32 s38, s42, 0x40000
	v_lshl_add_u64 v[222:223], s[42:43], 0, v[136:137]
	s_addc_u32 s39, s43, 0
	s_add_i32 s62, s55, s46
	global_load_lds_dwordx4 v[222:223], off
	v_lshl_add_u64 v[224:225], s[38:39], 0, v[132:133]
	s_mov_b32 m0, s62
	v_lshl_add_u64 v[226:227], s[44:45], 0, v[134:135]
	global_load_lds_dwordx4 v[224:225], off
	v_lshl_add_u64 v[224:225], s[38:39], 0, v[136:137]
	s_add_i32 m0, s62, 0x2000
	s_nop 0
	global_load_lds_dwordx4 v[224:225], off
	v_lshl_add_u64 v[224:225], s[44:45], 0, v[130:131]
	s_mov_b32 m0, s37
	s_nop 0
	global_load_lds_dwordx4 v[224:225], off
	s_mov_b32 m0, s47
	s_nop 0
	global_load_lds_dwordx4 v[226:227], off
	s_waitcnt vmcnt(8)
	s_waitcnt lgkmcnt(0)
	s_barrier
	s_setprio 1
	s_waitcnt lgkmcnt(0)
	v_mfma_f32_16x16x32_bf16 v[62:65], v[146:149], v[190:193], v[62:65]
	v_mfma_f32_16x16x32_bf16 v[58:61], v[160:163], v[190:193], v[58:61]
	v_mfma_f32_16x16x32_bf16 v[46:49], v[146:149], v[198:201], v[46:49]
	v_mfma_f32_16x16x32_bf16 v[42:45], v[160:163], v[198:201], v[42:45]
	v_mfma_f32_16x16x32_bf16 v[30:33], v[146:149], v[206:209], v[30:33]
	v_mfma_f32_16x16x32_bf16 v[26:29], v[160:163], v[206:209], v[26:29]
	v_mfma_f32_16x16x32_bf16 v[14:17], v[146:149], v[214:217], v[14:17]
	v_mfma_f32_16x16x32_bf16 v[10:13], v[160:163], v[214:217], v[10:13]
	v_mfma_f32_16x16x32_bf16 v[62:65], v[150:153], v[194:197], v[62:65]
	v_mfma_f32_16x16x32_bf16 v[58:61], v[164:167], v[194:197], v[58:61]
	v_mfma_f32_16x16x32_bf16 v[46:49], v[150:153], v[202:205], v[46:49]
	v_mfma_f32_16x16x32_bf16 v[42:45], v[164:167], v[202:205], v[42:45]
	v_mfma_f32_16x16x32_bf16 v[30:33], v[150:153], v[210:213], v[30:33]
	v_mfma_f32_16x16x32_bf16 v[26:29], v[164:167], v[210:213], v[26:29]
	v_mfma_f32_16x16x32_bf16 v[14:17], v[150:153], v[218:221], v[14:17]
	v_mfma_f32_16x16x32_bf16 v[10:13], v[164:167], v[218:221], v[10:13]
	s_setprio 0
	s_setprio 1
	v_mfma_f32_16x16x32_bf16 v[54:57], v[168:171], v[190:193], v[54:57]
	v_mfma_f32_16x16x32_bf16 v[50:53], v[182:185], v[190:193], v[50:53]
	v_mfma_f32_16x16x32_bf16 v[38:41], v[168:171], v[198:201], v[38:41]
	v_mfma_f32_16x16x32_bf16 v[34:37], v[182:185], v[198:201], v[34:37]
	v_mfma_f32_16x16x32_bf16 v[22:25], v[168:171], v[206:209], v[22:25]
	v_mfma_f32_16x16x32_bf16 v[18:21], v[182:185], v[206:209], v[18:21]
	v_mfma_f32_16x16x32_bf16 v[6:9], v[168:171], v[214:217], v[6:9]
	v_mfma_f32_16x16x32_bf16 v[2:5], v[182:185], v[214:217], v[2:5]
	v_mfma_f32_16x16x32_bf16 v[54:57], v[178:181], v[194:197], v[54:57]
	v_mfma_f32_16x16x32_bf16 v[50:53], v[186:189], v[194:197], v[50:53]
	v_mfma_f32_16x16x32_bf16 v[38:41], v[178:181], v[202:205], v[38:41]
	v_mfma_f32_16x16x32_bf16 v[34:37], v[186:189], v[202:205], v[34:37]
	v_mfma_f32_16x16x32_bf16 v[22:25], v[178:181], v[210:213], v[22:25]
	v_mfma_f32_16x16x32_bf16 v[18:21], v[186:189], v[210:213], v[18:21]
	v_mfma_f32_16x16x32_bf16 v[6:9], v[178:181], v[218:221], v[6:9]
	v_mfma_f32_16x16x32_bf16 v[2:5], v[186:189], v[218:221], v[2:5]
	s_setprio 0
	s_barrier
	s_add_i32 s62, 0, 0x18000
	v_add_u32_e32 v159, s62, v154
	s_add_i32 s63, 0, 0x1c000
	ds_read_b128 v[146:149], v159
	ds_read_b128 v[150:153], v159 offset:1024
	ds_read_b128 v[160:163], v159 offset:2048
	ds_read_b128 v[164:167], v159 offset:3072
	v_add_u32_e32 v159, s63, v154
	ds_read_b128 v[168:171], v159
	ds_read_b128 v[178:181], v159 offset:1024
	ds_read_b128 v[182:185], v159 offset:2048
	ds_read_b128 v[186:189], v159 offset:3072
	s_add_u32 s38, s44, 0x40000
	s_addc_u32 s39, s45, 0
	s_mov_b32 m0, s48
	v_lshl_add_u64 v[228:229], s[38:39], 0, v[130:131]
	ds_read_b128 v[190:193], v158 offset:32768
	ds_read_b128 v[194:197], v158 offset:33792
	ds_read_b128 v[198:201], v158 offset:34816
	ds_read_b128 v[202:205], v158 offset:35840
	ds_read_b128 v[206:209], v158 offset:36864
	ds_read_b128 v[210:213], v158 offset:37888
	ds_read_b128 v[214:217], v158 offset:38912
	ds_read_b128 v[218:221], v158 offset:39936
	global_load_lds_dwordx4 v[228:229], off
	v_lshl_add_u64 v[228:229], s[38:39], 0, v[134:135]
	s_mov_b32 m0, s49
	s_nop 0
	global_load_lds_dwordx4 v[228:229], off
	s_waitcnt vmcnt(8)
	s_waitcnt lgkmcnt(0)
	s_barrier
	s_setprio 1
	s_waitcnt lgkmcnt(0)
	v_mfma_f32_16x16x32_bf16 v[126:129], v[146:149], v[190:193], v[126:129]
	v_mfma_f32_16x16x32_bf16 v[122:125], v[160:163], v[190:193], v[122:125]
	v_mfma_f32_16x16x32_bf16 v[110:113], v[146:149], v[198:201], v[110:113]
	v_mfma_f32_16x16x32_bf16 v[106:109], v[160:163], v[198:201], v[106:109]
	v_mfma_f32_16x16x32_bf16 v[94:97], v[146:149], v[206:209], v[94:97]
	v_mfma_f32_16x16x32_bf16 v[90:93], v[160:163], v[206:209], v[90:93]
	v_mfma_f32_16x16x32_bf16 v[78:81], v[146:149], v[214:217], v[78:81]
	v_mfma_f32_16x16x32_bf16 v[74:77], v[160:163], v[214:217], v[74:77]
	v_mfma_f32_16x16x32_bf16 v[126:129], v[150:153], v[194:197], v[126:129]
	v_mfma_f32_16x16x32_bf16 v[122:125], v[164:167], v[194:197], v[122:125]
	v_mfma_f32_16x16x32_bf16 v[110:113], v[150:153], v[202:205], v[110:113]
	v_mfma_f32_16x16x32_bf16 v[106:109], v[164:167], v[202:205], v[106:109]
	v_mfma_f32_16x16x32_bf16 v[94:97], v[150:153], v[210:213], v[94:97]
	v_mfma_f32_16x16x32_bf16 v[90:93], v[164:167], v[210:213], v[90:93]
	v_mfma_f32_16x16x32_bf16 v[78:81], v[150:153], v[218:221], v[78:81]
	v_mfma_f32_16x16x32_bf16 v[74:77], v[164:167], v[218:221], v[74:77]
	s_setprio 0
	s_setprio 1
	v_mfma_f32_16x16x32_bf16 v[118:121], v[168:171], v[190:193], v[118:121]
	v_mfma_f32_16x16x32_bf16 v[114:117], v[182:185], v[190:193], v[114:117]
	v_mfma_f32_16x16x32_bf16 v[102:105], v[168:171], v[198:201], v[102:105]
	v_mfma_f32_16x16x32_bf16 v[98:101], v[182:185], v[198:201], v[98:101]
	v_mfma_f32_16x16x32_bf16 v[86:89], v[168:171], v[206:209], v[86:89]
	v_mfma_f32_16x16x32_bf16 v[82:85], v[182:185], v[206:209], v[82:85]
	v_mfma_f32_16x16x32_bf16 v[70:73], v[168:171], v[214:217], v[70:73]
	v_mfma_f32_16x16x32_bf16 v[66:69], v[182:185], v[214:217], v[66:69]
	v_mfma_f32_16x16x32_bf16 v[118:121], v[178:181], v[194:197], v[118:121]
	v_mfma_f32_16x16x32_bf16 v[114:117], v[186:189], v[194:197], v[114:117]
	v_mfma_f32_16x16x32_bf16 v[102:105], v[178:181], v[202:205], v[102:105]
	v_mfma_f32_16x16x32_bf16 v[98:101], v[186:189], v[202:205], v[98:101]
	v_mfma_f32_16x16x32_bf16 v[86:89], v[178:181], v[210:213], v[86:89]
	v_mfma_f32_16x16x32_bf16 v[82:85], v[186:189], v[210:213], v[82:85]
	v_mfma_f32_16x16x32_bf16 v[70:73], v[178:181], v[218:221], v[70:73]
	v_mfma_f32_16x16x32_bf16 v[66:69], v[186:189], v[218:221], v[66:69]
	s_setprio 0
	s_barrier
	s_add_i32 s38, s62, s46
	v_lshl_add_u64 v[172:173], v[172:173], 0, s[12:13]
	s_mov_b32 m0, s38
	ds_read_b128 v[190:193], v158 offset:49152
	ds_read_b128 v[194:197], v158 offset:50176
	ds_read_b128 v[198:201], v158 offset:51200
	ds_read_b128 v[202:205], v158 offset:52224
	ds_read_b128 v[206:209], v158 offset:53248
	ds_read_b128 v[210:213], v158 offset:54272
	ds_read_b128 v[214:217], v158 offset:55296
	ds_read_b128 v[218:221], v158 offset:56320
	global_load_lds_dwordx4 v[172:173], off
	s_add_i32 m0, s38, 0x2000
	s_add_u32 s38, s42, 0x40080
	v_lshl_add_u64 v[172:173], v[222:223], 0, s[12:13]
	s_addc_u32 s39, s43, 0
	s_add_i32 s42, s63, s46
	global_load_lds_dwordx4 v[172:173], off
	v_lshl_add_u64 v[172:173], s[38:39], 0, v[132:133]
	s_mov_b32 m0, s42
	s_nop 0
	global_load_lds_dwordx4 v[172:173], off
	v_lshl_add_u64 v[172:173], s[38:39], 0, v[136:137]
	s_add_i32 m0, s42, 0x2000
	s_nop 0
	global_load_lds_dwordx4 v[172:173], off
	v_lshl_add_u64 v[172:173], v[224:225], 0, s[12:13]
	s_mov_b32 m0, s51
	s_nop 0
	global_load_lds_dwordx4 v[172:173], off
	v_lshl_add_u64 v[172:173], v[226:227], 0, s[12:13]
	s_mov_b32 m0, s52
	s_nop 0
	global_load_lds_dwordx4 v[172:173], off
	s_waitcnt vmcnt(8)
	s_waitcnt lgkmcnt(0)
	s_barrier
	s_setprio 1
	s_waitcnt lgkmcnt(0)
	v_mfma_f32_16x16x32_bf16 v[62:65], v[146:149], v[190:193], v[62:65]
	v_mfma_f32_16x16x32_bf16 v[58:61], v[160:163], v[190:193], v[58:61]
	v_mfma_f32_16x16x32_bf16 v[46:49], v[146:149], v[198:201], v[46:49]
	v_mfma_f32_16x16x32_bf16 v[42:45], v[160:163], v[198:201], v[42:45]
	v_mfma_f32_16x16x32_bf16 v[30:33], v[146:149], v[206:209], v[30:33]
	v_mfma_f32_16x16x32_bf16 v[26:29], v[160:163], v[206:209], v[26:29]
	v_mfma_f32_16x16x32_bf16 v[14:17], v[146:149], v[214:217], v[14:17]
	v_mfma_f32_16x16x32_bf16 v[10:13], v[160:163], v[214:217], v[10:13]
	v_mfma_f32_16x16x32_bf16 v[62:65], v[150:153], v[194:197], v[62:65]
	v_mfma_f32_16x16x32_bf16 v[58:61], v[164:167], v[194:197], v[58:61]
	v_mfma_f32_16x16x32_bf16 v[46:49], v[150:153], v[202:205], v[46:49]
	v_mfma_f32_16x16x32_bf16 v[42:45], v[164:167], v[202:205], v[42:45]
	v_mfma_f32_16x16x32_bf16 v[30:33], v[150:153], v[210:213], v[30:33]
	v_mfma_f32_16x16x32_bf16 v[26:29], v[164:167], v[210:213], v[26:29]
	v_mfma_f32_16x16x32_bf16 v[14:17], v[150:153], v[218:221], v[14:17]
	v_mfma_f32_16x16x32_bf16 v[10:13], v[164:167], v[218:221], v[10:13]
	s_setprio 0
	s_setprio 1
	v_mfma_f32_16x16x32_bf16 v[54:57], v[168:171], v[190:193], v[54:57]
	v_mfma_f32_16x16x32_bf16 v[50:53], v[182:185], v[190:193], v[50:53]
	v_mfma_f32_16x16x32_bf16 v[38:41], v[168:171], v[198:201], v[38:41]
	v_mfma_f32_16x16x32_bf16 v[34:37], v[182:185], v[198:201], v[34:37]
	v_mfma_f32_16x16x32_bf16 v[22:25], v[168:171], v[206:209], v[22:25]
	v_mfma_f32_16x16x32_bf16 v[18:21], v[182:185], v[206:209], v[18:21]
	v_mfma_f32_16x16x32_bf16 v[6:9], v[168:171], v[214:217], v[6:9]
	v_mfma_f32_16x16x32_bf16 v[2:5], v[182:185], v[214:217], v[2:5]
	v_mfma_f32_16x16x32_bf16 v[54:57], v[178:181], v[194:197], v[54:57]
	v_mfma_f32_16x16x32_bf16 v[50:53], v[186:189], v[194:197], v[50:53]
	v_mfma_f32_16x16x32_bf16 v[38:41], v[178:181], v[202:205], v[38:41]
	v_mfma_f32_16x16x32_bf16 v[34:37], v[186:189], v[202:205], v[34:37]
	v_mfma_f32_16x16x32_bf16 v[22:25], v[178:181], v[210:213], v[22:25]
	v_mfma_f32_16x16x32_bf16 v[18:21], v[186:189], v[210:213], v[18:21]
	v_mfma_f32_16x16x32_bf16 v[6:9], v[178:181], v[218:221], v[6:9]
	v_mfma_f32_16x16x32_bf16 v[2:5], v[186:189], v[218:221], v[2:5]
	s_setprio 0
	s_add_i32 s61, s61, 2
	s_add_u32 s59, s59, 0x100
	s_addc_u32 s60, s60, 0
	s_cmp_gt_u32 s61, 13
	s_mov_b64 s[38:39], s[40:41]
	s_barrier
	s_cbranch_scc0 .LBB0_1135

.LBB0_1223:
	s_ashr_i32 s27, s26, 31
	s_lshl_b64 s[28:29], s[26:27], 19
	s_add_u32 s28, s3, s28
	s_addc_u32 s29, s14, s29
	s_and_b64 s[30:31], s[4:5], exec
	s_cselect_b32 s27, s29, s37
	s_cselect_b32 s35, s28, s36
	s_ashr_i32 s25, s24, 31
	s_lshl_b64 s[30:31], s[24:25], 19
	s_add_u32 s30, s15, s30
	s_addc_u32 s31, s16, s31
	s_and_b64 s[40:41], s[4:5], exec
	s_cselect_b32 s25, s31, s39
	s_cselect_b32 s56, s30, s38
	s_add_u32 s57, s38, 0x100
	s_addc_u32 s58, s39, 0
	s_mov_b32 s59, -2
	s_waitcnt lgkmcnt(0)
	ds_read_b128 v[146:149], v154
	ds_read_b128 v[158:161], v154 offset:1024
	ds_read_b128 v[162:165], v154 offset:2048
	ds_read_b128 v[166:169], v154 offset:3072
	ds_read_b128 v[170:173], v155
	ds_read_b128 v[178:181], v155 offset:1024
	ds_read_b128 v[182:185], v155 offset:2048
	ds_read_b128 v[186:189], v155 offset:3072
	s_add_u32 s38, s36, 0x100
	s_addc_u32 s39, s37, 0
	s_cmp_eq_u32 s59, 12
	s_cselect_b32 s43, s27, s39
	s_cselect_b32 s42, s35, s38
	s_cselect_b32 s41, s25, s58
	s_cselect_b32 s40, s56, s57
	v_lshl_add_u64 v[150:151], s[36:37], 0, v[138:139]
	s_add_i32 m0, s44, 0xc000
	ds_read_b128 v[190:193], v156
	ds_read_b128 v[194:197], v156 offset:1024
	ds_read_b128 v[198:201], v156 offset:2048
	ds_read_b128 v[202:205], v156 offset:3072
	ds_read_b128 v[206:209], v156 offset:4096
	ds_read_b128 v[210:213], v156 offset:5120
	ds_read_b128 v[214:217], v156 offset:6144
	ds_read_b128 v[218:221], v156 offset:7168
	global_load_lds_dwordx4 v[150:151], off
	v_lshl_add_u64 v[150:151], s[36:37], 0, v[140:141]
	s_add_i32 m0, s44, 0xe000
	s_nop 0
	global_load_lds_dwordx4 v[150:151], off
	s_waitcnt vmcnt(8)
	s_waitcnt lgkmcnt(0)
	s_barrier
	s_setprio 1
	s_waitcnt lgkmcnt(0)
	v_mfma_f32_16x16x32_bf16 v[126:129], v[146:149], v[190:193], 0
	v_mfma_f32_16x16x32_bf16 v[122:125], v[162:165], v[190:193], 0
	v_mfma_f32_16x16x32_bf16 v[110:113], v[146:149], v[198:201], 0
	v_mfma_f32_16x16x32_bf16 v[106:109], v[162:165], v[198:201], 0
	v_mfma_f32_16x16x32_bf16 v[94:97], v[146:149], v[206:209], 0
	v_mfma_f32_16x16x32_bf16 v[90:93], v[162:165], v[206:209], 0
	v_mfma_f32_16x16x32_bf16 v[78:81], v[146:149], v[214:217], 0
	v_mfma_f32_16x16x32_bf16 v[74:77], v[162:165], v[214:217], 0
	v_mfma_f32_16x16x32_bf16 v[126:129], v[158:161], v[194:197], v[126:129]
	v_mfma_f32_16x16x32_bf16 v[122:125], v[166:169], v[194:197], v[122:125]
	v_mfma_f32_16x16x32_bf16 v[110:113], v[158:161], v[202:205], v[110:113]
	v_mfma_f32_16x16x32_bf16 v[106:109], v[166:169], v[202:205], v[106:109]
	v_mfma_f32_16x16x32_bf16 v[94:97], v[158:161], v[210:213], v[94:97]
	v_mfma_f32_16x16x32_bf16 v[90:93], v[166:169], v[210:213], v[90:93]
	v_mfma_f32_16x16x32_bf16 v[78:81], v[158:161], v[218:221], v[78:81]
	v_mfma_f32_16x16x32_bf16 v[74:77], v[166:169], v[218:221], v[74:77]
	s_setprio 0
	s_setprio 1
	v_mfma_f32_16x16x32_bf16 v[118:121], v[170:173], v[190:193], 0
	v_mfma_f32_16x16x32_bf16 v[114:117], v[182:185], v[190:193], 0
	v_mfma_f32_16x16x32_bf16 v[102:105], v[170:173], v[198:201], 0
	v_mfma_f32_16x16x32_bf16 v[98:101], v[182:185], v[198:201], 0
	v_mfma_f32_16x16x32_bf16 v[86:89], v[170:173], v[206:209], 0
	v_mfma_f32_16x16x32_bf16 v[82:85], v[182:185], v[206:209], 0
	v_mfma_f32_16x16x32_bf16 v[70:73], v[170:173], v[214:217], 0
	v_mfma_f32_16x16x32_bf16 v[66:69], v[182:185], v[214:217], 0
	v_mfma_f32_16x16x32_bf16 v[118:121], v[178:181], v[194:197], v[118:121]
	v_mfma_f32_16x16x32_bf16 v[114:117], v[186:189], v[194:197], v[114:117]
	v_mfma_f32_16x16x32_bf16 v[102:105], v[178:181], v[202:205], v[102:105]
	v_mfma_f32_16x16x32_bf16 v[98:101], v[186:189], v[202:205], v[98:101]
	v_mfma_f32_16x16x32_bf16 v[86:89], v[178:181], v[210:213], v[86:89]
	v_mfma_f32_16x16x32_bf16 v[82:85], v[186:189], v[210:213], v[82:85]
	v_mfma_f32_16x16x32_bf16 v[70:73], v[178:181], v[218:221], v[70:73]
	v_mfma_f32_16x16x32_bf16 v[66:69], v[186:189], v[218:221], v[66:69]
	s_setprio 0
	s_barrier
	s_add_i32 s36, s53, s17
	v_lshl_add_u64 v[150:151], s[40:41], 0, v[132:133]
	s_mov_b32 m0, s36
	ds_read_b128 v[190:193], v156 offset:16384
	ds_read_b128 v[194:197], v156 offset:17408
	ds_read_b128 v[198:201], v156 offset:18432
	ds_read_b128 v[202:205], v156 offset:19456
	ds_read_b128 v[206:209], v156 offset:20480
	ds_read_b128 v[210:213], v156 offset:21504
	ds_read_b128 v[214:217], v156 offset:22528
	ds_read_b128 v[218:221], v156 offset:23552
	global_load_lds_dwordx4 v[150:151], off
	s_add_i32 m0, s36, 0x2000
	s_add_u32 s36, s40, 0x40000
	v_lshl_add_u64 v[222:223], s[40:41], 0, v[136:137]
	s_addc_u32 s37, s41, 0
	s_add_i32 s60, s54, s17
	global_load_lds_dwordx4 v[222:223], off
	v_lshl_add_u64 v[224:225], s[36:37], 0, v[132:133]
	s_mov_b32 m0, s60
	v_lshl_add_u64 v[226:227], s[42:43], 0, v[134:135]
	global_load_lds_dwordx4 v[224:225], off
	v_lshl_add_u64 v[224:225], s[36:37], 0, v[136:137]
	s_add_i32 m0, s60, 0x2000
	s_nop 0
	global_load_lds_dwordx4 v[224:225], off
	v_lshl_add_u64 v[224:225], s[42:43], 0, v[130:131]
	s_mov_b32 m0, s44
	s_nop 0
	global_load_lds_dwordx4 v[224:225], off
	s_mov_b32 m0, s45
	s_nop 0
	global_load_lds_dwordx4 v[226:227], off
	s_waitcnt vmcnt(8)
	s_waitcnt lgkmcnt(0)
	s_barrier
	s_setprio 1
	s_waitcnt lgkmcnt(0)
	v_mfma_f32_16x16x32_bf16 v[62:65], v[146:149], v[190:193], 0
	v_mfma_f32_16x16x32_bf16 v[58:61], v[162:165], v[190:193], 0
	v_mfma_f32_16x16x32_bf16 v[46:49], v[146:149], v[198:201], 0
	v_mfma_f32_16x16x32_bf16 v[42:45], v[162:165], v[198:201], 0
	v_mfma_f32_16x16x32_bf16 v[30:33], v[146:149], v[206:209], 0
	v_mfma_f32_16x16x32_bf16 v[26:29], v[162:165], v[206:209], 0
	v_mfma_f32_16x16x32_bf16 v[14:17], v[146:149], v[214:217], 0
	v_mfma_f32_16x16x32_bf16 v[10:13], v[162:165], v[214:217], 0
	v_mfma_f32_16x16x32_bf16 v[62:65], v[158:161], v[194:197], v[62:65]
	v_mfma_f32_16x16x32_bf16 v[58:61], v[166:169], v[194:197], v[58:61]
	v_mfma_f32_16x16x32_bf16 v[46:49], v[158:161], v[202:205], v[46:49]
	v_mfma_f32_16x16x32_bf16 v[42:45], v[166:169], v[202:205], v[42:45]
	v_mfma_f32_16x16x32_bf16 v[30:33], v[158:161], v[210:213], v[30:33]
	v_mfma_f32_16x16x32_bf16 v[26:29], v[166:169], v[210:213], v[26:29]
	v_mfma_f32_16x16x32_bf16 v[14:17], v[158:161], v[218:221], v[14:17]
	v_mfma_f32_16x16x32_bf16 v[10:13], v[166:169], v[218:221], v[10:13]
	s_setprio 0
	s_setprio 1
	v_mfma_f32_16x16x32_bf16 v[54:57], v[170:173], v[190:193], 0
	v_mfma_f32_16x16x32_bf16 v[50:53], v[182:185], v[190:193], 0
	v_mfma_f32_16x16x32_bf16 v[38:41], v[170:173], v[198:201], 0
	v_mfma_f32_16x16x32_bf16 v[34:37], v[182:185], v[198:201], 0
	v_mfma_f32_16x16x32_bf16 v[22:25], v[170:173], v[206:209], 0
	v_mfma_f32_16x16x32_bf16 v[18:21], v[182:185], v[206:209], 0
	v_mfma_f32_16x16x32_bf16 v[6:9], v[170:173], v[214:217], 0
	v_mfma_f32_16x16x32_bf16 v[2:5], v[182:185], v[214:217], 0
	v_mfma_f32_16x16x32_bf16 v[54:57], v[178:181], v[194:197], v[54:57]
	v_mfma_f32_16x16x32_bf16 v[50:53], v[186:189], v[194:197], v[50:53]
	v_mfma_f32_16x16x32_bf16 v[38:41], v[178:181], v[202:205], v[38:41]
	v_mfma_f32_16x16x32_bf16 v[34:37], v[186:189], v[202:205], v[34:37]
	v_mfma_f32_16x16x32_bf16 v[22:25], v[178:181], v[210:213], v[22:25]
	v_mfma_f32_16x16x32_bf16 v[18:21], v[186:189], v[210:213], v[18:21]
	v_mfma_f32_16x16x32_bf16 v[6:9], v[178:181], v[218:221], v[6:9]
	v_mfma_f32_16x16x32_bf16 v[2:5], v[186:189], v[218:221], v[2:5]
	s_setprio 0
	s_barrier
	s_add_i32 s60, 0, 0x18000
	s_add_i32 s61, 0, 0x1c000
	v_add_u32_e32 v166, s60, v152
	v_add_u32_e32 v177, s61, v152
	ds_read_b128 v[146:149], v166
	ds_read_b128 v[158:161], v166 offset:1024
	ds_read_b128 v[162:165], v166 offset:2048
	ds_read_b128 v[166:169], v166 offset:3072
	ds_read_b128 v[170:173], v177
	ds_read_b128 v[178:181], v177 offset:1024
	ds_read_b128 v[182:185], v177 offset:2048
	ds_read_b128 v[186:189], v177 offset:3072
	s_add_u32 s36, s42, 0x40000
	s_addc_u32 s37, s43, 0
	s_mov_b32 m0, s46
	v_lshl_add_u64 v[228:229], s[36:37], 0, v[130:131]
	ds_read_b128 v[190:193], v156 offset:32768
	ds_read_b128 v[194:197], v156 offset:33792
	ds_read_b128 v[198:201], v156 offset:34816
	ds_read_b128 v[202:205], v156 offset:35840
	ds_read_b128 v[206:209], v156 offset:36864
	ds_read_b128 v[210:213], v156 offset:37888
	ds_read_b128 v[214:217], v156 offset:38912
	ds_read_b128 v[218:221], v156 offset:39936
	global_load_lds_dwordx4 v[228:229], off
	v_lshl_add_u64 v[228:229], s[36:37], 0, v[134:135]
	s_mov_b32 m0, s47
	s_nop 0
	global_load_lds_dwordx4 v[228:229], off
	s_waitcnt vmcnt(8)
	s_waitcnt lgkmcnt(0)
	s_barrier
	s_setprio 1
	s_waitcnt lgkmcnt(0)
	v_mfma_f32_16x16x32_bf16 v[126:129], v[146:149], v[190:193], v[126:129]
	v_mfma_f32_16x16x32_bf16 v[122:125], v[162:165], v[190:193], v[122:125]
	v_mfma_f32_16x16x32_bf16 v[110:113], v[146:149], v[198:201], v[110:113]
	v_mfma_f32_16x16x32_bf16 v[106:109], v[162:165], v[198:201], v[106:109]
	v_mfma_f32_16x16x32_bf16 v[94:97], v[146:149], v[206:209], v[94:97]
	v_mfma_f32_16x16x32_bf16 v[90:93], v[162:165], v[206:209], v[90:93]
	v_mfma_f32_16x16x32_bf16 v[78:81], v[146:149], v[214:217], v[78:81]
	v_mfma_f32_16x16x32_bf16 v[74:77], v[162:165], v[214:217], v[74:77]
	v_mfma_f32_16x16x32_bf16 v[126:129], v[158:161], v[194:197], v[126:129]
	v_mfma_f32_16x16x32_bf16 v[122:125], v[166:169], v[194:197], v[122:125]
	v_mfma_f32_16x16x32_bf16 v[110:113], v[158:161], v[202:205], v[110:113]
	v_mfma_f32_16x16x32_bf16 v[106:109], v[166:169], v[202:205], v[106:109]
	v_mfma_f32_16x16x32_bf16 v[94:97], v[158:161], v[210:213], v[94:97]
	v_mfma_f32_16x16x32_bf16 v[90:93], v[166:169], v[210:213], v[90:93]
	v_mfma_f32_16x16x32_bf16 v[78:81], v[158:161], v[218:221], v[78:81]
	v_mfma_f32_16x16x32_bf16 v[74:77], v[166:169], v[218:221], v[74:77]
	s_setprio 0
	s_setprio 1
	v_mfma_f32_16x16x32_bf16 v[118:121], v[170:173], v[190:193], v[118:121]
	v_mfma_f32_16x16x32_bf16 v[114:117], v[182:185], v[190:193], v[114:117]
	v_mfma_f32_16x16x32_bf16 v[102:105], v[170:173], v[198:201], v[102:105]
	v_mfma_f32_16x16x32_bf16 v[98:101], v[182:185], v[198:201], v[98:101]
	v_mfma_f32_16x16x32_bf16 v[86:89], v[170:173], v[206:209], v[86:89]
	v_mfma_f32_16x16x32_bf16 v[82:85], v[182:185], v[206:209], v[82:85]
	v_mfma_f32_16x16x32_bf16 v[70:73], v[170:173], v[214:217], v[70:73]
	v_mfma_f32_16x16x32_bf16 v[66:69], v[182:185], v[214:217], v[66:69]
	v_mfma_f32_16x16x32_bf16 v[118:121], v[178:181], v[194:197], v[118:121]
	v_mfma_f32_16x16x32_bf16 v[114:117], v[186:189], v[194:197], v[114:117]
	v_mfma_f32_16x16x32_bf16 v[102:105], v[178:181], v[202:205], v[102:105]
	v_mfma_f32_16x16x32_bf16 v[98:101], v[186:189], v[202:205], v[98:101]
	v_mfma_f32_16x16x32_bf16 v[86:89], v[178:181], v[210:213], v[86:89]
	v_mfma_f32_16x16x32_bf16 v[82:85], v[186:189], v[210:213], v[82:85]
	v_mfma_f32_16x16x32_bf16 v[70:73], v[178:181], v[218:221], v[70:73]
	v_mfma_f32_16x16x32_bf16 v[66:69], v[186:189], v[218:221], v[66:69]
	s_setprio 0
	s_barrier
	s_add_i32 s36, s60, s17
	v_lshl_add_u64 v[150:151], v[150:151], 0, s[20:21]
	s_mov_b32 m0, s36
	ds_read_b128 v[190:193], v156 offset:49152
	ds_read_b128 v[194:197], v156 offset:50176
	ds_read_b128 v[198:201], v156 offset:51200
	ds_read_b128 v[202:205], v156 offset:52224
	ds_read_b128 v[206:209], v156 offset:53248
	ds_read_b128 v[210:213], v156 offset:54272
	ds_read_b128 v[214:217], v156 offset:55296
	ds_read_b128 v[218:221], v156 offset:56320
	global_load_lds_dwordx4 v[150:151], off
	s_add_i32 m0, s36, 0x2000
	s_add_u32 s36, s40, 0x40080
	v_lshl_add_u64 v[150:151], v[222:223], 0, s[20:21]
	s_addc_u32 s37, s41, 0
	s_add_i32 s40, s61, s17
	global_load_lds_dwordx4 v[150:151], off
	v_lshl_add_u64 v[150:151], s[36:37], 0, v[132:133]
	s_mov_b32 m0, s40
	s_nop 0
	global_load_lds_dwordx4 v[150:151], off
	v_lshl_add_u64 v[150:151], s[36:37], 0, v[136:137]
	s_add_i32 m0, s40, 0x2000
	s_nop 0
	global_load_lds_dwordx4 v[150:151], off
	v_lshl_add_u64 v[150:151], v[224:225], 0, s[20:21]
	s_mov_b32 m0, s49
	s_nop 0
	global_load_lds_dwordx4 v[150:151], off
	v_lshl_add_u64 v[150:151], v[226:227], 0, s[20:21]
	s_mov_b32 m0, s50
	s_nop 0
	global_load_lds_dwordx4 v[150:151], off
	s_waitcnt vmcnt(8)
	s_waitcnt lgkmcnt(0)
	s_barrier
	s_setprio 1
	s_waitcnt lgkmcnt(0)
	v_mfma_f32_16x16x32_bf16 v[62:65], v[146:149], v[190:193], v[62:65]
	v_mfma_f32_16x16x32_bf16 v[58:61], v[162:165], v[190:193], v[58:61]
	v_mfma_f32_16x16x32_bf16 v[46:49], v[146:149], v[198:201], v[46:49]
	v_mfma_f32_16x16x32_bf16 v[42:45], v[162:165], v[198:201], v[42:45]
	v_mfma_f32_16x16x32_bf16 v[30:33], v[146:149], v[206:209], v[30:33]
	v_mfma_f32_16x16x32_bf16 v[26:29], v[162:165], v[206:209], v[26:29]
	v_mfma_f32_16x16x32_bf16 v[14:17], v[146:149], v[214:217], v[14:17]
	v_mfma_f32_16x16x32_bf16 v[10:13], v[162:165], v[214:217], v[10:13]
	v_mfma_f32_16x16x32_bf16 v[62:65], v[158:161], v[194:197], v[62:65]
	v_mfma_f32_16x16x32_bf16 v[58:61], v[166:169], v[194:197], v[58:61]
	v_mfma_f32_16x16x32_bf16 v[46:49], v[158:161], v[202:205], v[46:49]
	v_mfma_f32_16x16x32_bf16 v[42:45], v[166:169], v[202:205], v[42:45]
	v_mfma_f32_16x16x32_bf16 v[30:33], v[158:161], v[210:213], v[30:33]
	v_mfma_f32_16x16x32_bf16 v[26:29], v[166:169], v[210:213], v[26:29]
	v_mfma_f32_16x16x32_bf16 v[14:17], v[158:161], v[218:221], v[14:17]
	v_mfma_f32_16x16x32_bf16 v[10:13], v[166:169], v[218:221], v[10:13]
	s_setprio 0
	s_setprio 1
	v_mfma_f32_16x16x32_bf16 v[54:57], v[170:173], v[190:193], v[54:57]
	v_mfma_f32_16x16x32_bf16 v[50:53], v[182:185], v[190:193], v[50:53]
	v_mfma_f32_16x16x32_bf16 v[38:41], v[170:173], v[198:201], v[38:41]
	v_mfma_f32_16x16x32_bf16 v[34:37], v[182:185], v[198:201], v[34:37]
	v_mfma_f32_16x16x32_bf16 v[22:25], v[170:173], v[206:209], v[22:25]
	v_mfma_f32_16x16x32_bf16 v[18:21], v[182:185], v[206:209], v[18:21]
	v_mfma_f32_16x16x32_bf16 v[6:9], v[170:173], v[214:217], v[6:9]
	v_mfma_f32_16x16x32_bf16 v[2:5], v[182:185], v[214:217], v[2:5]
	v_mfma_f32_16x16x32_bf16 v[54:57], v[178:181], v[194:197], v[54:57]
	v_mfma_f32_16x16x32_bf16 v[50:53], v[186:189], v[194:197], v[50:53]
	v_mfma_f32_16x16x32_bf16 v[38:41], v[178:181], v[202:205], v[38:41]
	v_mfma_f32_16x16x32_bf16 v[34:37], v[186:189], v[202:205], v[34:37]
	v_mfma_f32_16x16x32_bf16 v[22:25], v[178:181], v[210:213], v[22:25]
	v_mfma_f32_16x16x32_bf16 v[18:21], v[186:189], v[210:213], v[18:21]
	v_mfma_f32_16x16x32_bf16 v[6:9], v[178:181], v[218:221], v[6:9]
	v_mfma_f32_16x16x32_bf16 v[2:5], v[186:189], v[218:221], v[2:5]
	s_setprio 0
	s_add_i32 s59, s59, 2
	s_add_u32 s57, s57, 0x100
	s_addc_u32 s58, s58, 0
	s_cmp_gt_u32 s59, 13
	s_mov_b64 s[36:37], s[38:39]
	s_barrier
	s_cbranch_scc0 .LBB0_1224
	s_branch .Lpeel_exit_1224
.LBB0_1224:
	ds_read_b128 v[146:149], v154
	ds_read_b128 v[158:161], v154 offset:1024
	ds_read_b128 v[162:165], v154 offset:2048
	ds_read_b128 v[166:169], v154 offset:3072
	ds_read_b128 v[170:173], v155
	ds_read_b128 v[178:181], v155 offset:1024
	ds_read_b128 v[182:185], v155 offset:2048
	ds_read_b128 v[186:189], v155 offset:3072
	s_add_u32 s38, s36, 0x100
	s_addc_u32 s39, s37, 0
	s_cmp_eq_u32 s59, 12
	s_cselect_b32 s43, s27, s39
	s_cselect_b32 s42, s35, s38
	s_cselect_b32 s41, s25, s58
	s_cselect_b32 s40, s56, s57
	v_lshl_add_u64 v[150:151], s[36:37], 0, v[138:139]
	s_add_i32 m0, s44, 0xc000
	ds_read_b128 v[190:193], v156
	ds_read_b128 v[194:197], v156 offset:1024
	ds_read_b128 v[198:201], v156 offset:2048
	ds_read_b128 v[202:205], v156 offset:3072
	ds_read_b128 v[206:209], v156 offset:4096
	ds_read_b128 v[210:213], v156 offset:5120
	ds_read_b128 v[214:217], v156 offset:6144
	ds_read_b128 v[218:221], v156 offset:7168
	global_load_lds_dwordx4 v[150:151], off
	v_lshl_add_u64 v[150:151], s[36:37], 0, v[140:141]
	s_add_i32 m0, s44, 0xe000
	s_nop 0
	global_load_lds_dwordx4 v[150:151], off
	s_waitcnt vmcnt(8)
	s_waitcnt lgkmcnt(0)
	s_barrier
	s_setprio 1
	s_waitcnt lgkmcnt(0)
	v_mfma_f32_16x16x32_bf16 v[126:129], v[146:149], v[190:193], v[126:129]
	v_mfma_f32_16x16x32_bf16 v[122:125], v[162:165], v[190:193], v[122:125]
	v_mfma_f32_16x16x32_bf16 v[110:113], v[146:149], v[198:201], v[110:113]
	v_mfma_f32_16x16x32_bf16 v[106:109], v[162:165], v[198:201], v[106:109]
	v_mfma_f32_16x16x32_bf16 v[94:97], v[146:149], v[206:209], v[94:97]
	v_mfma_f32_16x16x32_bf16 v[90:93], v[162:165], v[206:209], v[90:93]
	v_mfma_f32_16x16x32_bf16 v[78:81], v[146:149], v[214:217], v[78:81]
	v_mfma_f32_16x16x32_bf16 v[74:77], v[162:165], v[214:217], v[74:77]
	v_mfma_f32_16x16x32_bf16 v[126:129], v[158:161], v[194:197], v[126:129]
	v_mfma_f32_16x16x32_bf16 v[122:125], v[166:169], v[194:197], v[122:125]
	v_mfma_f32_16x16x32_bf16 v[110:113], v[158:161], v[202:205], v[110:113]
	v_mfma_f32_16x16x32_bf16 v[106:109], v[166:169], v[202:205], v[106:109]
	v_mfma_f32_16x16x32_bf16 v[94:97], v[158:161], v[210:213], v[94:97]
	v_mfma_f32_16x16x32_bf16 v[90:93], v[166:169], v[210:213], v[90:93]
	v_mfma_f32_16x16x32_bf16 v[78:81], v[158:161], v[218:221], v[78:81]
	v_mfma_f32_16x16x32_bf16 v[74:77], v[166:169], v[218:221], v[74:77]
	s_setprio 0
	s_setprio 1
	v_mfma_f32_16x16x32_bf16 v[118:121], v[170:173], v[190:193], v[118:121]
	v_mfma_f32_16x16x32_bf16 v[114:117], v[182:185], v[190:193], v[114:117]
	v_mfma_f32_16x16x32_bf16 v[102:105], v[170:173], v[198:201], v[102:105]
	v_mfma_f32_16x16x32_bf16 v[98:101], v[182:185], v[198:201], v[98:101]
	v_mfma_f32_16x16x32_bf16 v[86:89], v[170:173], v[206:209], v[86:89]
	v_mfma_f32_16x16x32_bf16 v[82:85], v[182:185], v[206:209], v[82:85]
	v_mfma_f32_16x16x32_bf16 v[70:73], v[170:173], v[214:217], v[70:73]
	v_mfma_f32_16x16x32_bf16 v[66:69], v[182:185], v[214:217], v[66:69]
	v_mfma_f32_16x16x32_bf16 v[118:121], v[178:181], v[194:197], v[118:121]
	v_mfma_f32_16x16x32_bf16 v[114:117], v[186:189], v[194:197], v[114:117]
	v_mfma_f32_16x16x32_bf16 v[102:105], v[178:181], v[202:205], v[102:105]
	v_mfma_f32_16x16x32_bf16 v[98:101], v[186:189], v[202:205], v[98:101]
	v_mfma_f32_16x16x32_bf16 v[86:89], v[178:181], v[210:213], v[86:89]
	v_mfma_f32_16x16x32_bf16 v[82:85], v[186:189], v[210:213], v[82:85]
	v_mfma_f32_16x16x32_bf16 v[70:73], v[178:181], v[218:221], v[70:73]
	v_mfma_f32_16x16x32_bf16 v[66:69], v[186:189], v[218:221], v[66:69]
	s_setprio 0
	s_barrier
	s_add_i32 s36, s53, s17
	v_lshl_add_u64 v[150:151], s[40:41], 0, v[132:133]
	s_mov_b32 m0, s36
	ds_read_b128 v[190:193], v156 offset:16384
	ds_read_b128 v[194:197], v156 offset:17408
	ds_read_b128 v[198:201], v156 offset:18432
	ds_read_b128 v[202:205], v156 offset:19456
	ds_read_b128 v[206:209], v156 offset:20480
	ds_read_b128 v[210:213], v156 offset:21504
	ds_read_b128 v[214:217], v156 offset:22528
	ds_read_b128 v[218:221], v156 offset:23552
	global_load_lds_dwordx4 v[150:151], off
	s_add_i32 m0, s36, 0x2000
	s_add_u32 s36, s40, 0x40000
	v_lshl_add_u64 v[222:223], s[40:41], 0, v[136:137]
	s_addc_u32 s37, s41, 0
	s_add_i32 s60, s54, s17
	global_load_lds_dwordx4 v[222:223], off
	v_lshl_add_u64 v[224:225], s[36:37], 0, v[132:133]
	s_mov_b32 m0, s60
	v_lshl_add_u64 v[226:227], s[42:43], 0, v[134:135]
	global_load_lds_dwordx4 v[224:225], off
	v_lshl_add_u64 v[224:225], s[36:37], 0, v[136:137]
	s_add_i32 m0, s60, 0x2000
	s_nop 0
	global_load_lds_dwordx4 v[224:225], off
	v_lshl_add_u64 v[224:225], s[42:43], 0, v[130:131]
	s_mov_b32 m0, s44
	s_nop 0
	global_load_lds_dwordx4 v[224:225], off
	s_mov_b32 m0, s45
	s_nop 0
	global_load_lds_dwordx4 v[226:227], off
	s_waitcnt vmcnt(8)
	s_waitcnt lgkmcnt(0)
	s_barrier
	s_setprio 1
	s_waitcnt lgkmcnt(0)
	v_mfma_f32_16x16x32_bf16 v[62:65], v[146:149], v[190:193], v[62:65]
	v_mfma_f32_16x16x32_bf16 v[58:61], v[162:165], v[190:193], v[58:61]
	v_mfma_f32_16x16x32_bf16 v[46:49], v[146:149], v[198:201], v[46:49]
	v_mfma_f32_16x16x32_bf16 v[42:45], v[162:165], v[198:201], v[42:45]
	v_mfma_f32_16x16x32_bf16 v[30:33], v[146:149], v[206:209], v[30:33]
	v_mfma_f32_16x16x32_bf16 v[26:29], v[162:165], v[206:209], v[26:29]
	v_mfma_f32_16x16x32_bf16 v[14:17], v[146:149], v[214:217], v[14:17]
	v_mfma_f32_16x16x32_bf16 v[10:13], v[162:165], v[214:217], v[10:13]
	v_mfma_f32_16x16x32_bf16 v[62:65], v[158:161], v[194:197], v[62:65]
	v_mfma_f32_16x16x32_bf16 v[58:61], v[166:169], v[194:197], v[58:61]
	v_mfma_f32_16x16x32_bf16 v[46:49], v[158:161], v[202:205], v[46:49]
	v_mfma_f32_16x16x32_bf16 v[42:45], v[166:169], v[202:205], v[42:45]
	v_mfma_f32_16x16x32_bf16 v[30:33], v[158:161], v[210:213], v[30:33]
	v_mfma_f32_16x16x32_bf16 v[26:29], v[166:169], v[210:213], v[26:29]
	v_mfma_f32_16x16x32_bf16 v[14:17], v[158:161], v[218:221], v[14:17]
	v_mfma_f32_16x16x32_bf16 v[10:13], v[166:169], v[218:221], v[10:13]
	s_setprio 0
	s_setprio 1
	v_mfma_f32_16x16x32_bf16 v[54:57], v[170:173], v[190:193], v[54:57]
	v_mfma_f32_16x16x32_bf16 v[50:53], v[182:185], v[190:193], v[50:53]
	v_mfma_f32_16x16x32_bf16 v[38:41], v[170:173], v[198:201], v[38:41]
	v_mfma_f32_16x16x32_bf16 v[34:37], v[182:185], v[198:201], v[34:37]
	v_mfma_f32_16x16x32_bf16 v[22:25], v[170:173], v[206:209], v[22:25]
	v_mfma_f32_16x16x32_bf16 v[18:21], v[182:185], v[206:209], v[18:21]
	v_mfma_f32_16x16x32_bf16 v[6:9], v[170:173], v[214:217], v[6:9]
	v_mfma_f32_16x16x32_bf16 v[2:5], v[182:185], v[214:217], v[2:5]
	v_mfma_f32_16x16x32_bf16 v[54:57], v[178:181], v[194:197], v[54:57]
	v_mfma_f32_16x16x32_bf16 v[50:53], v[186:189], v[194:197], v[50:53]
	v_mfma_f32_16x16x32_bf16 v[38:41], v[178:181], v[202:205], v[38:41]
	v_mfma_f32_16x16x32_bf16 v[34:37], v[186:189], v[202:205], v[34:37]
	v_mfma_f32_16x16x32_bf16 v[22:25], v[178:181], v[210:213], v[22:25]
	v_mfma_f32_16x16x32_bf16 v[18:21], v[186:189], v[210:213], v[18:21]
	v_mfma_f32_16x16x32_bf16 v[6:9], v[178:181], v[218:221], v[6:9]
	v_mfma_f32_16x16x32_bf16 v[2:5], v[186:189], v[218:221], v[2:5]
	s_setprio 0
	s_barrier
	s_add_i32 s60, 0, 0x18000
	s_add_i32 s61, 0, 0x1c000
	v_add_u32_e32 v166, s60, v152
	v_add_u32_e32 v177, s61, v152
	ds_read_b128 v[146:149], v166
	ds_read_b128 v[158:161], v166 offset:1024
	ds_read_b128 v[162:165], v166 offset:2048
	ds_read_b128 v[166:169], v166 offset:3072
	ds_read_b128 v[170:173], v177
	ds_read_b128 v[178:181], v177 offset:1024
	ds_read_b128 v[182:185], v177 offset:2048
	ds_read_b128 v[186:189], v177 offset:3072
	s_add_u32 s36, s42, 0x40000
	s_addc_u32 s37, s43, 0
	s_mov_b32 m0, s46
	v_lshl_add_u64 v[228:229], s[36:37], 0, v[130:131]
	ds_read_b128 v[190:193], v156 offset:32768
	ds_read_b128 v[194:197], v156 offset:33792
	ds_read_b128 v[198:201], v156 offset:34816
	ds_read_b128 v[202:205], v156 offset:35840
	ds_read_b128 v[206:209], v156 offset:36864
	ds_read_b128 v[210:213], v156 offset:37888
	ds_read_b128 v[214:217], v156 offset:38912
	ds_read_b128 v[218:221], v156 offset:39936
	global_load_lds_dwordx4 v[228:229], off
	v_lshl_add_u64 v[228:229], s[36:37], 0, v[134:135]
	s_mov_b32 m0, s47
	s_nop 0
	global_load_lds_dwordx4 v[228:229], off
	s_waitcnt vmcnt(8)
	s_waitcnt lgkmcnt(0)
	s_barrier
	s_setprio 1
	s_waitcnt lgkmcnt(0)
	v_mfma_f32_16x16x32_bf16 v[126:129], v[146:149], v[190:193], v[126:129]
	v_mfma_f32_16x16x32_bf16 v[122:125], v[162:165], v[190:193], v[122:125]
	v_mfma_f32_16x16x32_bf16 v[110:113], v[146:149], v[198:201], v[110:113]
	v_mfma_f32_16x16x32_bf16 v[106:109], v[162:165], v[198:201], v[106:109]
	v_mfma_f32_16x16x32_bf16 v[94:97], v[146:149], v[206:209], v[94:97]
	v_mfma_f32_16x16x32_bf16 v[90:93], v[162:165], v[206:209], v[90:93]
	v_mfma_f32_16x16x32_bf16 v[78:81], v[146:149], v[214:217], v[78:81]
	v_mfma_f32_16x16x32_bf16 v[74:77], v[162:165], v[214:217], v[74:77]
	v_mfma_f32_16x16x32_bf16 v[126:129], v[158:161], v[194:197], v[126:129]
	v_mfma_f32_16x16x32_bf16 v[122:125], v[166:169], v[194:197], v[122:125]
	v_mfma_f32_16x16x32_bf16 v[110:113], v[158:161], v[202:205], v[110:113]
	v_mfma_f32_16x16x32_bf16 v[106:109], v[166:169], v[202:205], v[106:109]
	v_mfma_f32_16x16x32_bf16 v[94:97], v[158:161], v[210:213], v[94:97]
	v_mfma_f32_16x16x32_bf16 v[90:93], v[166:169], v[210:213], v[90:93]
	v_mfma_f32_16x16x32_bf16 v[78:81], v[158:161], v[218:221], v[78:81]
	v_mfma_f32_16x16x32_bf16 v[74:77], v[166:169], v[218:221], v[74:77]
	s_setprio 0
	s_setprio 1
	v_mfma_f32_16x16x32_bf16 v[118:121], v[170:173], v[190:193], v[118:121]
	v_mfma_f32_16x16x32_bf16 v[114:117], v[182:185], v[190:193], v[114:117]
	v_mfma_f32_16x16x32_bf16 v[102:105], v[170:173], v[198:201], v[102:105]
	v_mfma_f32_16x16x32_bf16 v[98:101], v[182:185], v[198:201], v[98:101]
	v_mfma_f32_16x16x32_bf16 v[86:89], v[170:173], v[206:209], v[86:89]
	v_mfma_f32_16x16x32_bf16 v[82:85], v[182:185], v[206:209], v[82:85]
	v_mfma_f32_16x16x32_bf16 v[70:73], v[170:173], v[214:217], v[70:73]
	v_mfma_f32_16x16x32_bf16 v[66:69], v[182:185], v[214:217], v[66:69]
	v_mfma_f32_16x16x32_bf16 v[118:121], v[178:181], v[194:197], v[118:121]
	v_mfma_f32_16x16x32_bf16 v[114:117], v[186:189], v[194:197], v[114:117]
	v_mfma_f32_16x16x32_bf16 v[102:105], v[178:181], v[202:205], v[102:105]
	v_mfma_f32_16x16x32_bf16 v[98:101], v[186:189], v[202:205], v[98:101]
	v_mfma_f32_16x16x32_bf16 v[86:89], v[178:181], v[210:213], v[86:89]
	v_mfma_f32_16x16x32_bf16 v[82:85], v[186:189], v[210:213], v[82:85]
	v_mfma_f32_16x16x32_bf16 v[70:73], v[178:181], v[218:221], v[70:73]
	v_mfma_f32_16x16x32_bf16 v[66:69], v[186:189], v[218:221], v[66:69]
	s_setprio 0
	s_barrier
	s_add_i32 s36, s60, s17
	v_lshl_add_u64 v[150:151], v[150:151], 0, s[20:21]
	s_mov_b32 m0, s36
	ds_read_b128 v[190:193], v156 offset:49152
	ds_read_b128 v[194:197], v156 offset:50176
	ds_read_b128 v[198:201], v156 offset:51200
	ds_read_b128 v[202:205], v156 offset:52224
	ds_read_b128 v[206:209], v156 offset:53248
	ds_read_b128 v[210:213], v156 offset:54272
	ds_read_b128 v[214:217], v156 offset:55296
	ds_read_b128 v[218:221], v156 offset:56320
	global_load_lds_dwordx4 v[150:151], off
	s_add_i32 m0, s36, 0x2000
	s_add_u32 s36, s40, 0x40080
	v_lshl_add_u64 v[150:151], v[222:223], 0, s[20:21]
	s_addc_u32 s37, s41, 0
	s_add_i32 s40, s61, s17
	global_load_lds_dwordx4 v[150:151], off
	v_lshl_add_u64 v[150:151], s[36:37], 0, v[132:133]
	s_mov_b32 m0, s40
	s_nop 0
	global_load_lds_dwordx4 v[150:151], off
	v_lshl_add_u64 v[150:151], s[36:37], 0, v[136:137]
	s_add_i32 m0, s40, 0x2000
	s_nop 0
	global_load_lds_dwordx4 v[150:151], off
	v_lshl_add_u64 v[150:151], v[224:225], 0, s[20:21]
	s_mov_b32 m0, s49
	s_nop 0
	global_load_lds_dwordx4 v[150:151], off
	v_lshl_add_u64 v[150:151], v[226:227], 0, s[20:21]
	s_mov_b32 m0, s50
	s_nop 0
	global_load_lds_dwordx4 v[150:151], off
	s_waitcnt vmcnt(8)
	s_waitcnt lgkmcnt(0)
	s_barrier
	s_setprio 1
	s_waitcnt lgkmcnt(0)
	v_mfma_f32_16x16x32_bf16 v[62:65], v[146:149], v[190:193], v[62:65]
	v_mfma_f32_16x16x32_bf16 v[58:61], v[162:165], v[190:193], v[58:61]
	v_mfma_f32_16x16x32_bf16 v[46:49], v[146:149], v[198:201], v[46:49]
	v_mfma_f32_16x16x32_bf16 v[42:45], v[162:165], v[198:201], v[42:45]
	v_mfma_f32_16x16x32_bf16 v[30:33], v[146:149], v[206:209], v[30:33]
	v_mfma_f32_16x16x32_bf16 v[26:29], v[162:165], v[206:209], v[26:29]
	v_mfma_f32_16x16x32_bf16 v[14:17], v[146:149], v[214:217], v[14:17]
	v_mfma_f32_16x16x32_bf16 v[10:13], v[162:165], v[214:217], v[10:13]
	v_mfma_f32_16x16x32_bf16 v[62:65], v[158:161], v[194:197], v[62:65]
	v_mfma_f32_16x16x32_bf16 v[58:61], v[166:169], v[194:197], v[58:61]
	v_mfma_f32_16x16x32_bf16 v[46:49], v[158:161], v[202:205], v[46:49]
	v_mfma_f32_16x16x32_bf16 v[42:45], v[166:169], v[202:205], v[42:45]
	v_mfma_f32_16x16x32_bf16 v[30:33], v[158:161], v[210:213], v[30:33]
	v_mfma_f32_16x16x32_bf16 v[26:29], v[166:169], v[210:213], v[26:29]
	v_mfma_f32_16x16x32_bf16 v[14:17], v[158:161], v[218:221], v[14:17]
	v_mfma_f32_16x16x32_bf16 v[10:13], v[166:169], v[218:221], v[10:13]
	s_setprio 0
	s_setprio 1
	v_mfma_f32_16x16x32_bf16 v[54:57], v[170:173], v[190:193], v[54:57]
	v_mfma_f32_16x16x32_bf16 v[50:53], v[182:185], v[190:193], v[50:53]
	v_mfma_f32_16x16x32_bf16 v[38:41], v[170:173], v[198:201], v[38:41]
	v_mfma_f32_16x16x32_bf16 v[34:37], v[182:185], v[198:201], v[34:37]
	v_mfma_f32_16x16x32_bf16 v[22:25], v[170:173], v[206:209], v[22:25]
	v_mfma_f32_16x16x32_bf16 v[18:21], v[182:185], v[206:209], v[18:21]
	v_mfma_f32_16x16x32_bf16 v[6:9], v[170:173], v[214:217], v[6:9]
	v_mfma_f32_16x16x32_bf16 v[2:5], v[182:185], v[214:217], v[2:5]
	v_mfma_f32_16x16x32_bf16 v[54:57], v[178:181], v[194:197], v[54:57]
	v_mfma_f32_16x16x32_bf16 v[50:53], v[186:189], v[194:197], v[50:53]
	v_mfma_f32_16x16x32_bf16 v[38:41], v[178:181], v[202:205], v[38:41]
	v_mfma_f32_16x16x32_bf16 v[34:37], v[186:189], v[202:205], v[34:37]
	v_mfma_f32_16x16x32_bf16 v[22:25], v[178:181], v[210:213], v[22:25]
	v_mfma_f32_16x16x32_bf16 v[18:21], v[186:189], v[210:213], v[18:21]
	v_mfma_f32_16x16x32_bf16 v[6:9], v[178:181], v[218:221], v[6:9]
	v_mfma_f32_16x16x32_bf16 v[2:5], v[186:189], v[218:221], v[2:5]
	s_setprio 0
	s_add_i32 s59, s59, 2
	s_add_u32 s57, s57, 0x100
	s_addc_u32 s58, s58, 0
	s_cmp_gt_u32 s59, 13
	s_mov_b64 s[36:37], s[38:39]
	s_barrier
	s_cbranch_scc0 .LBB0_1224

.LBB0_1322:
	s_ashr_i32 s23, s22, 31
	s_lshl_b64 s[24:25], s[22:23], 19
	s_add_u32 s24, s3, s24
	s_addc_u32 s25, s14, s25
	s_and_b64 s[26:27], s[0:1], exec
	s_cselect_b32 s23, s25, s29
	s_cselect_b32 s50, s24, s28
	s_ashr_i32 s21, s20, 31
	s_lshl_b64 s[26:27], s[20:21], 19
	s_add_u32 s26, s15, s26
	s_addc_u32 s27, s16, s27
	s_and_b64 s[34:35], s[0:1], exec
	s_cselect_b32 s21, s27, s31
	s_cselect_b32 s51, s26, s30
	s_add_u32 s52, s30, 0x100
	s_addc_u32 s53, s31, 0
	s_mov_b32 s54, -2
	ds_read_b128 v[148:151], v154
	ds_read_b128 v[160:163], v154 offset:1024
	ds_read_b128 v[164:167], v154 offset:2048
	ds_read_b128 v[168:171], v154 offset:3072
	ds_read_b128 v[178:181], v155
	ds_read_b128 v[182:185], v155 offset:1024
	ds_read_b128 v[186:189], v155 offset:2048
	ds_read_b128 v[190:193], v155 offset:3072
	s_add_u32 s30, s28, 0x100
	s_addc_u32 s31, s29, 0
	s_cmp_eq_u32 s54, 12
	s_cselect_b32 s37, s23, s31
	s_cselect_b32 s36, s50, s30
	s_cselect_b32 s35, s21, s53
	s_cselect_b32 s34, s51, s52
	v_lshl_add_u64 v[172:173], s[28:29], 0, v[140:141]
	s_add_i32 m0, s39, 0xc000
	ds_read_b128 v[194:197], v156
	ds_read_b128 v[198:201], v156 offset:1024
	ds_read_b128 v[202:205], v156 offset:2048
	ds_read_b128 v[206:209], v156 offset:3072
	ds_read_b128 v[210:213], v156 offset:4096
	ds_read_b128 v[214:217], v156 offset:5120
	ds_read_b128 v[218:221], v156 offset:6144
	ds_read_b128 v[222:225], v156 offset:7168
	global_load_lds_dwordx4 v[172:173], off
	v_lshl_add_u64 v[172:173], s[28:29], 0, v[142:143]
	s_add_i32 m0, s39, 0xe000
	s_nop 0
	global_load_lds_dwordx4 v[172:173], off
	s_waitcnt vmcnt(8)
	s_waitcnt lgkmcnt(0)
	s_barrier
	s_setprio 1
	s_waitcnt lgkmcnt(0)
	v_mfma_f32_16x16x32_bf16 v[126:129], v[148:151], v[194:197], 0
	v_mfma_f32_16x16x32_bf16 v[122:125], v[164:167], v[194:197], 0
	v_mfma_f32_16x16x32_bf16 v[110:113], v[148:151], v[202:205], 0
	v_mfma_f32_16x16x32_bf16 v[106:109], v[164:167], v[202:205], 0
	v_mfma_f32_16x16x32_bf16 v[94:97], v[148:151], v[210:213], 0
	v_mfma_f32_16x16x32_bf16 v[90:93], v[164:167], v[210:213], 0
	v_mfma_f32_16x16x32_bf16 v[78:81], v[148:151], v[218:221], 0
	v_mfma_f32_16x16x32_bf16 v[74:77], v[164:167], v[218:221], 0
	v_mfma_f32_16x16x32_bf16 v[126:129], v[160:163], v[198:201], v[126:129]
	v_mfma_f32_16x16x32_bf16 v[122:125], v[168:171], v[198:201], v[122:125]
	v_mfma_f32_16x16x32_bf16 v[110:113], v[160:163], v[206:209], v[110:113]
	v_mfma_f32_16x16x32_bf16 v[106:109], v[168:171], v[206:209], v[106:109]
	v_mfma_f32_16x16x32_bf16 v[94:97], v[160:163], v[214:217], v[94:97]
	v_mfma_f32_16x16x32_bf16 v[90:93], v[168:171], v[214:217], v[90:93]
	v_mfma_f32_16x16x32_bf16 v[78:81], v[160:163], v[222:225], v[78:81]
	v_mfma_f32_16x16x32_bf16 v[74:77], v[168:171], v[222:225], v[74:77]
	s_setprio 0
	s_setprio 1
	v_mfma_f32_16x16x32_bf16 v[118:121], v[178:181], v[194:197], 0
	v_mfma_f32_16x16x32_bf16 v[114:117], v[186:189], v[194:197], 0
	v_mfma_f32_16x16x32_bf16 v[102:105], v[178:181], v[202:205], 0
	v_mfma_f32_16x16x32_bf16 v[98:101], v[186:189], v[202:205], 0
	v_mfma_f32_16x16x32_bf16 v[86:89], v[178:181], v[210:213], 0
	v_mfma_f32_16x16x32_bf16 v[82:85], v[186:189], v[210:213], 0
	v_mfma_f32_16x16x32_bf16 v[70:73], v[178:181], v[218:221], 0
	v_mfma_f32_16x16x32_bf16 v[66:69], v[186:189], v[218:221], 0
	v_mfma_f32_16x16x32_bf16 v[118:121], v[182:185], v[198:201], v[118:121]
	v_mfma_f32_16x16x32_bf16 v[114:117], v[190:193], v[198:201], v[114:117]
	v_mfma_f32_16x16x32_bf16 v[102:105], v[182:185], v[206:209], v[102:105]
	v_mfma_f32_16x16x32_bf16 v[98:101], v[190:193], v[206:209], v[98:101]
	v_mfma_f32_16x16x32_bf16 v[86:89], v[182:185], v[214:217], v[86:89]
	v_mfma_f32_16x16x32_bf16 v[82:85], v[190:193], v[214:217], v[82:85]
	v_mfma_f32_16x16x32_bf16 v[70:73], v[182:185], v[222:225], v[70:73]
	v_mfma_f32_16x16x32_bf16 v[66:69], v[190:193], v[222:225], v[66:69]
	s_setprio 0
	s_barrier
	s_add_i32 s28, s47, s38
	v_lshl_add_u64 v[172:173], s[34:35], 0, v[132:133]
	s_mov_b32 m0, s28
	ds_read_b128 v[194:197], v156 offset:16384
	ds_read_b128 v[198:201], v156 offset:17408
	ds_read_b128 v[202:205], v156 offset:18432
	ds_read_b128 v[206:209], v156 offset:19456
	ds_read_b128 v[210:213], v156 offset:20480
	ds_read_b128 v[214:217], v156 offset:21504
	ds_read_b128 v[218:221], v156 offset:22528
	ds_read_b128 v[222:225], v156 offset:23552
	global_load_lds_dwordx4 v[172:173], off
	s_add_i32 m0, s28, 0x2000
	s_add_u32 s28, s34, 0x40000
	v_lshl_add_u64 v[226:227], s[34:35], 0, v[136:137]
	s_addc_u32 s29, s35, 0
	s_add_i32 s55, s48, s38
	global_load_lds_dwordx4 v[226:227], off
	v_lshl_add_u64 v[228:229], s[28:29], 0, v[132:133]
	s_mov_b32 m0, s55
	v_lshl_add_u64 v[230:231], s[36:37], 0, v[134:135]
	global_load_lds_dwordx4 v[228:229], off
	v_lshl_add_u64 v[228:229], s[28:29], 0, v[136:137]
	s_add_i32 m0, s55, 0x2000
	s_nop 0
	global_load_lds_dwordx4 v[228:229], off
	v_lshl_add_u64 v[228:229], s[36:37], 0, v[130:131]
	s_mov_b32 m0, s39
	s_nop 0
	global_load_lds_dwordx4 v[228:229], off
	s_mov_b32 m0, s40
	s_nop 0
	global_load_lds_dwordx4 v[230:231], off
	s_waitcnt vmcnt(8)
	s_waitcnt lgkmcnt(0)
	s_barrier
	s_setprio 1
	s_waitcnt lgkmcnt(0)
	v_mfma_f32_16x16x32_bf16 v[62:65], v[148:151], v[194:197], 0
	v_mfma_f32_16x16x32_bf16 v[58:61], v[164:167], v[194:197], 0
	v_mfma_f32_16x16x32_bf16 v[46:49], v[148:151], v[202:205], 0
	v_mfma_f32_16x16x32_bf16 v[42:45], v[164:167], v[202:205], 0
	v_mfma_f32_16x16x32_bf16 v[30:33], v[148:151], v[210:213], 0
	v_mfma_f32_16x16x32_bf16 v[26:29], v[164:167], v[210:213], 0
	v_mfma_f32_16x16x32_bf16 v[14:17], v[148:151], v[218:221], 0
	v_mfma_f32_16x16x32_bf16 v[10:13], v[164:167], v[218:221], 0
	v_mfma_f32_16x16x32_bf16 v[62:65], v[160:163], v[198:201], v[62:65]
	v_mfma_f32_16x16x32_bf16 v[58:61], v[168:171], v[198:201], v[58:61]
	v_mfma_f32_16x16x32_bf16 v[46:49], v[160:163], v[206:209], v[46:49]
	v_mfma_f32_16x16x32_bf16 v[42:45], v[168:171], v[206:209], v[42:45]
	v_mfma_f32_16x16x32_bf16 v[30:33], v[160:163], v[214:217], v[30:33]
	v_mfma_f32_16x16x32_bf16 v[26:29], v[168:171], v[214:217], v[26:29]
	v_mfma_f32_16x16x32_bf16 v[14:17], v[160:163], v[222:225], v[14:17]
	v_mfma_f32_16x16x32_bf16 v[10:13], v[168:171], v[222:225], v[10:13]
	s_setprio 0
	s_setprio 1
	v_mfma_f32_16x16x32_bf16 v[54:57], v[178:181], v[194:197], 0
	v_mfma_f32_16x16x32_bf16 v[50:53], v[186:189], v[194:197], 0
	v_mfma_f32_16x16x32_bf16 v[38:41], v[178:181], v[202:205], 0
	v_mfma_f32_16x16x32_bf16 v[34:37], v[186:189], v[202:205], 0
	v_mfma_f32_16x16x32_bf16 v[22:25], v[178:181], v[210:213], 0
	v_mfma_f32_16x16x32_bf16 v[18:21], v[186:189], v[210:213], 0
	v_mfma_f32_16x16x32_bf16 v[6:9], v[178:181], v[218:221], 0
	v_mfma_f32_16x16x32_bf16 v[2:5], v[186:189], v[218:221], 0
	v_mfma_f32_16x16x32_bf16 v[54:57], v[182:185], v[198:201], v[54:57]
	v_mfma_f32_16x16x32_bf16 v[50:53], v[190:193], v[198:201], v[50:53]
	v_mfma_f32_16x16x32_bf16 v[38:41], v[182:185], v[206:209], v[38:41]
	v_mfma_f32_16x16x32_bf16 v[34:37], v[190:193], v[206:209], v[34:37]
	v_mfma_f32_16x16x32_bf16 v[22:25], v[182:185], v[214:217], v[22:25]
	v_mfma_f32_16x16x32_bf16 v[18:21], v[190:193], v[214:217], v[18:21]
	v_mfma_f32_16x16x32_bf16 v[6:9], v[182:185], v[222:225], v[6:9]
	v_mfma_f32_16x16x32_bf16 v[2:5], v[190:193], v[222:225], v[2:5]
	s_setprio 0
	s_barrier
	s_add_i32 s55, 0, 0x18000
	v_add_u32_e32 v138, s55, v152
	s_add_i32 s56, 0, 0x1c000
	ds_read_b128 v[148:151], v138
	ds_read_b128 v[160:163], v138 offset:1024
	ds_read_b128 v[164:167], v138 offset:2048
	ds_read_b128 v[168:171], v138 offset:3072
	v_add_u32_e32 v138, s56, v152
	ds_read_b128 v[178:181], v138
	ds_read_b128 v[182:185], v138 offset:1024
	ds_read_b128 v[186:189], v138 offset:2048
	ds_read_b128 v[190:193], v138 offset:3072
	s_add_u32 s28, s36, 0x40000
	s_addc_u32 s29, s37, 0
	s_mov_b32 m0, s41
	v_lshl_add_u64 v[232:233], s[28:29], 0, v[130:131]
	ds_read_b128 v[194:197], v156 offset:32768
	ds_read_b128 v[198:201], v156 offset:33792
	ds_read_b128 v[202:205], v156 offset:34816
	ds_read_b128 v[206:209], v156 offset:35840
	ds_read_b128 v[210:213], v156 offset:36864
	ds_read_b128 v[214:217], v156 offset:37888
	ds_read_b128 v[218:221], v156 offset:38912
	ds_read_b128 v[222:225], v156 offset:39936
	global_load_lds_dwordx4 v[232:233], off
	v_lshl_add_u64 v[232:233], s[28:29], 0, v[134:135]
	s_mov_b32 m0, s42
	s_nop 0
	global_load_lds_dwordx4 v[232:233], off
	s_waitcnt vmcnt(8)
	s_waitcnt lgkmcnt(0)
	s_barrier
	s_setprio 1
	s_waitcnt lgkmcnt(0)
	v_mfma_f32_16x16x32_bf16 v[126:129], v[148:151], v[194:197], v[126:129]
	v_mfma_f32_16x16x32_bf16 v[122:125], v[164:167], v[194:197], v[122:125]
	v_mfma_f32_16x16x32_bf16 v[110:113], v[148:151], v[202:205], v[110:113]
	v_mfma_f32_16x16x32_bf16 v[106:109], v[164:167], v[202:205], v[106:109]
	v_mfma_f32_16x16x32_bf16 v[94:97], v[148:151], v[210:213], v[94:97]
	v_mfma_f32_16x16x32_bf16 v[90:93], v[164:167], v[210:213], v[90:93]
	v_mfma_f32_16x16x32_bf16 v[78:81], v[148:151], v[218:221], v[78:81]
	v_mfma_f32_16x16x32_bf16 v[74:77], v[164:167], v[218:221], v[74:77]
	v_mfma_f32_16x16x32_bf16 v[126:129], v[160:163], v[198:201], v[126:129]
	v_mfma_f32_16x16x32_bf16 v[122:125], v[168:171], v[198:201], v[122:125]
	v_mfma_f32_16x16x32_bf16 v[110:113], v[160:163], v[206:209], v[110:113]
	v_mfma_f32_16x16x32_bf16 v[106:109], v[168:171], v[206:209], v[106:109]
	v_mfma_f32_16x16x32_bf16 v[94:97], v[160:163], v[214:217], v[94:97]
	v_mfma_f32_16x16x32_bf16 v[90:93], v[168:171], v[214:217], v[90:93]
	v_mfma_f32_16x16x32_bf16 v[78:81], v[160:163], v[222:225], v[78:81]
	v_mfma_f32_16x16x32_bf16 v[74:77], v[168:171], v[222:225], v[74:77]
	s_setprio 0
	s_setprio 1
	v_mfma_f32_16x16x32_bf16 v[118:121], v[178:181], v[194:197], v[118:121]
	v_mfma_f32_16x16x32_bf16 v[114:117], v[186:189], v[194:197], v[114:117]
	v_mfma_f32_16x16x32_bf16 v[102:105], v[178:181], v[202:205], v[102:105]
	v_mfma_f32_16x16x32_bf16 v[98:101], v[186:189], v[202:205], v[98:101]
	v_mfma_f32_16x16x32_bf16 v[86:89], v[178:181], v[210:213], v[86:89]
	v_mfma_f32_16x16x32_bf16 v[82:85], v[186:189], v[210:213], v[82:85]
	v_mfma_f32_16x16x32_bf16 v[70:73], v[178:181], v[218:221], v[70:73]
	v_mfma_f32_16x16x32_bf16 v[66:69], v[186:189], v[218:221], v[66:69]
	v_mfma_f32_16x16x32_bf16 v[118:121], v[182:185], v[198:201], v[118:121]
	v_mfma_f32_16x16x32_bf16 v[114:117], v[190:193], v[198:201], v[114:117]
	v_mfma_f32_16x16x32_bf16 v[102:105], v[182:185], v[206:209], v[102:105]
	v_mfma_f32_16x16x32_bf16 v[98:101], v[190:193], v[206:209], v[98:101]
	v_mfma_f32_16x16x32_bf16 v[86:89], v[182:185], v[214:217], v[86:89]
	v_mfma_f32_16x16x32_bf16 v[82:85], v[190:193], v[214:217], v[82:85]
	v_mfma_f32_16x16x32_bf16 v[70:73], v[182:185], v[222:225], v[70:73]
	v_mfma_f32_16x16x32_bf16 v[66:69], v[190:193], v[222:225], v[66:69]
	s_setprio 0
	s_barrier
	s_add_i32 s28, s55, s38
	v_lshl_add_u64 v[172:173], v[172:173], 0, s[12:13]
	s_mov_b32 m0, s28
	ds_read_b128 v[194:197], v156 offset:49152
	ds_read_b128 v[198:201], v156 offset:50176
	ds_read_b128 v[202:205], v156 offset:51200
	ds_read_b128 v[206:209], v156 offset:52224
	ds_read_b128 v[210:213], v156 offset:53248
	ds_read_b128 v[214:217], v156 offset:54272
	ds_read_b128 v[218:221], v156 offset:55296
	ds_read_b128 v[222:225], v156 offset:56320
	global_load_lds_dwordx4 v[172:173], off
	s_add_i32 m0, s28, 0x2000
	s_add_u32 s28, s34, 0x40080
	v_lshl_add_u64 v[172:173], v[226:227], 0, s[12:13]
	s_addc_u32 s29, s35, 0
	s_add_i32 s34, s56, s38
	global_load_lds_dwordx4 v[172:173], off
	v_lshl_add_u64 v[172:173], s[28:29], 0, v[132:133]
	s_mov_b32 m0, s34
	s_nop 0
	global_load_lds_dwordx4 v[172:173], off
	v_lshl_add_u64 v[172:173], s[28:29], 0, v[136:137]
	s_add_i32 m0, s34, 0x2000
	s_nop 0
	global_load_lds_dwordx4 v[172:173], off
	v_lshl_add_u64 v[172:173], v[228:229], 0, s[12:13]
	s_mov_b32 m0, s44
	s_nop 0
	global_load_lds_dwordx4 v[172:173], off
	v_lshl_add_u64 v[172:173], v[230:231], 0, s[12:13]
	s_mov_b32 m0, s45
	s_nop 0
	global_load_lds_dwordx4 v[172:173], off
	s_waitcnt vmcnt(8)
	s_waitcnt lgkmcnt(0)
	s_barrier
	s_setprio 1
	s_waitcnt lgkmcnt(0)
	v_mfma_f32_16x16x32_bf16 v[62:65], v[148:151], v[194:197], v[62:65]
	v_mfma_f32_16x16x32_bf16 v[58:61], v[164:167], v[194:197], v[58:61]
	v_mfma_f32_16x16x32_bf16 v[46:49], v[148:151], v[202:205], v[46:49]
	v_mfma_f32_16x16x32_bf16 v[42:45], v[164:167], v[202:205], v[42:45]
	v_mfma_f32_16x16x32_bf16 v[30:33], v[148:151], v[210:213], v[30:33]
	v_mfma_f32_16x16x32_bf16 v[26:29], v[164:167], v[210:213], v[26:29]
	v_mfma_f32_16x16x32_bf16 v[14:17], v[148:151], v[218:221], v[14:17]
	v_mfma_f32_16x16x32_bf16 v[10:13], v[164:167], v[218:221], v[10:13]
	v_mfma_f32_16x16x32_bf16 v[62:65], v[160:163], v[198:201], v[62:65]
	v_mfma_f32_16x16x32_bf16 v[58:61], v[168:171], v[198:201], v[58:61]
	v_mfma_f32_16x16x32_bf16 v[46:49], v[160:163], v[206:209], v[46:49]
	v_mfma_f32_16x16x32_bf16 v[42:45], v[168:171], v[206:209], v[42:45]
	v_mfma_f32_16x16x32_bf16 v[30:33], v[160:163], v[214:217], v[30:33]
	v_mfma_f32_16x16x32_bf16 v[26:29], v[168:171], v[214:217], v[26:29]
	v_mfma_f32_16x16x32_bf16 v[14:17], v[160:163], v[222:225], v[14:17]
	v_mfma_f32_16x16x32_bf16 v[10:13], v[168:171], v[222:225], v[10:13]
	s_setprio 0
	s_setprio 1
	v_mfma_f32_16x16x32_bf16 v[54:57], v[178:181], v[194:197], v[54:57]
	v_mfma_f32_16x16x32_bf16 v[50:53], v[186:189], v[194:197], v[50:53]
	v_mfma_f32_16x16x32_bf16 v[38:41], v[178:181], v[202:205], v[38:41]
	v_mfma_f32_16x16x32_bf16 v[34:37], v[186:189], v[202:205], v[34:37]
	v_mfma_f32_16x16x32_bf16 v[22:25], v[178:181], v[210:213], v[22:25]
	v_mfma_f32_16x16x32_bf16 v[18:21], v[186:189], v[210:213], v[18:21]
	v_mfma_f32_16x16x32_bf16 v[6:9], v[178:181], v[218:221], v[6:9]
	v_mfma_f32_16x16x32_bf16 v[2:5], v[186:189], v[218:221], v[2:5]
	v_mfma_f32_16x16x32_bf16 v[54:57], v[182:185], v[198:201], v[54:57]
	v_mfma_f32_16x16x32_bf16 v[50:53], v[190:193], v[198:201], v[50:53]
	v_mfma_f32_16x16x32_bf16 v[38:41], v[182:185], v[206:209], v[38:41]
	v_mfma_f32_16x16x32_bf16 v[34:37], v[190:193], v[206:209], v[34:37]
	v_mfma_f32_16x16x32_bf16 v[22:25], v[182:185], v[214:217], v[22:25]
	v_mfma_f32_16x16x32_bf16 v[18:21], v[190:193], v[214:217], v[18:21]
	v_mfma_f32_16x16x32_bf16 v[6:9], v[182:185], v[222:225], v[6:9]
	v_mfma_f32_16x16x32_bf16 v[2:5], v[190:193], v[222:225], v[2:5]
	s_setprio 0
	s_add_i32 s54, s54, 2
	s_add_u32 s52, s52, 0x100
	s_addc_u32 s53, s53, 0
	s_cmp_gt_u32 s54, 13
	s_mov_b64 s[28:29], s[30:31]
	s_barrier
	s_cbranch_scc0 .LBB0_1323
	s_branch .Lpeel_exit_1323
.LBB0_1323:
	ds_read_b128 v[148:151], v154
	ds_read_b128 v[160:163], v154 offset:1024
	ds_read_b128 v[164:167], v154 offset:2048
	ds_read_b128 v[168:171], v154 offset:3072
	ds_read_b128 v[178:181], v155
	ds_read_b128 v[182:185], v155 offset:1024
	ds_read_b128 v[186:189], v155 offset:2048
	ds_read_b128 v[190:193], v155 offset:3072
	s_add_u32 s30, s28, 0x100
	s_addc_u32 s31, s29, 0
	s_cmp_eq_u32 s54, 12
	s_cselect_b32 s37, s23, s31
	s_cselect_b32 s36, s50, s30
	s_cselect_b32 s35, s21, s53
	s_cselect_b32 s34, s51, s52
	v_lshl_add_u64 v[172:173], s[28:29], 0, v[140:141]
	s_add_i32 m0, s39, 0xc000
	ds_read_b128 v[194:197], v156
	ds_read_b128 v[198:201], v156 offset:1024
	ds_read_b128 v[202:205], v156 offset:2048
	ds_read_b128 v[206:209], v156 offset:3072
	ds_read_b128 v[210:213], v156 offset:4096
	ds_read_b128 v[214:217], v156 offset:5120
	ds_read_b128 v[218:221], v156 offset:6144
	ds_read_b128 v[222:225], v156 offset:7168
	global_load_lds_dwordx4 v[172:173], off
	v_lshl_add_u64 v[172:173], s[28:29], 0, v[142:143]
	s_add_i32 m0, s39, 0xe000
	s_nop 0
	global_load_lds_dwordx4 v[172:173], off
	s_waitcnt vmcnt(8)
	s_waitcnt lgkmcnt(0)
	s_barrier
	s_setprio 1
	s_waitcnt lgkmcnt(0)
	v_mfma_f32_16x16x32_bf16 v[126:129], v[148:151], v[194:197], v[126:129]
	v_mfma_f32_16x16x32_bf16 v[122:125], v[164:167], v[194:197], v[122:125]
	v_mfma_f32_16x16x32_bf16 v[110:113], v[148:151], v[202:205], v[110:113]
	v_mfma_f32_16x16x32_bf16 v[106:109], v[164:167], v[202:205], v[106:109]
	v_mfma_f32_16x16x32_bf16 v[94:97], v[148:151], v[210:213], v[94:97]
	v_mfma_f32_16x16x32_bf16 v[90:93], v[164:167], v[210:213], v[90:93]
	v_mfma_f32_16x16x32_bf16 v[78:81], v[148:151], v[218:221], v[78:81]
	v_mfma_f32_16x16x32_bf16 v[74:77], v[164:167], v[218:221], v[74:77]
	v_mfma_f32_16x16x32_bf16 v[126:129], v[160:163], v[198:201], v[126:129]
	v_mfma_f32_16x16x32_bf16 v[122:125], v[168:171], v[198:201], v[122:125]
	v_mfma_f32_16x16x32_bf16 v[110:113], v[160:163], v[206:209], v[110:113]
	v_mfma_f32_16x16x32_bf16 v[106:109], v[168:171], v[206:209], v[106:109]
	v_mfma_f32_16x16x32_bf16 v[94:97], v[160:163], v[214:217], v[94:97]
	v_mfma_f32_16x16x32_bf16 v[90:93], v[168:171], v[214:217], v[90:93]
	v_mfma_f32_16x16x32_bf16 v[78:81], v[160:163], v[222:225], v[78:81]
	v_mfma_f32_16x16x32_bf16 v[74:77], v[168:171], v[222:225], v[74:77]
	s_setprio 0
	s_setprio 1
	v_mfma_f32_16x16x32_bf16 v[118:121], v[178:181], v[194:197], v[118:121]
	v_mfma_f32_16x16x32_bf16 v[114:117], v[186:189], v[194:197], v[114:117]
	v_mfma_f32_16x16x32_bf16 v[102:105], v[178:181], v[202:205], v[102:105]
	v_mfma_f32_16x16x32_bf16 v[98:101], v[186:189], v[202:205], v[98:101]
	v_mfma_f32_16x16x32_bf16 v[86:89], v[178:181], v[210:213], v[86:89]
	v_mfma_f32_16x16x32_bf16 v[82:85], v[186:189], v[210:213], v[82:85]
	v_mfma_f32_16x16x32_bf16 v[70:73], v[178:181], v[218:221], v[70:73]
	v_mfma_f32_16x16x32_bf16 v[66:69], v[186:189], v[218:221], v[66:69]
	v_mfma_f32_16x16x32_bf16 v[118:121], v[182:185], v[198:201], v[118:121]
	v_mfma_f32_16x16x32_bf16 v[114:117], v[190:193], v[198:201], v[114:117]
	v_mfma_f32_16x16x32_bf16 v[102:105], v[182:185], v[206:209], v[102:105]
	v_mfma_f32_16x16x32_bf16 v[98:101], v[190:193], v[206:209], v[98:101]
	v_mfma_f32_16x16x32_bf16 v[86:89], v[182:185], v[214:217], v[86:89]
	v_mfma_f32_16x16x32_bf16 v[82:85], v[190:193], v[214:217], v[82:85]
	v_mfma_f32_16x16x32_bf16 v[70:73], v[182:185], v[222:225], v[70:73]
	v_mfma_f32_16x16x32_bf16 v[66:69], v[190:193], v[222:225], v[66:69]
	s_setprio 0
	s_barrier
	s_add_i32 s28, s47, s38
	v_lshl_add_u64 v[172:173], s[34:35], 0, v[132:133]
	s_mov_b32 m0, s28
	ds_read_b128 v[194:197], v156 offset:16384
	ds_read_b128 v[198:201], v156 offset:17408
	ds_read_b128 v[202:205], v156 offset:18432
	ds_read_b128 v[206:209], v156 offset:19456
	ds_read_b128 v[210:213], v156 offset:20480
	ds_read_b128 v[214:217], v156 offset:21504
	ds_read_b128 v[218:221], v156 offset:22528
	ds_read_b128 v[222:225], v156 offset:23552
	global_load_lds_dwordx4 v[172:173], off
	s_add_i32 m0, s28, 0x2000
	s_add_u32 s28, s34, 0x40000
	v_lshl_add_u64 v[226:227], s[34:35], 0, v[136:137]
	s_addc_u32 s29, s35, 0
	s_add_i32 s55, s48, s38
	global_load_lds_dwordx4 v[226:227], off
	v_lshl_add_u64 v[228:229], s[28:29], 0, v[132:133]
	s_mov_b32 m0, s55
	v_lshl_add_u64 v[230:231], s[36:37], 0, v[134:135]
	global_load_lds_dwordx4 v[228:229], off
	v_lshl_add_u64 v[228:229], s[28:29], 0, v[136:137]
	s_add_i32 m0, s55, 0x2000
	s_nop 0
	global_load_lds_dwordx4 v[228:229], off
	v_lshl_add_u64 v[228:229], s[36:37], 0, v[130:131]
	s_mov_b32 m0, s39
	s_nop 0
	global_load_lds_dwordx4 v[228:229], off
	s_mov_b32 m0, s40
	s_nop 0
	global_load_lds_dwordx4 v[230:231], off
	s_waitcnt vmcnt(8)
	s_waitcnt lgkmcnt(0)
	s_barrier
	s_setprio 1
	s_waitcnt lgkmcnt(0)
	v_mfma_f32_16x16x32_bf16 v[62:65], v[148:151], v[194:197], v[62:65]
	v_mfma_f32_16x16x32_bf16 v[58:61], v[164:167], v[194:197], v[58:61]
	v_mfma_f32_16x16x32_bf16 v[46:49], v[148:151], v[202:205], v[46:49]
	v_mfma_f32_16x16x32_bf16 v[42:45], v[164:167], v[202:205], v[42:45]
	v_mfma_f32_16x16x32_bf16 v[30:33], v[148:151], v[210:213], v[30:33]
	v_mfma_f32_16x16x32_bf16 v[26:29], v[164:167], v[210:213], v[26:29]
	v_mfma_f32_16x16x32_bf16 v[14:17], v[148:151], v[218:221], v[14:17]
	v_mfma_f32_16x16x32_bf16 v[10:13], v[164:167], v[218:221], v[10:13]
	v_mfma_f32_16x16x32_bf16 v[62:65], v[160:163], v[198:201], v[62:65]
	v_mfma_f32_16x16x32_bf16 v[58:61], v[168:171], v[198:201], v[58:61]
	v_mfma_f32_16x16x32_bf16 v[46:49], v[160:163], v[206:209], v[46:49]
	v_mfma_f32_16x16x32_bf16 v[42:45], v[168:171], v[206:209], v[42:45]
	v_mfma_f32_16x16x32_bf16 v[30:33], v[160:163], v[214:217], v[30:33]
	v_mfma_f32_16x16x32_bf16 v[26:29], v[168:171], v[214:217], v[26:29]
	v_mfma_f32_16x16x32_bf16 v[14:17], v[160:163], v[222:225], v[14:17]
	v_mfma_f32_16x16x32_bf16 v[10:13], v[168:171], v[222:225], v[10:13]
	s_setprio 0
	s_setprio 1
	v_mfma_f32_16x16x32_bf16 v[54:57], v[178:181], v[194:197], v[54:57]
	v_mfma_f32_16x16x32_bf16 v[50:53], v[186:189], v[194:197], v[50:53]
	v_mfma_f32_16x16x32_bf16 v[38:41], v[178:181], v[202:205], v[38:41]
	v_mfma_f32_16x16x32_bf16 v[34:37], v[186:189], v[202:205], v[34:37]
	v_mfma_f32_16x16x32_bf16 v[22:25], v[178:181], v[210:213], v[22:25]
	v_mfma_f32_16x16x32_bf16 v[18:21], v[186:189], v[210:213], v[18:21]
	v_mfma_f32_16x16x32_bf16 v[6:9], v[178:181], v[218:221], v[6:9]
	v_mfma_f32_16x16x32_bf16 v[2:5], v[186:189], v[218:221], v[2:5]
	v_mfma_f32_16x16x32_bf16 v[54:57], v[182:185], v[198:201], v[54:57]
	v_mfma_f32_16x16x32_bf16 v[50:53], v[190:193], v[198:201], v[50:53]
	v_mfma_f32_16x16x32_bf16 v[38:41], v[182:185], v[206:209], v[38:41]
	v_mfma_f32_16x16x32_bf16 v[34:37], v[190:193], v[206:209], v[34:37]
	v_mfma_f32_16x16x32_bf16 v[22:25], v[182:185], v[214:217], v[22:25]
	v_mfma_f32_16x16x32_bf16 v[18:21], v[190:193], v[214:217], v[18:21]
	v_mfma_f32_16x16x32_bf16 v[6:9], v[182:185], v[222:225], v[6:9]
	v_mfma_f32_16x16x32_bf16 v[2:5], v[190:193], v[222:225], v[2:5]
	s_setprio 0
	s_barrier
	s_add_i32 s55, 0, 0x18000
	v_add_u32_e32 v138, s55, v152
	s_add_i32 s56, 0, 0x1c000
	ds_read_b128 v[148:151], v138
	ds_read_b128 v[160:163], v138 offset:1024
	ds_read_b128 v[164:167], v138 offset:2048
	ds_read_b128 v[168:171], v138 offset:3072
	v_add_u32_e32 v138, s56, v152
	ds_read_b128 v[178:181], v138
	ds_read_b128 v[182:185], v138 offset:1024
	ds_read_b128 v[186:189], v138 offset:2048
	ds_read_b128 v[190:193], v138 offset:3072
	s_add_u32 s28, s36, 0x40000
	s_addc_u32 s29, s37, 0
	s_mov_b32 m0, s41
	v_lshl_add_u64 v[232:233], s[28:29], 0, v[130:131]
	ds_read_b128 v[194:197], v156 offset:32768
	ds_read_b128 v[198:201], v156 offset:33792
	ds_read_b128 v[202:205], v156 offset:34816
	ds_read_b128 v[206:209], v156 offset:35840
	ds_read_b128 v[210:213], v156 offset:36864
	ds_read_b128 v[214:217], v156 offset:37888
	ds_read_b128 v[218:221], v156 offset:38912
	ds_read_b128 v[222:225], v156 offset:39936
	global_load_lds_dwordx4 v[232:233], off
	v_lshl_add_u64 v[232:233], s[28:29], 0, v[134:135]
	s_mov_b32 m0, s42
	s_nop 0
	global_load_lds_dwordx4 v[232:233], off
	s_waitcnt vmcnt(8)
	s_waitcnt lgkmcnt(0)
	s_barrier
	s_setprio 1
	s_waitcnt lgkmcnt(0)
	v_mfma_f32_16x16x32_bf16 v[126:129], v[148:151], v[194:197], v[126:129]
	v_mfma_f32_16x16x32_bf16 v[122:125], v[164:167], v[194:197], v[122:125]
	v_mfma_f32_16x16x32_bf16 v[110:113], v[148:151], v[202:205], v[110:113]
	v_mfma_f32_16x16x32_bf16 v[106:109], v[164:167], v[202:205], v[106:109]
	v_mfma_f32_16x16x32_bf16 v[94:97], v[148:151], v[210:213], v[94:97]
	v_mfma_f32_16x16x32_bf16 v[90:93], v[164:167], v[210:213], v[90:93]
	v_mfma_f32_16x16x32_bf16 v[78:81], v[148:151], v[218:221], v[78:81]
	v_mfma_f32_16x16x32_bf16 v[74:77], v[164:167], v[218:221], v[74:77]
	v_mfma_f32_16x16x32_bf16 v[126:129], v[160:163], v[198:201], v[126:129]
	v_mfma_f32_16x16x32_bf16 v[122:125], v[168:171], v[198:201], v[122:125]
	v_mfma_f32_16x16x32_bf16 v[110:113], v[160:163], v[206:209], v[110:113]
	v_mfma_f32_16x16x32_bf16 v[106:109], v[168:171], v[206:209], v[106:109]
	v_mfma_f32_16x16x32_bf16 v[94:97], v[160:163], v[214:217], v[94:97]
	v_mfma_f32_16x16x32_bf16 v[90:93], v[168:171], v[214:217], v[90:93]
	v_mfma_f32_16x16x32_bf16 v[78:81], v[160:163], v[222:225], v[78:81]
	v_mfma_f32_16x16x32_bf16 v[74:77], v[168:171], v[222:225], v[74:77]
	s_setprio 0
	s_setprio 1
	v_mfma_f32_16x16x32_bf16 v[118:121], v[178:181], v[194:197], v[118:121]
	v_mfma_f32_16x16x32_bf16 v[114:117], v[186:189], v[194:197], v[114:117]
	v_mfma_f32_16x16x32_bf16 v[102:105], v[178:181], v[202:205], v[102:105]
	v_mfma_f32_16x16x32_bf16 v[98:101], v[186:189], v[202:205], v[98:101]
	v_mfma_f32_16x16x32_bf16 v[86:89], v[178:181], v[210:213], v[86:89]
	v_mfma_f32_16x16x32_bf16 v[82:85], v[186:189], v[210:213], v[82:85]
	v_mfma_f32_16x16x32_bf16 v[70:73], v[178:181], v[218:221], v[70:73]
	v_mfma_f32_16x16x32_bf16 v[66:69], v[186:189], v[218:221], v[66:69]
	v_mfma_f32_16x16x32_bf16 v[118:121], v[182:185], v[198:201], v[118:121]
	v_mfma_f32_16x16x32_bf16 v[114:117], v[190:193], v[198:201], v[114:117]
	v_mfma_f32_16x16x32_bf16 v[102:105], v[182:185], v[206:209], v[102:105]
	v_mfma_f32_16x16x32_bf16 v[98:101], v[190:193], v[206:209], v[98:101]
	v_mfma_f32_16x16x32_bf16 v[86:89], v[182:185], v[214:217], v[86:89]
	v_mfma_f32_16x16x32_bf16 v[82:85], v[190:193], v[214:217], v[82:85]
	v_mfma_f32_16x16x32_bf16 v[70:73], v[182:185], v[222:225], v[70:73]
	v_mfma_f32_16x16x32_bf16 v[66:69], v[190:193], v[222:225], v[66:69]
	s_setprio 0
	s_barrier
	s_add_i32 s28, s55, s38
	v_lshl_add_u64 v[172:173], v[172:173], 0, s[12:13]
	s_mov_b32 m0, s28
	ds_read_b128 v[194:197], v156 offset:49152
	ds_read_b128 v[198:201], v156 offset:50176
	ds_read_b128 v[202:205], v156 offset:51200
	ds_read_b128 v[206:209], v156 offset:52224
	ds_read_b128 v[210:213], v156 offset:53248
	ds_read_b128 v[214:217], v156 offset:54272
	ds_read_b128 v[218:221], v156 offset:55296
	ds_read_b128 v[222:225], v156 offset:56320
	global_load_lds_dwordx4 v[172:173], off
	s_add_i32 m0, s28, 0x2000
	s_add_u32 s28, s34, 0x40080
	v_lshl_add_u64 v[172:173], v[226:227], 0, s[12:13]
	s_addc_u32 s29, s35, 0
	s_add_i32 s34, s56, s38
	global_load_lds_dwordx4 v[172:173], off
	v_lshl_add_u64 v[172:173], s[28:29], 0, v[132:133]
	s_mov_b32 m0, s34
	s_nop 0
	global_load_lds_dwordx4 v[172:173], off
	v_lshl_add_u64 v[172:173], s[28:29], 0, v[136:137]
	s_add_i32 m0, s34, 0x2000
	s_nop 0
	global_load_lds_dwordx4 v[172:173], off
	v_lshl_add_u64 v[172:173], v[228:229], 0, s[12:13]
	s_mov_b32 m0, s44
	s_nop 0
	global_load_lds_dwordx4 v[172:173], off
	v_lshl_add_u64 v[172:173], v[230:231], 0, s[12:13]
	s_mov_b32 m0, s45
	s_nop 0
	global_load_lds_dwordx4 v[172:173], off
	s_waitcnt vmcnt(8)
	s_waitcnt lgkmcnt(0)
	s_barrier
	s_setprio 1
	s_waitcnt lgkmcnt(0)
	v_mfma_f32_16x16x32_bf16 v[62:65], v[148:151], v[194:197], v[62:65]
	v_mfma_f32_16x16x32_bf16 v[58:61], v[164:167], v[194:197], v[58:61]
	v_mfma_f32_16x16x32_bf16 v[46:49], v[148:151], v[202:205], v[46:49]
	v_mfma_f32_16x16x32_bf16 v[42:45], v[164:167], v[202:205], v[42:45]
	v_mfma_f32_16x16x32_bf16 v[30:33], v[148:151], v[210:213], v[30:33]
	v_mfma_f32_16x16x32_bf16 v[26:29], v[164:167], v[210:213], v[26:29]
	v_mfma_f32_16x16x32_bf16 v[14:17], v[148:151], v[218:221], v[14:17]
	v_mfma_f32_16x16x32_bf16 v[10:13], v[164:167], v[218:221], v[10:13]
	v_mfma_f32_16x16x32_bf16 v[62:65], v[160:163], v[198:201], v[62:65]
	v_mfma_f32_16x16x32_bf16 v[58:61], v[168:171], v[198:201], v[58:61]
	v_mfma_f32_16x16x32_bf16 v[46:49], v[160:163], v[206:209], v[46:49]
	v_mfma_f32_16x16x32_bf16 v[42:45], v[168:171], v[206:209], v[42:45]
	v_mfma_f32_16x16x32_bf16 v[30:33], v[160:163], v[214:217], v[30:33]
	v_mfma_f32_16x16x32_bf16 v[26:29], v[168:171], v[214:217], v[26:29]
	v_mfma_f32_16x16x32_bf16 v[14:17], v[160:163], v[222:225], v[14:17]
	v_mfma_f32_16x16x32_bf16 v[10:13], v[168:171], v[222:225], v[10:13]
	s_setprio 0
	s_setprio 1
	v_mfma_f32_16x16x32_bf16 v[54:57], v[178:181], v[194:197], v[54:57]
	v_mfma_f32_16x16x32_bf16 v[50:53], v[186:189], v[194:197], v[50:53]
	v_mfma_f32_16x16x32_bf16 v[38:41], v[178:181], v[202:205], v[38:41]
	v_mfma_f32_16x16x32_bf16 v[34:37], v[186:189], v[202:205], v[34:37]
	v_mfma_f32_16x16x32_bf16 v[22:25], v[178:181], v[210:213], v[22:25]
	v_mfma_f32_16x16x32_bf16 v[18:21], v[186:189], v[210:213], v[18:21]
	v_mfma_f32_16x16x32_bf16 v[6:9], v[178:181], v[218:221], v[6:9]
	v_mfma_f32_16x16x32_bf16 v[2:5], v[186:189], v[218:221], v[2:5]
	v_mfma_f32_16x16x32_bf16 v[54:57], v[182:185], v[198:201], v[54:57]
	v_mfma_f32_16x16x32_bf16 v[50:53], v[190:193], v[198:201], v[50:53]
	v_mfma_f32_16x16x32_bf16 v[38:41], v[182:185], v[206:209], v[38:41]
	v_mfma_f32_16x16x32_bf16 v[34:37], v[190:193], v[206:209], v[34:37]
	v_mfma_f32_16x16x32_bf16 v[22:25], v[182:185], v[214:217], v[22:25]
	v_mfma_f32_16x16x32_bf16 v[18:21], v[190:193], v[214:217], v[18:21]
	v_mfma_f32_16x16x32_bf16 v[6:9], v[182:185], v[222:225], v[6:9]
	v_mfma_f32_16x16x32_bf16 v[2:5], v[190:193], v[222:225], v[2:5]
	s_setprio 0
	s_add_i32 s54, s54, 2
	s_add_u32 s52, s52, 0x100
	s_addc_u32 s53, s53, 0
	s_cmp_gt_u32 s54, 13
	s_mov_b64 s[28:29], s[30:31]
	s_barrier
	s_cbranch_scc0 .LBB0_1323

.LBB0_1495:
	s_ashr_i32 s25, s24, 31
	s_lshl_b64 s[26:27], s[24:25], 19
	s_add_u32 s26, s3, s26
	s_addc_u32 s27, s14, s27
	s_and_b64 s[28:29], s[4:5], exec
	s_cselect_b32 s25, s27, s35
	s_cselect_b32 s31, s26, s34
	s_ashr_i32 s23, s22, 31
	s_lshl_b64 s[28:29], s[22:23], 19
	s_add_u32 s28, s15, s28
	s_addc_u32 s29, s16, s29
	s_and_b64 s[38:39], s[4:5], exec
	s_cselect_b32 s23, s29, s37
	s_cselect_b32 s54, s28, s36
	s_add_u32 s55, s36, 0x100
	s_addc_u32 s56, s37, 0
	s_mov_b32 s57, -2
	s_waitcnt lgkmcnt(0)
	ds_read_b128 v[146:149], v153
	ds_read_b128 v[158:161], v153 offset:1024
	ds_read_b128 v[162:165], v153 offset:2048
	ds_read_b128 v[166:169], v153 offset:3072
	ds_read_b128 v[170:173], v154
	ds_read_b128 v[178:181], v154 offset:1024
	ds_read_b128 v[182:185], v154 offset:2048
	ds_read_b128 v[186:189], v154 offset:3072
	s_add_u32 s36, s34, 0x100
	s_addc_u32 s37, s35, 0
	s_cmp_eq_u32 s57, 12
	s_cselect_b32 s41, s25, s37
	s_cselect_b32 s40, s31, s36
	s_cselect_b32 s39, s23, s56
	s_cselect_b32 s38, s54, s55
	v_lshl_add_u64 v[222:223], s[34:35], 0, v[138:139]
	s_add_i32 m0, s42, 0xc000
	ds_read_b128 v[190:193], v155
	ds_read_b128 v[194:197], v155 offset:1024
	ds_read_b128 v[198:201], v155 offset:2048
	ds_read_b128 v[202:205], v155 offset:3072
	ds_read_b128 v[206:209], v155 offset:4096
	ds_read_b128 v[210:213], v155 offset:5120
	ds_read_b128 v[214:217], v155 offset:6144
	ds_read_b128 v[218:221], v155 offset:7168
	global_load_lds_dwordx4 v[222:223], off
	v_lshl_add_u64 v[222:223], s[34:35], 0, v[140:141]
	s_add_i32 m0, s42, 0xe000
	s_nop 0
	global_load_lds_dwordx4 v[222:223], off
	s_waitcnt vmcnt(8)
	s_waitcnt lgkmcnt(0)
	s_barrier
	s_setprio 1
	s_waitcnt lgkmcnt(0)
	v_mfma_f32_16x16x32_bf16 v[126:129], v[146:149], v[190:193], 0
	v_mfma_f32_16x16x32_bf16 v[122:125], v[162:165], v[190:193], 0
	v_mfma_f32_16x16x32_bf16 v[110:113], v[146:149], v[198:201], 0
	v_mfma_f32_16x16x32_bf16 v[106:109], v[162:165], v[198:201], 0
	v_mfma_f32_16x16x32_bf16 v[94:97], v[146:149], v[206:209], 0
	v_mfma_f32_16x16x32_bf16 v[90:93], v[162:165], v[206:209], 0
	v_mfma_f32_16x16x32_bf16 v[78:81], v[146:149], v[214:217], 0
	v_mfma_f32_16x16x32_bf16 v[74:77], v[162:165], v[214:217], 0
	v_mfma_f32_16x16x32_bf16 v[126:129], v[158:161], v[194:197], v[126:129]
	v_mfma_f32_16x16x32_bf16 v[122:125], v[166:169], v[194:197], v[122:125]
	v_mfma_f32_16x16x32_bf16 v[110:113], v[158:161], v[202:205], v[110:113]
	v_mfma_f32_16x16x32_bf16 v[106:109], v[166:169], v[202:205], v[106:109]
	v_mfma_f32_16x16x32_bf16 v[94:97], v[158:161], v[210:213], v[94:97]
	v_mfma_f32_16x16x32_bf16 v[90:93], v[166:169], v[210:213], v[90:93]
	v_mfma_f32_16x16x32_bf16 v[78:81], v[158:161], v[218:221], v[78:81]
	v_mfma_f32_16x16x32_bf16 v[74:77], v[166:169], v[218:221], v[74:77]
	s_setprio 0
	s_setprio 1
	v_mfma_f32_16x16x32_bf16 v[118:121], v[170:173], v[190:193], 0
	v_mfma_f32_16x16x32_bf16 v[114:117], v[182:185], v[190:193], 0
	v_mfma_f32_16x16x32_bf16 v[102:105], v[170:173], v[198:201], 0
	v_mfma_f32_16x16x32_bf16 v[98:101], v[182:185], v[198:201], 0
	v_mfma_f32_16x16x32_bf16 v[86:89], v[170:173], v[206:209], 0
	v_mfma_f32_16x16x32_bf16 v[82:85], v[182:185], v[206:209], 0
	v_mfma_f32_16x16x32_bf16 v[70:73], v[170:173], v[214:217], 0
	v_mfma_f32_16x16x32_bf16 v[66:69], v[182:185], v[214:217], 0
	v_mfma_f32_16x16x32_bf16 v[118:121], v[178:181], v[194:197], v[118:121]
	v_mfma_f32_16x16x32_bf16 v[114:117], v[186:189], v[194:197], v[114:117]
	v_mfma_f32_16x16x32_bf16 v[102:105], v[178:181], v[202:205], v[102:105]
	v_mfma_f32_16x16x32_bf16 v[98:101], v[186:189], v[202:205], v[98:101]
	v_mfma_f32_16x16x32_bf16 v[86:89], v[178:181], v[210:213], v[86:89]
	v_mfma_f32_16x16x32_bf16 v[82:85], v[186:189], v[210:213], v[82:85]
	v_mfma_f32_16x16x32_bf16 v[70:73], v[178:181], v[218:221], v[70:73]
	v_mfma_f32_16x16x32_bf16 v[66:69], v[186:189], v[218:221], v[66:69]
	s_setprio 0
	s_barrier
	s_add_i32 s34, s51, s17
	v_lshl_add_u64 v[222:223], s[38:39], 0, v[132:133]
	s_mov_b32 m0, s34
	ds_read_b128 v[190:193], v155 offset:16384
	ds_read_b128 v[194:197], v155 offset:17408
	ds_read_b128 v[198:201], v155 offset:18432
	ds_read_b128 v[202:205], v155 offset:19456
	ds_read_b128 v[206:209], v155 offset:20480
	ds_read_b128 v[210:213], v155 offset:21504
	ds_read_b128 v[214:217], v155 offset:22528
	ds_read_b128 v[218:221], v155 offset:23552
	global_load_lds_dwordx4 v[222:223], off
	s_add_i32 m0, s34, 0x2000
	s_add_u32 s34, s38, 0x40000
	v_lshl_add_u64 v[224:225], s[38:39], 0, v[136:137]
	s_addc_u32 s35, s39, 0
	s_add_i32 s58, s52, s17
	global_load_lds_dwordx4 v[224:225], off
	v_lshl_add_u64 v[226:227], s[34:35], 0, v[132:133]
	s_mov_b32 m0, s58
	v_lshl_add_u64 v[228:229], s[40:41], 0, v[134:135]
	global_load_lds_dwordx4 v[226:227], off
	v_lshl_add_u64 v[226:227], s[34:35], 0, v[136:137]
	s_add_i32 m0, s58, 0x2000
	s_nop 0
	global_load_lds_dwordx4 v[226:227], off
	v_lshl_add_u64 v[226:227], s[40:41], 0, v[130:131]
	s_mov_b32 m0, s42
	s_nop 0
	global_load_lds_dwordx4 v[226:227], off
	s_mov_b32 m0, s43
	s_nop 0
	global_load_lds_dwordx4 v[228:229], off
	s_waitcnt vmcnt(8)
	s_waitcnt lgkmcnt(0)
	s_barrier
	s_setprio 1
	s_waitcnt lgkmcnt(0)
	v_mfma_f32_16x16x32_bf16 v[62:65], v[146:149], v[190:193], 0
	v_mfma_f32_16x16x32_bf16 v[58:61], v[162:165], v[190:193], 0
	v_mfma_f32_16x16x32_bf16 v[46:49], v[146:149], v[198:201], 0
	v_mfma_f32_16x16x32_bf16 v[42:45], v[162:165], v[198:201], 0
	v_mfma_f32_16x16x32_bf16 v[30:33], v[146:149], v[206:209], 0
	v_mfma_f32_16x16x32_bf16 v[26:29], v[162:165], v[206:209], 0
	v_mfma_f32_16x16x32_bf16 v[14:17], v[146:149], v[214:217], 0
	v_mfma_f32_16x16x32_bf16 v[10:13], v[162:165], v[214:217], 0
	v_mfma_f32_16x16x32_bf16 v[62:65], v[158:161], v[194:197], v[62:65]
	v_mfma_f32_16x16x32_bf16 v[58:61], v[166:169], v[194:197], v[58:61]
	v_mfma_f32_16x16x32_bf16 v[46:49], v[158:161], v[202:205], v[46:49]
	v_mfma_f32_16x16x32_bf16 v[42:45], v[166:169], v[202:205], v[42:45]
	v_mfma_f32_16x16x32_bf16 v[30:33], v[158:161], v[210:213], v[30:33]
	v_mfma_f32_16x16x32_bf16 v[26:29], v[166:169], v[210:213], v[26:29]
	v_mfma_f32_16x16x32_bf16 v[14:17], v[158:161], v[218:221], v[14:17]
	v_mfma_f32_16x16x32_bf16 v[10:13], v[166:169], v[218:221], v[10:13]
	s_setprio 0
	s_setprio 1
	v_mfma_f32_16x16x32_bf16 v[54:57], v[170:173], v[190:193], 0
	v_mfma_f32_16x16x32_bf16 v[50:53], v[182:185], v[190:193], 0
	v_mfma_f32_16x16x32_bf16 v[38:41], v[170:173], v[198:201], 0
	v_mfma_f32_16x16x32_bf16 v[34:37], v[182:185], v[198:201], 0
	v_mfma_f32_16x16x32_bf16 v[22:25], v[170:173], v[206:209], 0
	v_mfma_f32_16x16x32_bf16 v[18:21], v[182:185], v[206:209], 0
	v_mfma_f32_16x16x32_bf16 v[6:9], v[170:173], v[214:217], 0
	v_mfma_f32_16x16x32_bf16 v[2:5], v[182:185], v[214:217], 0
	v_mfma_f32_16x16x32_bf16 v[54:57], v[178:181], v[194:197], v[54:57]
	v_mfma_f32_16x16x32_bf16 v[50:53], v[186:189], v[194:197], v[50:53]
	v_mfma_f32_16x16x32_bf16 v[38:41], v[178:181], v[202:205], v[38:41]
	v_mfma_f32_16x16x32_bf16 v[34:37], v[186:189], v[202:205], v[34:37]
	v_mfma_f32_16x16x32_bf16 v[22:25], v[178:181], v[210:213], v[22:25]
	v_mfma_f32_16x16x32_bf16 v[18:21], v[186:189], v[210:213], v[18:21]
	v_mfma_f32_16x16x32_bf16 v[6:9], v[178:181], v[218:221], v[6:9]
	v_mfma_f32_16x16x32_bf16 v[2:5], v[186:189], v[218:221], v[2:5]
	s_setprio 0
	s_barrier
	s_add_i32 s58, 0, 0x18000
	v_add_u32_e32 v157, s58, v151
	s_add_i32 s59, 0, 0x1c000
	ds_read_b128 v[146:149], v157
	ds_read_b128 v[158:161], v157 offset:1024
	ds_read_b128 v[162:165], v157 offset:2048
	ds_read_b128 v[166:169], v157 offset:3072
	v_add_u32_e32 v157, s59, v151
	ds_read_b128 v[170:173], v157
	ds_read_b128 v[178:181], v157 offset:1024
	ds_read_b128 v[182:185], v157 offset:2048
	ds_read_b128 v[186:189], v157 offset:3072
	s_add_u32 s34, s40, 0x40000
	s_addc_u32 s35, s41, 0
	s_mov_b32 m0, s44
	v_lshl_add_u64 v[230:231], s[34:35], 0, v[130:131]
	ds_read_b128 v[190:193], v155 offset:32768
	ds_read_b128 v[194:197], v155 offset:33792
	ds_read_b128 v[198:201], v155 offset:34816
	ds_read_b128 v[202:205], v155 offset:35840
	ds_read_b128 v[206:209], v155 offset:36864
	ds_read_b128 v[210:213], v155 offset:37888
	ds_read_b128 v[214:217], v155 offset:38912
	ds_read_b128 v[218:221], v155 offset:39936
	global_load_lds_dwordx4 v[230:231], off
	v_lshl_add_u64 v[230:231], s[34:35], 0, v[134:135]
	s_mov_b32 m0, s45
	s_nop 0
	global_load_lds_dwordx4 v[230:231], off
	s_waitcnt vmcnt(8)
	s_waitcnt lgkmcnt(0)
	s_barrier
	s_setprio 1
	s_waitcnt lgkmcnt(0)
	v_mfma_f32_16x16x32_bf16 v[126:129], v[146:149], v[190:193], v[126:129]
	v_mfma_f32_16x16x32_bf16 v[122:125], v[162:165], v[190:193], v[122:125]
	v_mfma_f32_16x16x32_bf16 v[110:113], v[146:149], v[198:201], v[110:113]
	v_mfma_f32_16x16x32_bf16 v[106:109], v[162:165], v[198:201], v[106:109]
	v_mfma_f32_16x16x32_bf16 v[94:97], v[146:149], v[206:209], v[94:97]
	v_mfma_f32_16x16x32_bf16 v[90:93], v[162:165], v[206:209], v[90:93]
	v_mfma_f32_16x16x32_bf16 v[78:81], v[146:149], v[214:217], v[78:81]
	v_mfma_f32_16x16x32_bf16 v[74:77], v[162:165], v[214:217], v[74:77]
	v_mfma_f32_16x16x32_bf16 v[126:129], v[158:161], v[194:197], v[126:129]
	v_mfma_f32_16x16x32_bf16 v[122:125], v[166:169], v[194:197], v[122:125]
	v_mfma_f32_16x16x32_bf16 v[110:113], v[158:161], v[202:205], v[110:113]
	v_mfma_f32_16x16x32_bf16 v[106:109], v[166:169], v[202:205], v[106:109]
	v_mfma_f32_16x16x32_bf16 v[94:97], v[158:161], v[210:213], v[94:97]
	v_mfma_f32_16x16x32_bf16 v[90:93], v[166:169], v[210:213], v[90:93]
	v_mfma_f32_16x16x32_bf16 v[78:81], v[158:161], v[218:221], v[78:81]
	v_mfma_f32_16x16x32_bf16 v[74:77], v[166:169], v[218:221], v[74:77]
	s_setprio 0
	s_setprio 1
	v_mfma_f32_16x16x32_bf16 v[118:121], v[170:173], v[190:193], v[118:121]
	v_mfma_f32_16x16x32_bf16 v[114:117], v[182:185], v[190:193], v[114:117]
	v_mfma_f32_16x16x32_bf16 v[102:105], v[170:173], v[198:201], v[102:105]
	v_mfma_f32_16x16x32_bf16 v[98:101], v[182:185], v[198:201], v[98:101]
	v_mfma_f32_16x16x32_bf16 v[86:89], v[170:173], v[206:209], v[86:89]
	v_mfma_f32_16x16x32_bf16 v[82:85], v[182:185], v[206:209], v[82:85]
	v_mfma_f32_16x16x32_bf16 v[70:73], v[170:173], v[214:217], v[70:73]
	v_mfma_f32_16x16x32_bf16 v[66:69], v[182:185], v[214:217], v[66:69]
	v_mfma_f32_16x16x32_bf16 v[118:121], v[178:181], v[194:197], v[118:121]
	v_mfma_f32_16x16x32_bf16 v[114:117], v[186:189], v[194:197], v[114:117]
	v_mfma_f32_16x16x32_bf16 v[102:105], v[178:181], v[202:205], v[102:105]
	v_mfma_f32_16x16x32_bf16 v[98:101], v[186:189], v[202:205], v[98:101]
	v_mfma_f32_16x16x32_bf16 v[86:89], v[178:181], v[210:213], v[86:89]
	v_mfma_f32_16x16x32_bf16 v[82:85], v[186:189], v[210:213], v[82:85]
	v_mfma_f32_16x16x32_bf16 v[70:73], v[178:181], v[218:221], v[70:73]
	v_mfma_f32_16x16x32_bf16 v[66:69], v[186:189], v[218:221], v[66:69]
	s_setprio 0
	s_barrier
	s_add_i32 s34, s58, s17
	v_lshl_add_u64 v[222:223], v[222:223], 0, s[18:19]
	s_mov_b32 m0, s34
	ds_read_b128 v[190:193], v155 offset:49152
	ds_read_b128 v[194:197], v155 offset:50176
	ds_read_b128 v[198:201], v155 offset:51200
	ds_read_b128 v[202:205], v155 offset:52224
	ds_read_b128 v[206:209], v155 offset:53248
	ds_read_b128 v[210:213], v155 offset:54272
	ds_read_b128 v[214:217], v155 offset:55296
	ds_read_b128 v[218:221], v155 offset:56320
	global_load_lds_dwordx4 v[222:223], off
	s_add_i32 m0, s34, 0x2000
	s_add_u32 s34, s38, 0x40080
	v_lshl_add_u64 v[222:223], v[224:225], 0, s[18:19]
	s_addc_u32 s35, s39, 0
	s_add_i32 s38, s59, s17
	global_load_lds_dwordx4 v[222:223], off
	v_lshl_add_u64 v[222:223], s[34:35], 0, v[132:133]
	s_mov_b32 m0, s38
	s_nop 0
	global_load_lds_dwordx4 v[222:223], off
	v_lshl_add_u64 v[222:223], s[34:35], 0, v[136:137]
	s_add_i32 m0, s38, 0x2000
	s_nop 0
	global_load_lds_dwordx4 v[222:223], off
	v_lshl_add_u64 v[222:223], v[226:227], 0, s[18:19]
	s_mov_b32 m0, s47
	s_nop 0
	global_load_lds_dwordx4 v[222:223], off
	v_lshl_add_u64 v[222:223], v[228:229], 0, s[18:19]
	s_mov_b32 m0, s48
	s_nop 0
	global_load_lds_dwordx4 v[222:223], off
	s_waitcnt vmcnt(8)
	s_waitcnt lgkmcnt(0)
	s_barrier
	s_setprio 1
	s_waitcnt lgkmcnt(0)
	v_mfma_f32_16x16x32_bf16 v[62:65], v[146:149], v[190:193], v[62:65]
	v_mfma_f32_16x16x32_bf16 v[58:61], v[162:165], v[190:193], v[58:61]
	v_mfma_f32_16x16x32_bf16 v[46:49], v[146:149], v[198:201], v[46:49]
	v_mfma_f32_16x16x32_bf16 v[42:45], v[162:165], v[198:201], v[42:45]
	v_mfma_f32_16x16x32_bf16 v[30:33], v[146:149], v[206:209], v[30:33]
	v_mfma_f32_16x16x32_bf16 v[26:29], v[162:165], v[206:209], v[26:29]
	v_mfma_f32_16x16x32_bf16 v[14:17], v[146:149], v[214:217], v[14:17]
	v_mfma_f32_16x16x32_bf16 v[10:13], v[162:165], v[214:217], v[10:13]
	v_mfma_f32_16x16x32_bf16 v[62:65], v[158:161], v[194:197], v[62:65]
	v_mfma_f32_16x16x32_bf16 v[58:61], v[166:169], v[194:197], v[58:61]
	v_mfma_f32_16x16x32_bf16 v[46:49], v[158:161], v[202:205], v[46:49]
	v_mfma_f32_16x16x32_bf16 v[42:45], v[166:169], v[202:205], v[42:45]
	v_mfma_f32_16x16x32_bf16 v[30:33], v[158:161], v[210:213], v[30:33]
	v_mfma_f32_16x16x32_bf16 v[26:29], v[166:169], v[210:213], v[26:29]
	v_mfma_f32_16x16x32_bf16 v[14:17], v[158:161], v[218:221], v[14:17]
	v_mfma_f32_16x16x32_bf16 v[10:13], v[166:169], v[218:221], v[10:13]
	s_setprio 0
	s_setprio 1
	v_mfma_f32_16x16x32_bf16 v[54:57], v[170:173], v[190:193], v[54:57]
	v_mfma_f32_16x16x32_bf16 v[50:53], v[182:185], v[190:193], v[50:53]
	v_mfma_f32_16x16x32_bf16 v[38:41], v[170:173], v[198:201], v[38:41]
	v_mfma_f32_16x16x32_bf16 v[34:37], v[182:185], v[198:201], v[34:37]
	v_mfma_f32_16x16x32_bf16 v[22:25], v[170:173], v[206:209], v[22:25]
	v_mfma_f32_16x16x32_bf16 v[18:21], v[182:185], v[206:209], v[18:21]
	v_mfma_f32_16x16x32_bf16 v[6:9], v[170:173], v[214:217], v[6:9]
	v_mfma_f32_16x16x32_bf16 v[2:5], v[182:185], v[214:217], v[2:5]
	v_mfma_f32_16x16x32_bf16 v[54:57], v[178:181], v[194:197], v[54:57]
	v_mfma_f32_16x16x32_bf16 v[50:53], v[186:189], v[194:197], v[50:53]
	v_mfma_f32_16x16x32_bf16 v[38:41], v[178:181], v[202:205], v[38:41]
	v_mfma_f32_16x16x32_bf16 v[34:37], v[186:189], v[202:205], v[34:37]
	v_mfma_f32_16x16x32_bf16 v[22:25], v[178:181], v[210:213], v[22:25]
	v_mfma_f32_16x16x32_bf16 v[18:21], v[186:189], v[210:213], v[18:21]
	v_mfma_f32_16x16x32_bf16 v[6:9], v[178:181], v[218:221], v[6:9]
	v_mfma_f32_16x16x32_bf16 v[2:5], v[186:189], v[218:221], v[2:5]
	s_setprio 0
	s_add_i32 s57, s57, 2
	s_add_u32 s55, s55, 0x100
	s_addc_u32 s56, s56, 0
	s_cmp_gt_u32 s57, 13
	s_mov_b64 s[34:35], s[36:37]
	s_barrier
	s_cbranch_scc0 .LBB0_1496
	s_branch .Lpeel_exit_1496
.LBB0_1496:
	ds_read_b128 v[146:149], v153
	ds_read_b128 v[158:161], v153 offset:1024
	ds_read_b128 v[162:165], v153 offset:2048
	ds_read_b128 v[166:169], v153 offset:3072
	ds_read_b128 v[170:173], v154
	ds_read_b128 v[178:181], v154 offset:1024
	ds_read_b128 v[182:185], v154 offset:2048
	ds_read_b128 v[186:189], v154 offset:3072
	s_add_u32 s36, s34, 0x100
	s_addc_u32 s37, s35, 0
	s_cmp_eq_u32 s57, 12
	s_cselect_b32 s41, s25, s37
	s_cselect_b32 s40, s31, s36
	s_cselect_b32 s39, s23, s56
	s_cselect_b32 s38, s54, s55
	v_lshl_add_u64 v[222:223], s[34:35], 0, v[138:139]
	s_add_i32 m0, s42, 0xc000
	ds_read_b128 v[190:193], v155
	ds_read_b128 v[194:197], v155 offset:1024
	ds_read_b128 v[198:201], v155 offset:2048
	ds_read_b128 v[202:205], v155 offset:3072
	ds_read_b128 v[206:209], v155 offset:4096
	ds_read_b128 v[210:213], v155 offset:5120
	ds_read_b128 v[214:217], v155 offset:6144
	ds_read_b128 v[218:221], v155 offset:7168
	global_load_lds_dwordx4 v[222:223], off
	v_lshl_add_u64 v[222:223], s[34:35], 0, v[140:141]
	s_add_i32 m0, s42, 0xe000
	s_nop 0
	global_load_lds_dwordx4 v[222:223], off
	s_waitcnt vmcnt(8)
	s_waitcnt lgkmcnt(0)
	s_barrier
	s_setprio 1
	s_waitcnt lgkmcnt(0)
	v_mfma_f32_16x16x32_bf16 v[126:129], v[146:149], v[190:193], v[126:129]
	v_mfma_f32_16x16x32_bf16 v[122:125], v[162:165], v[190:193], v[122:125]
	v_mfma_f32_16x16x32_bf16 v[110:113], v[146:149], v[198:201], v[110:113]
	v_mfma_f32_16x16x32_bf16 v[106:109], v[162:165], v[198:201], v[106:109]
	v_mfma_f32_16x16x32_bf16 v[94:97], v[146:149], v[206:209], v[94:97]
	v_mfma_f32_16x16x32_bf16 v[90:93], v[162:165], v[206:209], v[90:93]
	v_mfma_f32_16x16x32_bf16 v[78:81], v[146:149], v[214:217], v[78:81]
	v_mfma_f32_16x16x32_bf16 v[74:77], v[162:165], v[214:217], v[74:77]
	v_mfma_f32_16x16x32_bf16 v[126:129], v[158:161], v[194:197], v[126:129]
	v_mfma_f32_16x16x32_bf16 v[122:125], v[166:169], v[194:197], v[122:125]
	v_mfma_f32_16x16x32_bf16 v[110:113], v[158:161], v[202:205], v[110:113]
	v_mfma_f32_16x16x32_bf16 v[106:109], v[166:169], v[202:205], v[106:109]
	v_mfma_f32_16x16x32_bf16 v[94:97], v[158:161], v[210:213], v[94:97]
	v_mfma_f32_16x16x32_bf16 v[90:93], v[166:169], v[210:213], v[90:93]
	v_mfma_f32_16x16x32_bf16 v[78:81], v[158:161], v[218:221], v[78:81]
	v_mfma_f32_16x16x32_bf16 v[74:77], v[166:169], v[218:221], v[74:77]
	s_setprio 0
	s_setprio 1
	v_mfma_f32_16x16x32_bf16 v[118:121], v[170:173], v[190:193], v[118:121]
	v_mfma_f32_16x16x32_bf16 v[114:117], v[182:185], v[190:193], v[114:117]
	v_mfma_f32_16x16x32_bf16 v[102:105], v[170:173], v[198:201], v[102:105]
	v_mfma_f32_16x16x32_bf16 v[98:101], v[182:185], v[198:201], v[98:101]
	v_mfma_f32_16x16x32_bf16 v[86:89], v[170:173], v[206:209], v[86:89]
	v_mfma_f32_16x16x32_bf16 v[82:85], v[182:185], v[206:209], v[82:85]
	v_mfma_f32_16x16x32_bf16 v[70:73], v[170:173], v[214:217], v[70:73]
	v_mfma_f32_16x16x32_bf16 v[66:69], v[182:185], v[214:217], v[66:69]
	v_mfma_f32_16x16x32_bf16 v[118:121], v[178:181], v[194:197], v[118:121]
	v_mfma_f32_16x16x32_bf16 v[114:117], v[186:189], v[194:197], v[114:117]
	v_mfma_f32_16x16x32_bf16 v[102:105], v[178:181], v[202:205], v[102:105]
	v_mfma_f32_16x16x32_bf16 v[98:101], v[186:189], v[202:205], v[98:101]
	v_mfma_f32_16x16x32_bf16 v[86:89], v[178:181], v[210:213], v[86:89]
	v_mfma_f32_16x16x32_bf16 v[82:85], v[186:189], v[210:213], v[82:85]
	v_mfma_f32_16x16x32_bf16 v[70:73], v[178:181], v[218:221], v[70:73]
	v_mfma_f32_16x16x32_bf16 v[66:69], v[186:189], v[218:221], v[66:69]
	s_setprio 0
	s_barrier
	s_add_i32 s34, s51, s17
	v_lshl_add_u64 v[222:223], s[38:39], 0, v[132:133]
	s_mov_b32 m0, s34
	ds_read_b128 v[190:193], v155 offset:16384
	ds_read_b128 v[194:197], v155 offset:17408
	ds_read_b128 v[198:201], v155 offset:18432
	ds_read_b128 v[202:205], v155 offset:19456
	ds_read_b128 v[206:209], v155 offset:20480
	ds_read_b128 v[210:213], v155 offset:21504
	ds_read_b128 v[214:217], v155 offset:22528
	ds_read_b128 v[218:221], v155 offset:23552
	global_load_lds_dwordx4 v[222:223], off
	s_add_i32 m0, s34, 0x2000
	s_add_u32 s34, s38, 0x40000
	v_lshl_add_u64 v[224:225], s[38:39], 0, v[136:137]
	s_addc_u32 s35, s39, 0
	s_add_i32 s58, s52, s17
	global_load_lds_dwordx4 v[224:225], off
	v_lshl_add_u64 v[226:227], s[34:35], 0, v[132:133]
	s_mov_b32 m0, s58
	v_lshl_add_u64 v[228:229], s[40:41], 0, v[134:135]
	global_load_lds_dwordx4 v[226:227], off
	v_lshl_add_u64 v[226:227], s[34:35], 0, v[136:137]
	s_add_i32 m0, s58, 0x2000
	s_nop 0
	global_load_lds_dwordx4 v[226:227], off
	v_lshl_add_u64 v[226:227], s[40:41], 0, v[130:131]
	s_mov_b32 m0, s42
	s_nop 0
	global_load_lds_dwordx4 v[226:227], off
	s_mov_b32 m0, s43
	s_nop 0
	global_load_lds_dwordx4 v[228:229], off
	s_waitcnt vmcnt(8)
	s_waitcnt lgkmcnt(0)
	s_barrier
	s_setprio 1
	s_waitcnt lgkmcnt(0)
	v_mfma_f32_16x16x32_bf16 v[62:65], v[146:149], v[190:193], v[62:65]
	v_mfma_f32_16x16x32_bf16 v[58:61], v[162:165], v[190:193], v[58:61]
	v_mfma_f32_16x16x32_bf16 v[46:49], v[146:149], v[198:201], v[46:49]
	v_mfma_f32_16x16x32_bf16 v[42:45], v[162:165], v[198:201], v[42:45]
	v_mfma_f32_16x16x32_bf16 v[30:33], v[146:149], v[206:209], v[30:33]
	v_mfma_f32_16x16x32_bf16 v[26:29], v[162:165], v[206:209], v[26:29]
	v_mfma_f32_16x16x32_bf16 v[14:17], v[146:149], v[214:217], v[14:17]
	v_mfma_f32_16x16x32_bf16 v[10:13], v[162:165], v[214:217], v[10:13]
	v_mfma_f32_16x16x32_bf16 v[62:65], v[158:161], v[194:197], v[62:65]
	v_mfma_f32_16x16x32_bf16 v[58:61], v[166:169], v[194:197], v[58:61]
	v_mfma_f32_16x16x32_bf16 v[46:49], v[158:161], v[202:205], v[46:49]
	v_mfma_f32_16x16x32_bf16 v[42:45], v[166:169], v[202:205], v[42:45]
	v_mfma_f32_16x16x32_bf16 v[30:33], v[158:161], v[210:213], v[30:33]
	v_mfma_f32_16x16x32_bf16 v[26:29], v[166:169], v[210:213], v[26:29]
	v_mfma_f32_16x16x32_bf16 v[14:17], v[158:161], v[218:221], v[14:17]
	v_mfma_f32_16x16x32_bf16 v[10:13], v[166:169], v[218:221], v[10:13]
	s_setprio 0
	s_setprio 1
	v_mfma_f32_16x16x32_bf16 v[54:57], v[170:173], v[190:193], v[54:57]
	v_mfma_f32_16x16x32_bf16 v[50:53], v[182:185], v[190:193], v[50:53]
	v_mfma_f32_16x16x32_bf16 v[38:41], v[170:173], v[198:201], v[38:41]
	v_mfma_f32_16x16x32_bf16 v[34:37], v[182:185], v[198:201], v[34:37]
	v_mfma_f32_16x16x32_bf16 v[22:25], v[170:173], v[206:209], v[22:25]
	v_mfma_f32_16x16x32_bf16 v[18:21], v[182:185], v[206:209], v[18:21]
	v_mfma_f32_16x16x32_bf16 v[6:9], v[170:173], v[214:217], v[6:9]
	v_mfma_f32_16x16x32_bf16 v[2:5], v[182:185], v[214:217], v[2:5]
	v_mfma_f32_16x16x32_bf16 v[54:57], v[178:181], v[194:197], v[54:57]
	v_mfma_f32_16x16x32_bf16 v[50:53], v[186:189], v[194:197], v[50:53]
	v_mfma_f32_16x16x32_bf16 v[38:41], v[178:181], v[202:205], v[38:41]
	v_mfma_f32_16x16x32_bf16 v[34:37], v[186:189], v[202:205], v[34:37]
	v_mfma_f32_16x16x32_bf16 v[22:25], v[178:181], v[210:213], v[22:25]
	v_mfma_f32_16x16x32_bf16 v[18:21], v[186:189], v[210:213], v[18:21]
	v_mfma_f32_16x16x32_bf16 v[6:9], v[178:181], v[218:221], v[6:9]
	v_mfma_f32_16x16x32_bf16 v[2:5], v[186:189], v[218:221], v[2:5]
	s_setprio 0
	s_barrier
	s_add_i32 s58, 0, 0x18000
	v_add_u32_e32 v157, s58, v151
	s_add_i32 s59, 0, 0x1c000
	ds_read_b128 v[146:149], v157
	ds_read_b128 v[158:161], v157 offset:1024
	ds_read_b128 v[162:165], v157 offset:2048
	ds_read_b128 v[166:169], v157 offset:3072
	v_add_u32_e32 v157, s59, v151
	ds_read_b128 v[170:173], v157
	ds_read_b128 v[178:181], v157 offset:1024
	ds_read_b128 v[182:185], v157 offset:2048
	ds_read_b128 v[186:189], v157 offset:3072
	s_add_u32 s34, s40, 0x40000
	s_addc_u32 s35, s41, 0
	s_mov_b32 m0, s44
	v_lshl_add_u64 v[230:231], s[34:35], 0, v[130:131]
	ds_read_b128 v[190:193], v155 offset:32768
	ds_read_b128 v[194:197], v155 offset:33792
	ds_read_b128 v[198:201], v155 offset:34816
	ds_read_b128 v[202:205], v155 offset:35840
	ds_read_b128 v[206:209], v155 offset:36864
	ds_read_b128 v[210:213], v155 offset:37888
	ds_read_b128 v[214:217], v155 offset:38912
	ds_read_b128 v[218:221], v155 offset:39936
	global_load_lds_dwordx4 v[230:231], off
	v_lshl_add_u64 v[230:231], s[34:35], 0, v[134:135]
	s_mov_b32 m0, s45
	s_nop 0
	global_load_lds_dwordx4 v[230:231], off
	s_waitcnt vmcnt(8)
	s_waitcnt lgkmcnt(0)
	s_barrier
	s_setprio 1
	s_waitcnt lgkmcnt(0)
	v_mfma_f32_16x16x32_bf16 v[126:129], v[146:149], v[190:193], v[126:129]
	v_mfma_f32_16x16x32_bf16 v[122:125], v[162:165], v[190:193], v[122:125]
	v_mfma_f32_16x16x32_bf16 v[110:113], v[146:149], v[198:201], v[110:113]
	v_mfma_f32_16x16x32_bf16 v[106:109], v[162:165], v[198:201], v[106:109]
	v_mfma_f32_16x16x32_bf16 v[94:97], v[146:149], v[206:209], v[94:97]
	v_mfma_f32_16x16x32_bf16 v[90:93], v[162:165], v[206:209], v[90:93]
	v_mfma_f32_16x16x32_bf16 v[78:81], v[146:149], v[214:217], v[78:81]
	v_mfma_f32_16x16x32_bf16 v[74:77], v[162:165], v[214:217], v[74:77]
	v_mfma_f32_16x16x32_bf16 v[126:129], v[158:161], v[194:197], v[126:129]
	v_mfma_f32_16x16x32_bf16 v[122:125], v[166:169], v[194:197], v[122:125]
	v_mfma_f32_16x16x32_bf16 v[110:113], v[158:161], v[202:205], v[110:113]
	v_mfma_f32_16x16x32_bf16 v[106:109], v[166:169], v[202:205], v[106:109]
	v_mfma_f32_16x16x32_bf16 v[94:97], v[158:161], v[210:213], v[94:97]
	v_mfma_f32_16x16x32_bf16 v[90:93], v[166:169], v[210:213], v[90:93]
	v_mfma_f32_16x16x32_bf16 v[78:81], v[158:161], v[218:221], v[78:81]
	v_mfma_f32_16x16x32_bf16 v[74:77], v[166:169], v[218:221], v[74:77]
	s_setprio 0
	s_setprio 1
	v_mfma_f32_16x16x32_bf16 v[118:121], v[170:173], v[190:193], v[118:121]
	v_mfma_f32_16x16x32_bf16 v[114:117], v[182:185], v[190:193], v[114:117]
	v_mfma_f32_16x16x32_bf16 v[102:105], v[170:173], v[198:201], v[102:105]
	v_mfma_f32_16x16x32_bf16 v[98:101], v[182:185], v[198:201], v[98:101]
	v_mfma_f32_16x16x32_bf16 v[86:89], v[170:173], v[206:209], v[86:89]
	v_mfma_f32_16x16x32_bf16 v[82:85], v[182:185], v[206:209], v[82:85]
	v_mfma_f32_16x16x32_bf16 v[70:73], v[170:173], v[214:217], v[70:73]
	v_mfma_f32_16x16x32_bf16 v[66:69], v[182:185], v[214:217], v[66:69]
	v_mfma_f32_16x16x32_bf16 v[118:121], v[178:181], v[194:197], v[118:121]
	v_mfma_f32_16x16x32_bf16 v[114:117], v[186:189], v[194:197], v[114:117]
	v_mfma_f32_16x16x32_bf16 v[102:105], v[178:181], v[202:205], v[102:105]
	v_mfma_f32_16x16x32_bf16 v[98:101], v[186:189], v[202:205], v[98:101]
	v_mfma_f32_16x16x32_bf16 v[86:89], v[178:181], v[210:213], v[86:89]
	v_mfma_f32_16x16x32_bf16 v[82:85], v[186:189], v[210:213], v[82:85]
	v_mfma_f32_16x16x32_bf16 v[70:73], v[178:181], v[218:221], v[70:73]
	v_mfma_f32_16x16x32_bf16 v[66:69], v[186:189], v[218:221], v[66:69]
	s_setprio 0
	s_barrier
	s_add_i32 s34, s58, s17
	v_lshl_add_u64 v[222:223], v[222:223], 0, s[18:19]
	s_mov_b32 m0, s34
	ds_read_b128 v[190:193], v155 offset:49152
	ds_read_b128 v[194:197], v155 offset:50176
	ds_read_b128 v[198:201], v155 offset:51200
	ds_read_b128 v[202:205], v155 offset:52224
	ds_read_b128 v[206:209], v155 offset:53248
	ds_read_b128 v[210:213], v155 offset:54272
	ds_read_b128 v[214:217], v155 offset:55296
	ds_read_b128 v[218:221], v155 offset:56320
	global_load_lds_dwordx4 v[222:223], off
	s_add_i32 m0, s34, 0x2000
	s_add_u32 s34, s38, 0x40080
	v_lshl_add_u64 v[222:223], v[224:225], 0, s[18:19]
	s_addc_u32 s35, s39, 0
	s_add_i32 s38, s59, s17
	global_load_lds_dwordx4 v[222:223], off
	v_lshl_add_u64 v[222:223], s[34:35], 0, v[132:133]
	s_mov_b32 m0, s38
	s_nop 0
	global_load_lds_dwordx4 v[222:223], off
	v_lshl_add_u64 v[222:223], s[34:35], 0, v[136:137]
	s_add_i32 m0, s38, 0x2000
	s_nop 0
	global_load_lds_dwordx4 v[222:223], off
	v_lshl_add_u64 v[222:223], v[226:227], 0, s[18:19]
	s_mov_b32 m0, s47
	s_nop 0
	global_load_lds_dwordx4 v[222:223], off
	v_lshl_add_u64 v[222:223], v[228:229], 0, s[18:19]
	s_mov_b32 m0, s48
	s_nop 0
	global_load_lds_dwordx4 v[222:223], off
	s_waitcnt vmcnt(8)
	s_waitcnt lgkmcnt(0)
	s_barrier
	s_setprio 1
	s_waitcnt lgkmcnt(0)
	v_mfma_f32_16x16x32_bf16 v[62:65], v[146:149], v[190:193], v[62:65]
	v_mfma_f32_16x16x32_bf16 v[58:61], v[162:165], v[190:193], v[58:61]
	v_mfma_f32_16x16x32_bf16 v[46:49], v[146:149], v[198:201], v[46:49]
	v_mfma_f32_16x16x32_bf16 v[42:45], v[162:165], v[198:201], v[42:45]
	v_mfma_f32_16x16x32_bf16 v[30:33], v[146:149], v[206:209], v[30:33]
	v_mfma_f32_16x16x32_bf16 v[26:29], v[162:165], v[206:209], v[26:29]
	v_mfma_f32_16x16x32_bf16 v[14:17], v[146:149], v[214:217], v[14:17]
	v_mfma_f32_16x16x32_bf16 v[10:13], v[162:165], v[214:217], v[10:13]
	v_mfma_f32_16x16x32_bf16 v[62:65], v[158:161], v[194:197], v[62:65]
	v_mfma_f32_16x16x32_bf16 v[58:61], v[166:169], v[194:197], v[58:61]
	v_mfma_f32_16x16x32_bf16 v[46:49], v[158:161], v[202:205], v[46:49]
	v_mfma_f32_16x16x32_bf16 v[42:45], v[166:169], v[202:205], v[42:45]
	v_mfma_f32_16x16x32_bf16 v[30:33], v[158:161], v[210:213], v[30:33]
	v_mfma_f32_16x16x32_bf16 v[26:29], v[166:169], v[210:213], v[26:29]
	v_mfma_f32_16x16x32_bf16 v[14:17], v[158:161], v[218:221], v[14:17]
	v_mfma_f32_16x16x32_bf16 v[10:13], v[166:169], v[218:221], v[10:13]
	s_setprio 0
	s_setprio 1
	v_mfma_f32_16x16x32_bf16 v[54:57], v[170:173], v[190:193], v[54:57]
	v_mfma_f32_16x16x32_bf16 v[50:53], v[182:185], v[190:193], v[50:53]
	v_mfma_f32_16x16x32_bf16 v[38:41], v[170:173], v[198:201], v[38:41]
	v_mfma_f32_16x16x32_bf16 v[34:37], v[182:185], v[198:201], v[34:37]
	v_mfma_f32_16x16x32_bf16 v[22:25], v[170:173], v[206:209], v[22:25]
	v_mfma_f32_16x16x32_bf16 v[18:21], v[182:185], v[206:209], v[18:21]
	v_mfma_f32_16x16x32_bf16 v[6:9], v[170:173], v[214:217], v[6:9]
	v_mfma_f32_16x16x32_bf16 v[2:5], v[182:185], v[214:217], v[2:5]
	v_mfma_f32_16x16x32_bf16 v[54:57], v[178:181], v[194:197], v[54:57]
	v_mfma_f32_16x16x32_bf16 v[50:53], v[186:189], v[194:197], v[50:53]
	v_mfma_f32_16x16x32_bf16 v[38:41], v[178:181], v[202:205], v[38:41]
	v_mfma_f32_16x16x32_bf16 v[34:37], v[186:189], v[202:205], v[34:37]
	v_mfma_f32_16x16x32_bf16 v[22:25], v[178:181], v[210:213], v[22:25]
	v_mfma_f32_16x16x32_bf16 v[18:21], v[186:189], v[210:213], v[18:21]
	v_mfma_f32_16x16x32_bf16 v[6:9], v[178:181], v[218:221], v[6:9]
	v_mfma_f32_16x16x32_bf16 v[2:5], v[186:189], v[218:221], v[2:5]
	s_setprio 0
	s_add_i32 s57, s57, 2
	s_add_u32 s55, s55, 0x100
	s_addc_u32 s56, s56, 0
	s_cmp_gt_u32 s57, 13
	s_mov_b64 s[34:35], s[36:37]
	s_barrier
	s_cbranch_scc0 .LBB0_1496

.LBB0_1589:
	s_ashr_i32 s21, s20, 31
	s_lshl_b64 s[22:23], s[20:21], 19
	s_add_u32 s22, s14, s22
	s_addc_u32 s23, s15, s23
	s_and_b64 s[24:25], s[0:1], exec
	s_cselect_b32 s21, s23, s27
	s_cselect_b32 s49, s22, s26
	s_ashr_i32 s19, s18, 31
	s_lshl_b64 s[24:25], s[18:19], 19
	s_add_u32 s24, s16, s24
	s_addc_u32 s25, s17, s25
	s_and_b64 s[30:31], s[0:1], exec
	s_cselect_b32 s19, s25, s29
	s_cselect_b32 s50, s24, s28
	s_add_u32 s51, s28, 0x100
	s_addc_u32 s52, s29, 0
	s_mov_b32 s53, -2
	s_waitcnt vmcnt(0)
	ds_read_b128 v[146:149], v155
	ds_read_b128 v[160:163], v155 offset:1024
	ds_read_b128 v[164:167], v155 offset:2048
	ds_read_b128 v[168:171], v155 offset:3072
	ds_read_b128 v[178:181], v156
	ds_read_b128 v[182:185], v156 offset:1024
	ds_read_b128 v[186:189], v156 offset:2048
	ds_read_b128 v[190:193], v156 offset:3072
	s_add_u32 s28, s26, 0x100
	s_addc_u32 s29, s27, 0
	s_cmp_eq_u32 s53, 12
	s_cselect_b32 s35, s21, s29
	s_cselect_b32 s34, s49, s28
	s_cselect_b32 s31, s19, s52
	s_cselect_b32 s30, s50, s51
	v_lshl_add_u64 v[150:151], s[26:27], 0, v[138:139]
	s_add_i32 m0, s37, 0xc000
	ds_read_b128 v[194:197], v157
	ds_read_b128 v[198:201], v157 offset:1024
	ds_read_b128 v[202:205], v157 offset:2048
	ds_read_b128 v[206:209], v157 offset:3072
	ds_read_b128 v[210:213], v157 offset:4096
	ds_read_b128 v[214:217], v157 offset:5120
	ds_read_b128 v[218:221], v157 offset:6144
	ds_read_b128 v[222:225], v157 offset:7168
	global_load_lds_dwordx4 v[150:151], off
	v_lshl_add_u64 v[150:151], s[26:27], 0, v[140:141]
	s_add_i32 m0, s37, 0xe000
	s_nop 0
	global_load_lds_dwordx4 v[150:151], off
	s_waitcnt vmcnt(8)
	s_waitcnt lgkmcnt(0)
	s_barrier
	s_setprio 1
	s_waitcnt lgkmcnt(0)
	v_mfma_f32_16x16x32_bf16 v[126:129], v[146:149], v[194:197], 0
	v_mfma_f32_16x16x32_bf16 v[122:125], v[164:167], v[194:197], 0
	v_mfma_f32_16x16x32_bf16 v[110:113], v[146:149], v[202:205], 0
	v_mfma_f32_16x16x32_bf16 v[106:109], v[164:167], v[202:205], 0
	v_mfma_f32_16x16x32_bf16 v[94:97], v[146:149], v[210:213], 0
	v_mfma_f32_16x16x32_bf16 v[90:93], v[164:167], v[210:213], 0
	v_mfma_f32_16x16x32_bf16 v[78:81], v[146:149], v[218:221], 0
	v_mfma_f32_16x16x32_bf16 v[74:77], v[164:167], v[218:221], 0
	v_mfma_f32_16x16x32_bf16 v[126:129], v[160:163], v[198:201], v[126:129]
	v_mfma_f32_16x16x32_bf16 v[122:125], v[168:171], v[198:201], v[122:125]
	v_mfma_f32_16x16x32_bf16 v[110:113], v[160:163], v[206:209], v[110:113]
	v_mfma_f32_16x16x32_bf16 v[106:109], v[168:171], v[206:209], v[106:109]
	v_mfma_f32_16x16x32_bf16 v[94:97], v[160:163], v[214:217], v[94:97]
	v_mfma_f32_16x16x32_bf16 v[90:93], v[168:171], v[214:217], v[90:93]
	v_mfma_f32_16x16x32_bf16 v[78:81], v[160:163], v[222:225], v[78:81]
	v_mfma_f32_16x16x32_bf16 v[74:77], v[168:171], v[222:225], v[74:77]
	s_setprio 0
	s_setprio 1
	v_mfma_f32_16x16x32_bf16 v[118:121], v[178:181], v[194:197], 0
	v_mfma_f32_16x16x32_bf16 v[114:117], v[186:189], v[194:197], 0
	v_mfma_f32_16x16x32_bf16 v[102:105], v[178:181], v[202:205], 0
	v_mfma_f32_16x16x32_bf16 v[98:101], v[186:189], v[202:205], 0
	v_mfma_f32_16x16x32_bf16 v[86:89], v[178:181], v[210:213], 0
	v_mfma_f32_16x16x32_bf16 v[82:85], v[186:189], v[210:213], 0
	v_mfma_f32_16x16x32_bf16 v[70:73], v[178:181], v[218:221], 0
	v_mfma_f32_16x16x32_bf16 v[66:69], v[186:189], v[218:221], 0
	v_mfma_f32_16x16x32_bf16 v[118:121], v[182:185], v[198:201], v[118:121]
	v_mfma_f32_16x16x32_bf16 v[114:117], v[190:193], v[198:201], v[114:117]
	v_mfma_f32_16x16x32_bf16 v[102:105], v[182:185], v[206:209], v[102:105]
	v_mfma_f32_16x16x32_bf16 v[98:101], v[190:193], v[206:209], v[98:101]
	v_mfma_f32_16x16x32_bf16 v[86:89], v[182:185], v[214:217], v[86:89]
	v_mfma_f32_16x16x32_bf16 v[82:85], v[190:193], v[214:217], v[82:85]
	v_mfma_f32_16x16x32_bf16 v[70:73], v[182:185], v[222:225], v[70:73]
	v_mfma_f32_16x16x32_bf16 v[66:69], v[190:193], v[222:225], v[66:69]
	s_setprio 0
	s_barrier
	s_add_i32 s26, s45, s36
	v_lshl_add_u64 v[150:151], s[30:31], 0, v[132:133]
	s_mov_b32 m0, s26
	ds_read_b128 v[194:197], v157 offset:16384
	ds_read_b128 v[198:201], v157 offset:17408
	ds_read_b128 v[202:205], v157 offset:18432
	ds_read_b128 v[206:209], v157 offset:19456
	ds_read_b128 v[210:213], v157 offset:20480
	ds_read_b128 v[214:217], v157 offset:21504
	ds_read_b128 v[218:221], v157 offset:22528
	ds_read_b128 v[222:225], v157 offset:23552
	global_load_lds_dwordx4 v[150:151], off
	s_add_i32 m0, s26, 0x2000
	s_add_u32 s26, s30, 0x40000
	v_lshl_add_u64 v[172:173], s[30:31], 0, v[136:137]
	s_addc_u32 s27, s31, 0
	s_add_i32 s54, s46, s36
	global_load_lds_dwordx4 v[172:173], off
	v_lshl_add_u64 v[226:227], s[26:27], 0, v[132:133]
	s_mov_b32 m0, s54
	v_lshl_add_u64 v[228:229], s[34:35], 0, v[134:135]
	global_load_lds_dwordx4 v[226:227], off
	v_lshl_add_u64 v[226:227], s[26:27], 0, v[136:137]
	s_add_i32 m0, s54, 0x2000
	s_nop 0
	global_load_lds_dwordx4 v[226:227], off
	v_lshl_add_u64 v[226:227], s[34:35], 0, v[130:131]
	s_mov_b32 m0, s37
	s_nop 0
	global_load_lds_dwordx4 v[226:227], off
	s_mov_b32 m0, s38
	s_nop 0
	global_load_lds_dwordx4 v[228:229], off
	s_waitcnt vmcnt(8)
	s_waitcnt lgkmcnt(0)
	s_barrier
	s_setprio 1
	s_waitcnt lgkmcnt(0)
	v_mfma_f32_16x16x32_bf16 v[62:65], v[146:149], v[194:197], 0
	v_mfma_f32_16x16x32_bf16 v[58:61], v[164:167], v[194:197], 0
	v_mfma_f32_16x16x32_bf16 v[46:49], v[146:149], v[202:205], 0
	v_mfma_f32_16x16x32_bf16 v[42:45], v[164:167], v[202:205], 0
	v_mfma_f32_16x16x32_bf16 v[30:33], v[146:149], v[210:213], 0
	v_mfma_f32_16x16x32_bf16 v[26:29], v[164:167], v[210:213], 0
	v_mfma_f32_16x16x32_bf16 v[14:17], v[146:149], v[218:221], 0
	v_mfma_f32_16x16x32_bf16 v[10:13], v[164:167], v[218:221], 0
	v_mfma_f32_16x16x32_bf16 v[62:65], v[160:163], v[198:201], v[62:65]
	v_mfma_f32_16x16x32_bf16 v[58:61], v[168:171], v[198:201], v[58:61]
	v_mfma_f32_16x16x32_bf16 v[46:49], v[160:163], v[206:209], v[46:49]
	v_mfma_f32_16x16x32_bf16 v[42:45], v[168:171], v[206:209], v[42:45]
	v_mfma_f32_16x16x32_bf16 v[30:33], v[160:163], v[214:217], v[30:33]
	v_mfma_f32_16x16x32_bf16 v[26:29], v[168:171], v[214:217], v[26:29]
	v_mfma_f32_16x16x32_bf16 v[14:17], v[160:163], v[222:225], v[14:17]
	v_mfma_f32_16x16x32_bf16 v[10:13], v[168:171], v[222:225], v[10:13]
	s_setprio 0
	s_setprio 1
	v_mfma_f32_16x16x32_bf16 v[54:57], v[178:181], v[194:197], 0
	v_mfma_f32_16x16x32_bf16 v[50:53], v[186:189], v[194:197], 0
	v_mfma_f32_16x16x32_bf16 v[38:41], v[178:181], v[202:205], 0
	v_mfma_f32_16x16x32_bf16 v[34:37], v[186:189], v[202:205], 0
	v_mfma_f32_16x16x32_bf16 v[22:25], v[178:181], v[210:213], 0
	v_mfma_f32_16x16x32_bf16 v[18:21], v[186:189], v[210:213], 0
	v_mfma_f32_16x16x32_bf16 v[6:9], v[178:181], v[218:221], 0
	v_mfma_f32_16x16x32_bf16 v[2:5], v[186:189], v[218:221], 0
	v_mfma_f32_16x16x32_bf16 v[54:57], v[182:185], v[198:201], v[54:57]
	v_mfma_f32_16x16x32_bf16 v[50:53], v[190:193], v[198:201], v[50:53]
	v_mfma_f32_16x16x32_bf16 v[38:41], v[182:185], v[206:209], v[38:41]
	v_mfma_f32_16x16x32_bf16 v[34:37], v[190:193], v[206:209], v[34:37]
	v_mfma_f32_16x16x32_bf16 v[22:25], v[182:185], v[214:217], v[22:25]
	v_mfma_f32_16x16x32_bf16 v[18:21], v[190:193], v[214:217], v[18:21]
	v_mfma_f32_16x16x32_bf16 v[6:9], v[182:185], v[222:225], v[6:9]
	v_mfma_f32_16x16x32_bf16 v[2:5], v[190:193], v[222:225], v[2:5]
	s_setprio 0
	s_barrier
	s_add_i32 s54, 0, 0x18000
	s_add_i32 s55, 0, 0x1c000
	v_add_u32_e32 v168, s54, v153
	v_add_u32_e32 v177, s55, v153
	ds_read_b128 v[146:149], v168
	ds_read_b128 v[160:163], v168 offset:1024
	ds_read_b128 v[164:167], v168 offset:2048
	ds_read_b128 v[168:171], v168 offset:3072
	ds_read_b128 v[178:181], v177
	ds_read_b128 v[182:185], v177 offset:1024
	ds_read_b128 v[186:189], v177 offset:2048
	ds_read_b128 v[190:193], v177 offset:3072
	s_add_u32 s26, s34, 0x40000
	s_addc_u32 s27, s35, 0
	s_mov_b32 m0, s39
	v_lshl_add_u64 v[230:231], s[26:27], 0, v[130:131]
	ds_read_b128 v[194:197], v157 offset:32768
	ds_read_b128 v[198:201], v157 offset:33792
	ds_read_b128 v[202:205], v157 offset:34816
	ds_read_b128 v[206:209], v157 offset:35840
	ds_read_b128 v[210:213], v157 offset:36864
	ds_read_b128 v[214:217], v157 offset:37888
	ds_read_b128 v[218:221], v157 offset:38912
	ds_read_b128 v[222:225], v157 offset:39936
	global_load_lds_dwordx4 v[230:231], off
	v_lshl_add_u64 v[230:231], s[26:27], 0, v[134:135]
	s_mov_b32 m0, s40
	s_nop 0
	global_load_lds_dwordx4 v[230:231], off
	s_waitcnt vmcnt(8)
	s_waitcnt lgkmcnt(0)
	s_barrier
	s_setprio 1
	s_waitcnt lgkmcnt(0)
	v_mfma_f32_16x16x32_bf16 v[126:129], v[146:149], v[194:197], v[126:129]
	v_mfma_f32_16x16x32_bf16 v[122:125], v[164:167], v[194:197], v[122:125]
	v_mfma_f32_16x16x32_bf16 v[110:113], v[146:149], v[202:205], v[110:113]
	v_mfma_f32_16x16x32_bf16 v[106:109], v[164:167], v[202:205], v[106:109]
	v_mfma_f32_16x16x32_bf16 v[94:97], v[146:149], v[210:213], v[94:97]
	v_mfma_f32_16x16x32_bf16 v[90:93], v[164:167], v[210:213], v[90:93]
	v_mfma_f32_16x16x32_bf16 v[78:81], v[146:149], v[218:221], v[78:81]
	v_mfma_f32_16x16x32_bf16 v[74:77], v[164:167], v[218:221], v[74:77]
	v_mfma_f32_16x16x32_bf16 v[126:129], v[160:163], v[198:201], v[126:129]
	v_mfma_f32_16x16x32_bf16 v[122:125], v[168:171], v[198:201], v[122:125]
	v_mfma_f32_16x16x32_bf16 v[110:113], v[160:163], v[206:209], v[110:113]
	v_mfma_f32_16x16x32_bf16 v[106:109], v[168:171], v[206:209], v[106:109]
	v_mfma_f32_16x16x32_bf16 v[94:97], v[160:163], v[214:217], v[94:97]
	v_mfma_f32_16x16x32_bf16 v[90:93], v[168:171], v[214:217], v[90:93]
	v_mfma_f32_16x16x32_bf16 v[78:81], v[160:163], v[222:225], v[78:81]
	v_mfma_f32_16x16x32_bf16 v[74:77], v[168:171], v[222:225], v[74:77]
	s_setprio 0
	s_setprio 1
	v_mfma_f32_16x16x32_bf16 v[118:121], v[178:181], v[194:197], v[118:121]
	v_mfma_f32_16x16x32_bf16 v[114:117], v[186:189], v[194:197], v[114:117]
	v_mfma_f32_16x16x32_bf16 v[102:105], v[178:181], v[202:205], v[102:105]
	v_mfma_f32_16x16x32_bf16 v[98:101], v[186:189], v[202:205], v[98:101]
	v_mfma_f32_16x16x32_bf16 v[86:89], v[178:181], v[210:213], v[86:89]
	v_mfma_f32_16x16x32_bf16 v[82:85], v[186:189], v[210:213], v[82:85]
	v_mfma_f32_16x16x32_bf16 v[70:73], v[178:181], v[218:221], v[70:73]
	v_mfma_f32_16x16x32_bf16 v[66:69], v[186:189], v[218:221], v[66:69]
	v_mfma_f32_16x16x32_bf16 v[118:121], v[182:185], v[198:201], v[118:121]
	v_mfma_f32_16x16x32_bf16 v[114:117], v[190:193], v[198:201], v[114:117]
	v_mfma_f32_16x16x32_bf16 v[102:105], v[182:185], v[206:209], v[102:105]
	v_mfma_f32_16x16x32_bf16 v[98:101], v[190:193], v[206:209], v[98:101]
	v_mfma_f32_16x16x32_bf16 v[86:89], v[182:185], v[214:217], v[86:89]
	v_mfma_f32_16x16x32_bf16 v[82:85], v[190:193], v[214:217], v[82:85]
	v_mfma_f32_16x16x32_bf16 v[70:73], v[182:185], v[222:225], v[70:73]
	v_mfma_f32_16x16x32_bf16 v[66:69], v[190:193], v[222:225], v[66:69]
	s_setprio 0
	s_barrier
	s_add_i32 s26, s54, s36
	v_lshl_add_u64 v[150:151], v[150:151], 0, s[10:11]
	s_mov_b32 m0, s26
	ds_read_b128 v[194:197], v157 offset:49152
	ds_read_b128 v[198:201], v157 offset:50176
	ds_read_b128 v[202:205], v157 offset:51200
	ds_read_b128 v[206:209], v157 offset:52224
	ds_read_b128 v[210:213], v157 offset:53248
	ds_read_b128 v[214:217], v157 offset:54272
	ds_read_b128 v[218:221], v157 offset:55296
	ds_read_b128 v[222:225], v157 offset:56320
	global_load_lds_dwordx4 v[150:151], off
	s_add_i32 m0, s26, 0x2000
	s_add_u32 s26, s30, 0x40080
	v_lshl_add_u64 v[150:151], v[172:173], 0, s[10:11]
	s_addc_u32 s27, s31, 0
	s_add_i32 s30, s55, s36
	global_load_lds_dwordx4 v[150:151], off
	v_lshl_add_u64 v[150:151], s[26:27], 0, v[132:133]
	s_mov_b32 m0, s30
	s_nop 0
	global_load_lds_dwordx4 v[150:151], off
	v_lshl_add_u64 v[150:151], s[26:27], 0, v[136:137]
	s_add_i32 m0, s30, 0x2000
	s_nop 0
	global_load_lds_dwordx4 v[150:151], off
	v_lshl_add_u64 v[150:151], v[226:227], 0, s[10:11]
	s_mov_b32 m0, s42
	s_nop 0
	global_load_lds_dwordx4 v[150:151], off
	v_lshl_add_u64 v[150:151], v[228:229], 0, s[10:11]
	s_mov_b32 m0, s43
	s_nop 0
	global_load_lds_dwordx4 v[150:151], off
	s_waitcnt vmcnt(8)
	s_waitcnt lgkmcnt(0)
	s_barrier
	s_setprio 1
	s_waitcnt lgkmcnt(0)
	v_mfma_f32_16x16x32_bf16 v[62:65], v[146:149], v[194:197], v[62:65]
	v_mfma_f32_16x16x32_bf16 v[58:61], v[164:167], v[194:197], v[58:61]
	v_mfma_f32_16x16x32_bf16 v[46:49], v[146:149], v[202:205], v[46:49]
	v_mfma_f32_16x16x32_bf16 v[42:45], v[164:167], v[202:205], v[42:45]
	v_mfma_f32_16x16x32_bf16 v[30:33], v[146:149], v[210:213], v[30:33]
	v_mfma_f32_16x16x32_bf16 v[26:29], v[164:167], v[210:213], v[26:29]
	v_mfma_f32_16x16x32_bf16 v[14:17], v[146:149], v[218:221], v[14:17]
	v_mfma_f32_16x16x32_bf16 v[10:13], v[164:167], v[218:221], v[10:13]
	v_mfma_f32_16x16x32_bf16 v[62:65], v[160:163], v[198:201], v[62:65]
	v_mfma_f32_16x16x32_bf16 v[58:61], v[168:171], v[198:201], v[58:61]
	v_mfma_f32_16x16x32_bf16 v[46:49], v[160:163], v[206:209], v[46:49]
	v_mfma_f32_16x16x32_bf16 v[42:45], v[168:171], v[206:209], v[42:45]
	v_mfma_f32_16x16x32_bf16 v[30:33], v[160:163], v[214:217], v[30:33]
	v_mfma_f32_16x16x32_bf16 v[26:29], v[168:171], v[214:217], v[26:29]
	v_mfma_f32_16x16x32_bf16 v[14:17], v[160:163], v[222:225], v[14:17]
	v_mfma_f32_16x16x32_bf16 v[10:13], v[168:171], v[222:225], v[10:13]
	s_setprio 0
	s_setprio 1
	v_mfma_f32_16x16x32_bf16 v[54:57], v[178:181], v[194:197], v[54:57]
	v_mfma_f32_16x16x32_bf16 v[50:53], v[186:189], v[194:197], v[50:53]
	v_mfma_f32_16x16x32_bf16 v[38:41], v[178:181], v[202:205], v[38:41]
	v_mfma_f32_16x16x32_bf16 v[34:37], v[186:189], v[202:205], v[34:37]
	v_mfma_f32_16x16x32_bf16 v[22:25], v[178:181], v[210:213], v[22:25]
	v_mfma_f32_16x16x32_bf16 v[18:21], v[186:189], v[210:213], v[18:21]
	v_mfma_f32_16x16x32_bf16 v[6:9], v[178:181], v[218:221], v[6:9]
	v_mfma_f32_16x16x32_bf16 v[2:5], v[186:189], v[218:221], v[2:5]
	v_mfma_f32_16x16x32_bf16 v[54:57], v[182:185], v[198:201], v[54:57]
	v_mfma_f32_16x16x32_bf16 v[50:53], v[190:193], v[198:201], v[50:53]
	v_mfma_f32_16x16x32_bf16 v[38:41], v[182:185], v[206:209], v[38:41]
	v_mfma_f32_16x16x32_bf16 v[34:37], v[190:193], v[206:209], v[34:37]
	v_mfma_f32_16x16x32_bf16 v[22:25], v[182:185], v[214:217], v[22:25]
	v_mfma_f32_16x16x32_bf16 v[18:21], v[190:193], v[214:217], v[18:21]
	v_mfma_f32_16x16x32_bf16 v[6:9], v[182:185], v[222:225], v[6:9]
	v_mfma_f32_16x16x32_bf16 v[2:5], v[190:193], v[222:225], v[2:5]
	s_setprio 0
	s_add_i32 s53, s53, 2
	s_add_u32 s51, s51, 0x100
	s_addc_u32 s52, s52, 0
	s_cmp_gt_u32 s53, 13
	s_mov_b64 s[26:27], s[28:29]
	s_barrier
	s_cbranch_scc0 .LBB0_1590
	s_branch .Lpeel_exit_1590
.LBB0_1590:
	ds_read_b128 v[146:149], v155
	ds_read_b128 v[160:163], v155 offset:1024
	ds_read_b128 v[164:167], v155 offset:2048
	ds_read_b128 v[168:171], v155 offset:3072
	ds_read_b128 v[178:181], v156
	ds_read_b128 v[182:185], v156 offset:1024
	ds_read_b128 v[186:189], v156 offset:2048
	ds_read_b128 v[190:193], v156 offset:3072
	s_add_u32 s28, s26, 0x100
	s_addc_u32 s29, s27, 0
	s_cmp_eq_u32 s53, 12
	s_cselect_b32 s35, s21, s29
	s_cselect_b32 s34, s49, s28
	s_cselect_b32 s31, s19, s52
	s_cselect_b32 s30, s50, s51
	v_lshl_add_u64 v[150:151], s[26:27], 0, v[138:139]
	s_add_i32 m0, s37, 0xc000
	ds_read_b128 v[194:197], v157
	ds_read_b128 v[198:201], v157 offset:1024
	ds_read_b128 v[202:205], v157 offset:2048
	ds_read_b128 v[206:209], v157 offset:3072
	ds_read_b128 v[210:213], v157 offset:4096
	ds_read_b128 v[214:217], v157 offset:5120
	ds_read_b128 v[218:221], v157 offset:6144
	ds_read_b128 v[222:225], v157 offset:7168
	global_load_lds_dwordx4 v[150:151], off
	v_lshl_add_u64 v[150:151], s[26:27], 0, v[140:141]
	s_add_i32 m0, s37, 0xe000
	s_nop 0
	global_load_lds_dwordx4 v[150:151], off
	s_waitcnt vmcnt(8)
	s_waitcnt lgkmcnt(0)
	s_barrier
	s_setprio 1
	s_waitcnt lgkmcnt(0)
	v_mfma_f32_16x16x32_bf16 v[126:129], v[146:149], v[194:197], v[126:129]
	v_mfma_f32_16x16x32_bf16 v[122:125], v[164:167], v[194:197], v[122:125]
	v_mfma_f32_16x16x32_bf16 v[110:113], v[146:149], v[202:205], v[110:113]
	v_mfma_f32_16x16x32_bf16 v[106:109], v[164:167], v[202:205], v[106:109]
	v_mfma_f32_16x16x32_bf16 v[94:97], v[146:149], v[210:213], v[94:97]
	v_mfma_f32_16x16x32_bf16 v[90:93], v[164:167], v[210:213], v[90:93]
	v_mfma_f32_16x16x32_bf16 v[78:81], v[146:149], v[218:221], v[78:81]
	v_mfma_f32_16x16x32_bf16 v[74:77], v[164:167], v[218:221], v[74:77]
	v_mfma_f32_16x16x32_bf16 v[126:129], v[160:163], v[198:201], v[126:129]
	v_mfma_f32_16x16x32_bf16 v[122:125], v[168:171], v[198:201], v[122:125]
	v_mfma_f32_16x16x32_bf16 v[110:113], v[160:163], v[206:209], v[110:113]
	v_mfma_f32_16x16x32_bf16 v[106:109], v[168:171], v[206:209], v[106:109]
	v_mfma_f32_16x16x32_bf16 v[94:97], v[160:163], v[214:217], v[94:97]
	v_mfma_f32_16x16x32_bf16 v[90:93], v[168:171], v[214:217], v[90:93]
	v_mfma_f32_16x16x32_bf16 v[78:81], v[160:163], v[222:225], v[78:81]
	v_mfma_f32_16x16x32_bf16 v[74:77], v[168:171], v[222:225], v[74:77]
	s_setprio 0
	s_setprio 1
	v_mfma_f32_16x16x32_bf16 v[118:121], v[178:181], v[194:197], v[118:121]
	v_mfma_f32_16x16x32_bf16 v[114:117], v[186:189], v[194:197], v[114:117]
	v_mfma_f32_16x16x32_bf16 v[102:105], v[178:181], v[202:205], v[102:105]
	v_mfma_f32_16x16x32_bf16 v[98:101], v[186:189], v[202:205], v[98:101]
	v_mfma_f32_16x16x32_bf16 v[86:89], v[178:181], v[210:213], v[86:89]
	v_mfma_f32_16x16x32_bf16 v[82:85], v[186:189], v[210:213], v[82:85]
	v_mfma_f32_16x16x32_bf16 v[70:73], v[178:181], v[218:221], v[70:73]
	v_mfma_f32_16x16x32_bf16 v[66:69], v[186:189], v[218:221], v[66:69]
	v_mfma_f32_16x16x32_bf16 v[118:121], v[182:185], v[198:201], v[118:121]
	v_mfma_f32_16x16x32_bf16 v[114:117], v[190:193], v[198:201], v[114:117]
	v_mfma_f32_16x16x32_bf16 v[102:105], v[182:185], v[206:209], v[102:105]
	v_mfma_f32_16x16x32_bf16 v[98:101], v[190:193], v[206:209], v[98:101]
	v_mfma_f32_16x16x32_bf16 v[86:89], v[182:185], v[214:217], v[86:89]
	v_mfma_f32_16x16x32_bf16 v[82:85], v[190:193], v[214:217], v[82:85]
	v_mfma_f32_16x16x32_bf16 v[70:73], v[182:185], v[222:225], v[70:73]
	v_mfma_f32_16x16x32_bf16 v[66:69], v[190:193], v[222:225], v[66:69]
	s_setprio 0
	s_barrier
	s_add_i32 s26, s45, s36
	v_lshl_add_u64 v[150:151], s[30:31], 0, v[132:133]
	s_mov_b32 m0, s26
	ds_read_b128 v[194:197], v157 offset:16384
	ds_read_b128 v[198:201], v157 offset:17408
	ds_read_b128 v[202:205], v157 offset:18432
	ds_read_b128 v[206:209], v157 offset:19456
	ds_read_b128 v[210:213], v157 offset:20480
	ds_read_b128 v[214:217], v157 offset:21504
	ds_read_b128 v[218:221], v157 offset:22528
	ds_read_b128 v[222:225], v157 offset:23552
	global_load_lds_dwordx4 v[150:151], off
	s_add_i32 m0, s26, 0x2000
	s_add_u32 s26, s30, 0x40000
	v_lshl_add_u64 v[172:173], s[30:31], 0, v[136:137]
	s_addc_u32 s27, s31, 0
	s_add_i32 s54, s46, s36
	global_load_lds_dwordx4 v[172:173], off
	v_lshl_add_u64 v[226:227], s[26:27], 0, v[132:133]
	s_mov_b32 m0, s54
	v_lshl_add_u64 v[228:229], s[34:35], 0, v[134:135]
	global_load_lds_dwordx4 v[226:227], off
	v_lshl_add_u64 v[226:227], s[26:27], 0, v[136:137]
	s_add_i32 m0, s54, 0x2000
	s_nop 0
	global_load_lds_dwordx4 v[226:227], off
	v_lshl_add_u64 v[226:227], s[34:35], 0, v[130:131]
	s_mov_b32 m0, s37
	s_nop 0
	global_load_lds_dwordx4 v[226:227], off
	s_mov_b32 m0, s38
	s_nop 0
	global_load_lds_dwordx4 v[228:229], off
	s_waitcnt vmcnt(8)
	s_waitcnt lgkmcnt(0)
	s_barrier
	s_setprio 1
	s_waitcnt lgkmcnt(0)
	v_mfma_f32_16x16x32_bf16 v[62:65], v[146:149], v[194:197], v[62:65]
	v_mfma_f32_16x16x32_bf16 v[58:61], v[164:167], v[194:197], v[58:61]
	v_mfma_f32_16x16x32_bf16 v[46:49], v[146:149], v[202:205], v[46:49]
	v_mfma_f32_16x16x32_bf16 v[42:45], v[164:167], v[202:205], v[42:45]
	v_mfma_f32_16x16x32_bf16 v[30:33], v[146:149], v[210:213], v[30:33]
	v_mfma_f32_16x16x32_bf16 v[26:29], v[164:167], v[210:213], v[26:29]
	v_mfma_f32_16x16x32_bf16 v[14:17], v[146:149], v[218:221], v[14:17]
	v_mfma_f32_16x16x32_bf16 v[10:13], v[164:167], v[218:221], v[10:13]
	v_mfma_f32_16x16x32_bf16 v[62:65], v[160:163], v[198:201], v[62:65]
	v_mfma_f32_16x16x32_bf16 v[58:61], v[168:171], v[198:201], v[58:61]
	v_mfma_f32_16x16x32_bf16 v[46:49], v[160:163], v[206:209], v[46:49]
	v_mfma_f32_16x16x32_bf16 v[42:45], v[168:171], v[206:209], v[42:45]
	v_mfma_f32_16x16x32_bf16 v[30:33], v[160:163], v[214:217], v[30:33]
	v_mfma_f32_16x16x32_bf16 v[26:29], v[168:171], v[214:217], v[26:29]
	v_mfma_f32_16x16x32_bf16 v[14:17], v[160:163], v[222:225], v[14:17]
	v_mfma_f32_16x16x32_bf16 v[10:13], v[168:171], v[222:225], v[10:13]
	s_setprio 0
	s_setprio 1
	v_mfma_f32_16x16x32_bf16 v[54:57], v[178:181], v[194:197], v[54:57]
	v_mfma_f32_16x16x32_bf16 v[50:53], v[186:189], v[194:197], v[50:53]
	v_mfma_f32_16x16x32_bf16 v[38:41], v[178:181], v[202:205], v[38:41]
	v_mfma_f32_16x16x32_bf16 v[34:37], v[186:189], v[202:205], v[34:37]
	v_mfma_f32_16x16x32_bf16 v[22:25], v[178:181], v[210:213], v[22:25]
	v_mfma_f32_16x16x32_bf16 v[18:21], v[186:189], v[210:213], v[18:21]
	v_mfma_f32_16x16x32_bf16 v[6:9], v[178:181], v[218:221], v[6:9]
	v_mfma_f32_16x16x32_bf16 v[2:5], v[186:189], v[218:221], v[2:5]
	v_mfma_f32_16x16x32_bf16 v[54:57], v[182:185], v[198:201], v[54:57]
	v_mfma_f32_16x16x32_bf16 v[50:53], v[190:193], v[198:201], v[50:53]
	v_mfma_f32_16x16x32_bf16 v[38:41], v[182:185], v[206:209], v[38:41]
	v_mfma_f32_16x16x32_bf16 v[34:37], v[190:193], v[206:209], v[34:37]
	v_mfma_f32_16x16x32_bf16 v[22:25], v[182:185], v[214:217], v[22:25]
	v_mfma_f32_16x16x32_bf16 v[18:21], v[190:193], v[214:217], v[18:21]
	v_mfma_f32_16x16x32_bf16 v[6:9], v[182:185], v[222:225], v[6:9]
	v_mfma_f32_16x16x32_bf16 v[2:5], v[190:193], v[222:225], v[2:5]
	s_setprio 0
	s_barrier
	s_add_i32 s54, 0, 0x18000
	s_add_i32 s55, 0, 0x1c000
	v_add_u32_e32 v168, s54, v153
	v_add_u32_e32 v177, s55, v153
	ds_read_b128 v[146:149], v168
	ds_read_b128 v[160:163], v168 offset:1024
	ds_read_b128 v[164:167], v168 offset:2048
	ds_read_b128 v[168:171], v168 offset:3072
	ds_read_b128 v[178:181], v177
	ds_read_b128 v[182:185], v177 offset:1024
	ds_read_b128 v[186:189], v177 offset:2048
	ds_read_b128 v[190:193], v177 offset:3072
	s_add_u32 s26, s34, 0x40000
	s_addc_u32 s27, s35, 0
	s_mov_b32 m0, s39
	v_lshl_add_u64 v[230:231], s[26:27], 0, v[130:131]
	ds_read_b128 v[194:197], v157 offset:32768
	ds_read_b128 v[198:201], v157 offset:33792
	ds_read_b128 v[202:205], v157 offset:34816
	ds_read_b128 v[206:209], v157 offset:35840
	ds_read_b128 v[210:213], v157 offset:36864
	ds_read_b128 v[214:217], v157 offset:37888
	ds_read_b128 v[218:221], v157 offset:38912
	ds_read_b128 v[222:225], v157 offset:39936
	global_load_lds_dwordx4 v[230:231], off
	v_lshl_add_u64 v[230:231], s[26:27], 0, v[134:135]
	s_mov_b32 m0, s40
	s_nop 0
	global_load_lds_dwordx4 v[230:231], off
	s_waitcnt vmcnt(8)
	s_waitcnt lgkmcnt(0)
	s_barrier
	s_setprio 1
	s_waitcnt lgkmcnt(0)
	v_mfma_f32_16x16x32_bf16 v[126:129], v[146:149], v[194:197], v[126:129]
	v_mfma_f32_16x16x32_bf16 v[122:125], v[164:167], v[194:197], v[122:125]
	v_mfma_f32_16x16x32_bf16 v[110:113], v[146:149], v[202:205], v[110:113]
	v_mfma_f32_16x16x32_bf16 v[106:109], v[164:167], v[202:205], v[106:109]
	v_mfma_f32_16x16x32_bf16 v[94:97], v[146:149], v[210:213], v[94:97]
	v_mfma_f32_16x16x32_bf16 v[90:93], v[164:167], v[210:213], v[90:93]
	v_mfma_f32_16x16x32_bf16 v[78:81], v[146:149], v[218:221], v[78:81]
	v_mfma_f32_16x16x32_bf16 v[74:77], v[164:167], v[218:221], v[74:77]
	v_mfma_f32_16x16x32_bf16 v[126:129], v[160:163], v[198:201], v[126:129]
	v_mfma_f32_16x16x32_bf16 v[122:125], v[168:171], v[198:201], v[122:125]
	v_mfma_f32_16x16x32_bf16 v[110:113], v[160:163], v[206:209], v[110:113]
	v_mfma_f32_16x16x32_bf16 v[106:109], v[168:171], v[206:209], v[106:109]
	v_mfma_f32_16x16x32_bf16 v[94:97], v[160:163], v[214:217], v[94:97]
	v_mfma_f32_16x16x32_bf16 v[90:93], v[168:171], v[214:217], v[90:93]
	v_mfma_f32_16x16x32_bf16 v[78:81], v[160:163], v[222:225], v[78:81]
	v_mfma_f32_16x16x32_bf16 v[74:77], v[168:171], v[222:225], v[74:77]
	s_setprio 0
	s_setprio 1
	v_mfma_f32_16x16x32_bf16 v[118:121], v[178:181], v[194:197], v[118:121]
	v_mfma_f32_16x16x32_bf16 v[114:117], v[186:189], v[194:197], v[114:117]
	v_mfma_f32_16x16x32_bf16 v[102:105], v[178:181], v[202:205], v[102:105]
	v_mfma_f32_16x16x32_bf16 v[98:101], v[186:189], v[202:205], v[98:101]
	v_mfma_f32_16x16x32_bf16 v[86:89], v[178:181], v[210:213], v[86:89]
	v_mfma_f32_16x16x32_bf16 v[82:85], v[186:189], v[210:213], v[82:85]
	v_mfma_f32_16x16x32_bf16 v[70:73], v[178:181], v[218:221], v[70:73]
	v_mfma_f32_16x16x32_bf16 v[66:69], v[186:189], v[218:221], v[66:69]
	v_mfma_f32_16x16x32_bf16 v[118:121], v[182:185], v[198:201], v[118:121]
	v_mfma_f32_16x16x32_bf16 v[114:117], v[190:193], v[198:201], v[114:117]
	v_mfma_f32_16x16x32_bf16 v[102:105], v[182:185], v[206:209], v[102:105]
	v_mfma_f32_16x16x32_bf16 v[98:101], v[190:193], v[206:209], v[98:101]
	v_mfma_f32_16x16x32_bf16 v[86:89], v[182:185], v[214:217], v[86:89]
	v_mfma_f32_16x16x32_bf16 v[82:85], v[190:193], v[214:217], v[82:85]
	v_mfma_f32_16x16x32_bf16 v[70:73], v[182:185], v[222:225], v[70:73]
	v_mfma_f32_16x16x32_bf16 v[66:69], v[190:193], v[222:225], v[66:69]
	s_setprio 0
	s_barrier
	s_add_i32 s26, s54, s36
	v_lshl_add_u64 v[150:151], v[150:151], 0, s[10:11]
	s_mov_b32 m0, s26
	ds_read_b128 v[194:197], v157 offset:49152
	ds_read_b128 v[198:201], v157 offset:50176
	ds_read_b128 v[202:205], v157 offset:51200
	ds_read_b128 v[206:209], v157 offset:52224
	ds_read_b128 v[210:213], v157 offset:53248
	ds_read_b128 v[214:217], v157 offset:54272
	ds_read_b128 v[218:221], v157 offset:55296
	ds_read_b128 v[222:225], v157 offset:56320
	global_load_lds_dwordx4 v[150:151], off
	s_add_i32 m0, s26, 0x2000
	s_add_u32 s26, s30, 0x40080
	v_lshl_add_u64 v[150:151], v[172:173], 0, s[10:11]
	s_addc_u32 s27, s31, 0
	s_add_i32 s30, s55, s36
	global_load_lds_dwordx4 v[150:151], off
	v_lshl_add_u64 v[150:151], s[26:27], 0, v[132:133]
	s_mov_b32 m0, s30
	s_nop 0
	global_load_lds_dwordx4 v[150:151], off
	v_lshl_add_u64 v[150:151], s[26:27], 0, v[136:137]
	s_add_i32 m0, s30, 0x2000
	s_nop 0
	global_load_lds_dwordx4 v[150:151], off
	v_lshl_add_u64 v[150:151], v[226:227], 0, s[10:11]
	s_mov_b32 m0, s42
	s_nop 0
	global_load_lds_dwordx4 v[150:151], off
	v_lshl_add_u64 v[150:151], v[228:229], 0, s[10:11]
	s_mov_b32 m0, s43
	s_nop 0
	global_load_lds_dwordx4 v[150:151], off
	s_waitcnt vmcnt(8)
	s_waitcnt lgkmcnt(0)
	s_barrier
	s_setprio 1
	s_waitcnt lgkmcnt(0)
	v_mfma_f32_16x16x32_bf16 v[62:65], v[146:149], v[194:197], v[62:65]
	v_mfma_f32_16x16x32_bf16 v[58:61], v[164:167], v[194:197], v[58:61]
	v_mfma_f32_16x16x32_bf16 v[46:49], v[146:149], v[202:205], v[46:49]
	v_mfma_f32_16x16x32_bf16 v[42:45], v[164:167], v[202:205], v[42:45]
	v_mfma_f32_16x16x32_bf16 v[30:33], v[146:149], v[210:213], v[30:33]
	v_mfma_f32_16x16x32_bf16 v[26:29], v[164:167], v[210:213], v[26:29]
	v_mfma_f32_16x16x32_bf16 v[14:17], v[146:149], v[218:221], v[14:17]
	v_mfma_f32_16x16x32_bf16 v[10:13], v[164:167], v[218:221], v[10:13]
	v_mfma_f32_16x16x32_bf16 v[62:65], v[160:163], v[198:201], v[62:65]
	v_mfma_f32_16x16x32_bf16 v[58:61], v[168:171], v[198:201], v[58:61]
	v_mfma_f32_16x16x32_bf16 v[46:49], v[160:163], v[206:209], v[46:49]
	v_mfma_f32_16x16x32_bf16 v[42:45], v[168:171], v[206:209], v[42:45]
	v_mfma_f32_16x16x32_bf16 v[30:33], v[160:163], v[214:217], v[30:33]
	v_mfma_f32_16x16x32_bf16 v[26:29], v[168:171], v[214:217], v[26:29]
	v_mfma_f32_16x16x32_bf16 v[14:17], v[160:163], v[222:225], v[14:17]
	v_mfma_f32_16x16x32_bf16 v[10:13], v[168:171], v[222:225], v[10:13]
	s_setprio 0
	s_setprio 1
	v_mfma_f32_16x16x32_bf16 v[54:57], v[178:181], v[194:197], v[54:57]
	v_mfma_f32_16x16x32_bf16 v[50:53], v[186:189], v[194:197], v[50:53]
	v_mfma_f32_16x16x32_bf16 v[38:41], v[178:181], v[202:205], v[38:41]
	v_mfma_f32_16x16x32_bf16 v[34:37], v[186:189], v[202:205], v[34:37]
	v_mfma_f32_16x16x32_bf16 v[22:25], v[178:181], v[210:213], v[22:25]
	v_mfma_f32_16x16x32_bf16 v[18:21], v[186:189], v[210:213], v[18:21]
	v_mfma_f32_16x16x32_bf16 v[6:9], v[178:181], v[218:221], v[6:9]
	v_mfma_f32_16x16x32_bf16 v[2:5], v[186:189], v[218:221], v[2:5]
	v_mfma_f32_16x16x32_bf16 v[54:57], v[182:185], v[198:201], v[54:57]
	v_mfma_f32_16x16x32_bf16 v[50:53], v[190:193], v[198:201], v[50:53]
	v_mfma_f32_16x16x32_bf16 v[38:41], v[182:185], v[206:209], v[38:41]
	v_mfma_f32_16x16x32_bf16 v[34:37], v[190:193], v[206:209], v[34:37]
	v_mfma_f32_16x16x32_bf16 v[22:25], v[182:185], v[214:217], v[22:25]
	v_mfma_f32_16x16x32_bf16 v[18:21], v[190:193], v[214:217], v[18:21]
	v_mfma_f32_16x16x32_bf16 v[6:9], v[182:185], v[222:225], v[6:9]
	v_mfma_f32_16x16x32_bf16 v[2:5], v[190:193], v[222:225], v[2:5]
	s_setprio 0
	s_add_i32 s53, s53, 2
	s_add_u32 s51, s51, 0x100
	s_addc_u32 s52, s52, 0
	s_cmp_gt_u32 s53, 13
	s_mov_b64 s[26:27], s[28:29]
	s_barrier
	s_cbranch_scc0 .LBB0_1590

.LBB0_1683:
	s_add_u32 s49, s28, 0x100
	s_addc_u32 s50, s29, 0
	s_mov_b32 s51, -2
	s_waitcnt lgkmcnt(0)
	ds_read_b128 v[144:147], v151
	ds_read_b128 v[156:159], v151 offset:1024
	ds_read_b128 v[160:163], v151 offset:2048
	ds_read_b128 v[164:167], v151 offset:3072
	ds_read_b128 v[168:171], v152
	ds_read_b128 v[176:179], v152 offset:1024
	ds_read_b128 v[180:183], v152 offset:2048
	ds_read_b128 v[184:187], v152 offset:3072
	s_add_u32 s28, s26, 0x100
	s_addc_u32 s29, s27, 0
	s_cmp_eq_u32 s51, 40
	s_cselect_b32 s35, s7, s29
	s_cselect_b32 s34, s6, s28
	s_cselect_b32 s31, s25, s50
	s_cselect_b32 s30, s24, s49
	v_lshl_add_u64 v[172:173], s[26:27], 0, v[136:137]
	s_add_i32 m0, s16, 0xc000
	ds_read_b128 v[188:191], v153
	ds_read_b128 v[192:195], v153 offset:1024
	ds_read_b128 v[196:199], v153 offset:2048
	ds_read_b128 v[200:203], v153 offset:3072
	ds_read_b128 v[204:207], v153 offset:4096
	ds_read_b128 v[208:211], v153 offset:5120
	ds_read_b128 v[212:215], v153 offset:6144
	ds_read_b128 v[216:219], v153 offset:7168
	global_load_lds_dwordx4 v[172:173], off
	v_lshl_add_u64 v[172:173], s[26:27], 0, v[138:139]
	s_add_i32 m0, s16, 0xe000
	s_nop 0
	global_load_lds_dwordx4 v[172:173], off
	s_waitcnt vmcnt(8)
	s_waitcnt lgkmcnt(0)
	s_barrier
	s_setprio 1
	s_waitcnt lgkmcnt(0)
	v_mfma_f32_16x16x32_bf16 v[124:127], v[144:147], v[188:191], 0
	v_mfma_f32_16x16x32_bf16 v[120:123], v[160:163], v[188:191], 0
	v_mfma_f32_16x16x32_bf16 v[108:111], v[144:147], v[196:199], 0
	v_mfma_f32_16x16x32_bf16 v[104:107], v[160:163], v[196:199], 0
	v_mfma_f32_16x16x32_bf16 v[92:95], v[144:147], v[204:207], 0
	v_mfma_f32_16x16x32_bf16 v[88:91], v[160:163], v[204:207], 0
	v_mfma_f32_16x16x32_bf16 v[76:79], v[144:147], v[212:215], 0
	v_mfma_f32_16x16x32_bf16 v[72:75], v[160:163], v[212:215], 0
	v_mfma_f32_16x16x32_bf16 v[124:127], v[156:159], v[192:195], v[124:127]
	v_mfma_f32_16x16x32_bf16 v[120:123], v[164:167], v[192:195], v[120:123]
	v_mfma_f32_16x16x32_bf16 v[108:111], v[156:159], v[200:203], v[108:111]
	v_mfma_f32_16x16x32_bf16 v[104:107], v[164:167], v[200:203], v[104:107]
	v_mfma_f32_16x16x32_bf16 v[92:95], v[156:159], v[208:211], v[92:95]
	v_mfma_f32_16x16x32_bf16 v[88:91], v[164:167], v[208:211], v[88:91]
	v_mfma_f32_16x16x32_bf16 v[76:79], v[156:159], v[216:219], v[76:79]
	v_mfma_f32_16x16x32_bf16 v[72:75], v[164:167], v[216:219], v[72:75]
	s_setprio 0
	s_setprio 1
	v_mfma_f32_16x16x32_bf16 v[116:119], v[168:171], v[188:191], 0
	v_mfma_f32_16x16x32_bf16 v[112:115], v[180:183], v[188:191], 0
	v_mfma_f32_16x16x32_bf16 v[100:103], v[168:171], v[196:199], 0
	v_mfma_f32_16x16x32_bf16 v[96:99], v[180:183], v[196:199], 0
	v_mfma_f32_16x16x32_bf16 v[84:87], v[168:171], v[204:207], 0
	v_mfma_f32_16x16x32_bf16 v[80:83], v[180:183], v[204:207], 0
	v_mfma_f32_16x16x32_bf16 v[68:71], v[168:171], v[212:215], 0
	v_mfma_f32_16x16x32_bf16 v[64:67], v[180:183], v[212:215], 0
	v_mfma_f32_16x16x32_bf16 v[116:119], v[176:179], v[192:195], v[116:119]
	v_mfma_f32_16x16x32_bf16 v[112:115], v[184:187], v[192:195], v[112:115]
	v_mfma_f32_16x16x32_bf16 v[100:103], v[176:179], v[200:203], v[100:103]
	v_mfma_f32_16x16x32_bf16 v[96:99], v[184:187], v[200:203], v[96:99]
	v_mfma_f32_16x16x32_bf16 v[84:87], v[176:179], v[208:211], v[84:87]
	v_mfma_f32_16x16x32_bf16 v[80:83], v[184:187], v[208:211], v[80:83]
	v_mfma_f32_16x16x32_bf16 v[68:71], v[176:179], v[216:219], v[68:71]
	v_mfma_f32_16x16x32_bf16 v[64:67], v[184:187], v[216:219], v[64:67]
	s_setprio 0
	s_barrier
	s_add_i32 s26, s43, s15
	v_lshl_add_u64 v[172:173], s[30:31], 0, v[130:131]
	s_mov_b32 m0, s26
	ds_read_b128 v[188:191], v153 offset:16384
	ds_read_b128 v[192:195], v153 offset:17408
	ds_read_b128 v[196:199], v153 offset:18432
	ds_read_b128 v[200:203], v153 offset:19456
	ds_read_b128 v[204:207], v153 offset:20480
	ds_read_b128 v[208:211], v153 offset:21504
	ds_read_b128 v[212:215], v153 offset:22528
	ds_read_b128 v[216:219], v153 offset:23552
	global_load_lds_dwordx4 v[172:173], off
	s_add_i32 m0, s26, 0x2000
	s_add_u32 s26, s30, 0xb0000
	v_lshl_add_u64 v[220:221], s[30:31], 0, v[134:135]
	s_addc_u32 s27, s31, 0
	s_add_i32 s52, s44, s15
	global_load_lds_dwordx4 v[220:221], off
	v_lshl_add_u64 v[222:223], s[26:27], 0, v[130:131]
	s_mov_b32 m0, s52
	v_lshl_add_u64 v[224:225], s[34:35], 0, v[132:133]
	global_load_lds_dwordx4 v[222:223], off
	v_lshl_add_u64 v[222:223], s[26:27], 0, v[134:135]
	s_add_i32 m0, s52, 0x2000
	s_nop 0
	global_load_lds_dwordx4 v[222:223], off
	v_lshl_add_u64 v[222:223], s[34:35], 0, v[128:129]
	s_mov_b32 m0, s16
	s_nop 0
	global_load_lds_dwordx4 v[222:223], off
	s_mov_b32 m0, s17
	s_nop 0
	global_load_lds_dwordx4 v[224:225], off
	s_waitcnt vmcnt(8)
	s_waitcnt lgkmcnt(0)
	s_barrier
	s_setprio 1
	s_waitcnt lgkmcnt(0)
	v_mfma_f32_16x16x32_bf16 v[60:63], v[144:147], v[188:191], 0
	v_mfma_f32_16x16x32_bf16 v[56:59], v[160:163], v[188:191], 0
	v_mfma_f32_16x16x32_bf16 v[44:47], v[144:147], v[196:199], 0
	v_mfma_f32_16x16x32_bf16 v[40:43], v[160:163], v[196:199], 0
	v_mfma_f32_16x16x32_bf16 v[28:31], v[144:147], v[204:207], 0
	v_mfma_f32_16x16x32_bf16 v[24:27], v[160:163], v[204:207], 0
	v_mfma_f32_16x16x32_bf16 v[12:15], v[144:147], v[212:215], 0
	v_mfma_f32_16x16x32_bf16 v[8:11], v[160:163], v[212:215], 0
	v_mfma_f32_16x16x32_bf16 v[60:63], v[156:159], v[192:195], v[60:63]
	v_mfma_f32_16x16x32_bf16 v[56:59], v[164:167], v[192:195], v[56:59]
	v_mfma_f32_16x16x32_bf16 v[44:47], v[156:159], v[200:203], v[44:47]
	v_mfma_f32_16x16x32_bf16 v[40:43], v[164:167], v[200:203], v[40:43]
	v_mfma_f32_16x16x32_bf16 v[28:31], v[156:159], v[208:211], v[28:31]
	v_mfma_f32_16x16x32_bf16 v[24:27], v[164:167], v[208:211], v[24:27]
	v_mfma_f32_16x16x32_bf16 v[12:15], v[156:159], v[216:219], v[12:15]
	v_mfma_f32_16x16x32_bf16 v[8:11], v[164:167], v[216:219], v[8:11]
	s_setprio 0
	s_setprio 1
	v_mfma_f32_16x16x32_bf16 v[52:55], v[168:171], v[188:191], 0
	v_mfma_f32_16x16x32_bf16 v[48:51], v[180:183], v[188:191], 0
	v_mfma_f32_16x16x32_bf16 v[36:39], v[168:171], v[196:199], 0
	v_mfma_f32_16x16x32_bf16 v[32:35], v[180:183], v[196:199], 0
	v_mfma_f32_16x16x32_bf16 v[20:23], v[168:171], v[204:207], 0
	v_mfma_f32_16x16x32_bf16 v[16:19], v[180:183], v[204:207], 0
	v_mfma_f32_16x16x32_bf16 v[4:7], v[168:171], v[212:215], 0
	v_mfma_f32_16x16x32_bf16 v[0:3], v[180:183], v[212:215], 0
	v_mfma_f32_16x16x32_bf16 v[52:55], v[176:179], v[192:195], v[52:55]
	v_mfma_f32_16x16x32_bf16 v[48:51], v[184:187], v[192:195], v[48:51]
	v_mfma_f32_16x16x32_bf16 v[36:39], v[176:179], v[200:203], v[36:39]
	v_mfma_f32_16x16x32_bf16 v[32:35], v[184:187], v[200:203], v[32:35]
	v_mfma_f32_16x16x32_bf16 v[20:23], v[176:179], v[208:211], v[20:23]
	v_mfma_f32_16x16x32_bf16 v[16:19], v[184:187], v[208:211], v[16:19]
	v_mfma_f32_16x16x32_bf16 v[4:7], v[176:179], v[216:219], v[4:7]
	v_mfma_f32_16x16x32_bf16 v[0:3], v[184:187], v[216:219], v[0:3]
	s_setprio 0
	s_barrier
	s_add_i32 s52, 0, 0x18000
	v_add_u32_e32 v155, s52, v149
	s_add_i32 s53, 0, 0x1c000
	ds_read_b128 v[144:147], v155
	ds_read_b128 v[156:159], v155 offset:1024
	ds_read_b128 v[160:163], v155 offset:2048
	ds_read_b128 v[164:167], v155 offset:3072
	v_add_u32_e32 v155, s53, v149
	ds_read_b128 v[168:171], v155
	ds_read_b128 v[176:179], v155 offset:1024
	ds_read_b128 v[180:183], v155 offset:2048
	ds_read_b128 v[184:187], v155 offset:3072
	s_add_u32 s26, s34, 0xb0000
	s_addc_u32 s27, s35, 0
	s_mov_b32 m0, s36
	v_lshl_add_u64 v[226:227], s[26:27], 0, v[128:129]
	ds_read_b128 v[188:191], v153 offset:32768
	ds_read_b128 v[192:195], v153 offset:33792
	ds_read_b128 v[196:199], v153 offset:34816
	ds_read_b128 v[200:203], v153 offset:35840
	ds_read_b128 v[204:207], v153 offset:36864
	ds_read_b128 v[208:211], v153 offset:37888
	ds_read_b128 v[212:215], v153 offset:38912
	ds_read_b128 v[216:219], v153 offset:39936
	global_load_lds_dwordx4 v[226:227], off
	v_lshl_add_u64 v[226:227], s[26:27], 0, v[132:133]
	s_mov_b32 m0, s37
	s_nop 0
	global_load_lds_dwordx4 v[226:227], off
	s_waitcnt vmcnt(8)
	s_waitcnt lgkmcnt(0)
	s_barrier
	s_setprio 1
	s_waitcnt lgkmcnt(0)
	v_mfma_f32_16x16x32_bf16 v[124:127], v[144:147], v[188:191], v[124:127]
	v_mfma_f32_16x16x32_bf16 v[120:123], v[160:163], v[188:191], v[120:123]
	v_mfma_f32_16x16x32_bf16 v[108:111], v[144:147], v[196:199], v[108:111]
	v_mfma_f32_16x16x32_bf16 v[104:107], v[160:163], v[196:199], v[104:107]
	v_mfma_f32_16x16x32_bf16 v[92:95], v[144:147], v[204:207], v[92:95]
	v_mfma_f32_16x16x32_bf16 v[88:91], v[160:163], v[204:207], v[88:91]
	v_mfma_f32_16x16x32_bf16 v[76:79], v[144:147], v[212:215], v[76:79]
	v_mfma_f32_16x16x32_bf16 v[72:75], v[160:163], v[212:215], v[72:75]
	v_mfma_f32_16x16x32_bf16 v[124:127], v[156:159], v[192:195], v[124:127]
	v_mfma_f32_16x16x32_bf16 v[120:123], v[164:167], v[192:195], v[120:123]
	v_mfma_f32_16x16x32_bf16 v[108:111], v[156:159], v[200:203], v[108:111]
	v_mfma_f32_16x16x32_bf16 v[104:107], v[164:167], v[200:203], v[104:107]
	v_mfma_f32_16x16x32_bf16 v[92:95], v[156:159], v[208:211], v[92:95]
	v_mfma_f32_16x16x32_bf16 v[88:91], v[164:167], v[208:211], v[88:91]
	v_mfma_f32_16x16x32_bf16 v[76:79], v[156:159], v[216:219], v[76:79]
	v_mfma_f32_16x16x32_bf16 v[72:75], v[164:167], v[216:219], v[72:75]
	s_setprio 0
	s_setprio 1
	v_mfma_f32_16x16x32_bf16 v[116:119], v[168:171], v[188:191], v[116:119]
	v_mfma_f32_16x16x32_bf16 v[112:115], v[180:183], v[188:191], v[112:115]
	v_mfma_f32_16x16x32_bf16 v[100:103], v[168:171], v[196:199], v[100:103]
	v_mfma_f32_16x16x32_bf16 v[96:99], v[180:183], v[196:199], v[96:99]
	v_mfma_f32_16x16x32_bf16 v[84:87], v[168:171], v[204:207], v[84:87]
	v_mfma_f32_16x16x32_bf16 v[80:83], v[180:183], v[204:207], v[80:83]
	v_mfma_f32_16x16x32_bf16 v[68:71], v[168:171], v[212:215], v[68:71]
	v_mfma_f32_16x16x32_bf16 v[64:67], v[180:183], v[212:215], v[64:67]
	v_mfma_f32_16x16x32_bf16 v[116:119], v[176:179], v[192:195], v[116:119]
	v_mfma_f32_16x16x32_bf16 v[112:115], v[184:187], v[192:195], v[112:115]
	v_mfma_f32_16x16x32_bf16 v[100:103], v[176:179], v[200:203], v[100:103]
	v_mfma_f32_16x16x32_bf16 v[96:99], v[184:187], v[200:203], v[96:99]
	v_mfma_f32_16x16x32_bf16 v[84:87], v[176:179], v[208:211], v[84:87]
	v_mfma_f32_16x16x32_bf16 v[80:83], v[184:187], v[208:211], v[80:83]
	v_mfma_f32_16x16x32_bf16 v[68:71], v[176:179], v[216:219], v[68:71]
	v_mfma_f32_16x16x32_bf16 v[64:67], v[184:187], v[216:219], v[64:67]
	s_setprio 0
	s_barrier
	s_add_i32 s26, s52, s15
	v_lshl_add_u64 v[172:173], v[172:173], 0, s[20:21]
	s_mov_b32 m0, s26
	ds_read_b128 v[188:191], v153 offset:49152
	ds_read_b128 v[192:195], v153 offset:50176
	ds_read_b128 v[196:199], v153 offset:51200
	ds_read_b128 v[200:203], v153 offset:52224
	ds_read_b128 v[204:207], v153 offset:53248
	ds_read_b128 v[208:211], v153 offset:54272
	ds_read_b128 v[212:215], v153 offset:55296
	ds_read_b128 v[216:219], v153 offset:56320
	global_load_lds_dwordx4 v[172:173], off
	s_add_i32 m0, s26, 0x2000
	s_add_u32 s26, s30, 0xb0080
	v_lshl_add_u64 v[172:173], v[220:221], 0, s[20:21]
	s_addc_u32 s27, s31, 0
	s_add_i32 s30, s53, s15
	global_load_lds_dwordx4 v[172:173], off
	v_lshl_add_u64 v[172:173], s[26:27], 0, v[130:131]
	s_mov_b32 m0, s30
	s_nop 0
	global_load_lds_dwordx4 v[172:173], off
	v_lshl_add_u64 v[172:173], s[26:27], 0, v[134:135]
	s_add_i32 m0, s30, 0x2000
	s_nop 0
	global_load_lds_dwordx4 v[172:173], off
	v_lshl_add_u64 v[172:173], v[222:223], 0, s[20:21]
	s_mov_b32 m0, s39
	s_nop 0
	global_load_lds_dwordx4 v[172:173], off
	v_lshl_add_u64 v[172:173], v[224:225], 0, s[20:21]
	s_mov_b32 m0, s40
	s_nop 0
	global_load_lds_dwordx4 v[172:173], off
	s_waitcnt vmcnt(8)
	s_waitcnt lgkmcnt(0)
	s_barrier
	s_setprio 1
	s_waitcnt lgkmcnt(0)
	v_mfma_f32_16x16x32_bf16 v[60:63], v[144:147], v[188:191], v[60:63]
	v_mfma_f32_16x16x32_bf16 v[56:59], v[160:163], v[188:191], v[56:59]
	v_mfma_f32_16x16x32_bf16 v[44:47], v[144:147], v[196:199], v[44:47]
	v_mfma_f32_16x16x32_bf16 v[40:43], v[160:163], v[196:199], v[40:43]
	v_mfma_f32_16x16x32_bf16 v[28:31], v[144:147], v[204:207], v[28:31]
	v_mfma_f32_16x16x32_bf16 v[24:27], v[160:163], v[204:207], v[24:27]
	v_mfma_f32_16x16x32_bf16 v[12:15], v[144:147], v[212:215], v[12:15]
	v_mfma_f32_16x16x32_bf16 v[8:11], v[160:163], v[212:215], v[8:11]
	v_mfma_f32_16x16x32_bf16 v[60:63], v[156:159], v[192:195], v[60:63]
	v_mfma_f32_16x16x32_bf16 v[56:59], v[164:167], v[192:195], v[56:59]
	v_mfma_f32_16x16x32_bf16 v[44:47], v[156:159], v[200:203], v[44:47]
	v_mfma_f32_16x16x32_bf16 v[40:43], v[164:167], v[200:203], v[40:43]
	v_mfma_f32_16x16x32_bf16 v[28:31], v[156:159], v[208:211], v[28:31]
	v_mfma_f32_16x16x32_bf16 v[24:27], v[164:167], v[208:211], v[24:27]
	v_mfma_f32_16x16x32_bf16 v[12:15], v[156:159], v[216:219], v[12:15]
	v_mfma_f32_16x16x32_bf16 v[8:11], v[164:167], v[216:219], v[8:11]
	s_setprio 0
	s_setprio 1
	v_mfma_f32_16x16x32_bf16 v[52:55], v[168:171], v[188:191], v[52:55]
	v_mfma_f32_16x16x32_bf16 v[48:51], v[180:183], v[188:191], v[48:51]
	v_mfma_f32_16x16x32_bf16 v[36:39], v[168:171], v[196:199], v[36:39]
	v_mfma_f32_16x16x32_bf16 v[32:35], v[180:183], v[196:199], v[32:35]
	v_mfma_f32_16x16x32_bf16 v[20:23], v[168:171], v[204:207], v[20:23]
	v_mfma_f32_16x16x32_bf16 v[16:19], v[180:183], v[204:207], v[16:19]
	v_mfma_f32_16x16x32_bf16 v[4:7], v[168:171], v[212:215], v[4:7]
	v_mfma_f32_16x16x32_bf16 v[0:3], v[180:183], v[212:215], v[0:3]
	v_mfma_f32_16x16x32_bf16 v[52:55], v[176:179], v[192:195], v[52:55]
	v_mfma_f32_16x16x32_bf16 v[48:51], v[184:187], v[192:195], v[48:51]
	v_mfma_f32_16x16x32_bf16 v[36:39], v[176:179], v[200:203], v[36:39]
	v_mfma_f32_16x16x32_bf16 v[32:35], v[184:187], v[200:203], v[32:35]
	v_mfma_f32_16x16x32_bf16 v[20:23], v[176:179], v[208:211], v[20:23]
	v_mfma_f32_16x16x32_bf16 v[16:19], v[184:187], v[208:211], v[16:19]
	v_mfma_f32_16x16x32_bf16 v[4:7], v[176:179], v[216:219], v[4:7]
	v_mfma_f32_16x16x32_bf16 v[0:3], v[184:187], v[216:219], v[0:3]
	s_setprio 0
	s_add_i32 s51, s51, 2
	s_add_u32 s49, s49, 0x100
	s_addc_u32 s50, s50, 0
	s_cmp_gt_u32 s51, 41
	s_mov_b64 s[26:27], s[28:29]
	s_barrier
	s_cbranch_scc0 .LBB0_1684
	s_branch .Lpeel_exit_1684
.LBB0_1684:
	ds_read_b128 v[144:147], v151
	ds_read_b128 v[156:159], v151 offset:1024
	ds_read_b128 v[160:163], v151 offset:2048
	ds_read_b128 v[164:167], v151 offset:3072
	ds_read_b128 v[168:171], v152
	ds_read_b128 v[176:179], v152 offset:1024
	ds_read_b128 v[180:183], v152 offset:2048
	ds_read_b128 v[184:187], v152 offset:3072
	s_add_u32 s28, s26, 0x100
	s_addc_u32 s29, s27, 0
	s_cmp_eq_u32 s51, 40
	s_cselect_b32 s35, s7, s29
	s_cselect_b32 s34, s6, s28
	s_cselect_b32 s31, s25, s50
	s_cselect_b32 s30, s24, s49
	v_lshl_add_u64 v[172:173], s[26:27], 0, v[136:137]
	s_add_i32 m0, s16, 0xc000
	ds_read_b128 v[188:191], v153
	ds_read_b128 v[192:195], v153 offset:1024
	ds_read_b128 v[196:199], v153 offset:2048
	ds_read_b128 v[200:203], v153 offset:3072
	ds_read_b128 v[204:207], v153 offset:4096
	ds_read_b128 v[208:211], v153 offset:5120
	ds_read_b128 v[212:215], v153 offset:6144
	ds_read_b128 v[216:219], v153 offset:7168
	global_load_lds_dwordx4 v[172:173], off
	v_lshl_add_u64 v[172:173], s[26:27], 0, v[138:139]
	s_add_i32 m0, s16, 0xe000
	s_nop 0
	global_load_lds_dwordx4 v[172:173], off
	s_waitcnt vmcnt(8)
	s_waitcnt lgkmcnt(0)
	s_barrier
	s_setprio 1
	s_waitcnt lgkmcnt(0)
	v_mfma_f32_16x16x32_bf16 v[124:127], v[144:147], v[188:191], v[124:127]
	v_mfma_f32_16x16x32_bf16 v[120:123], v[160:163], v[188:191], v[120:123]
	v_mfma_f32_16x16x32_bf16 v[108:111], v[144:147], v[196:199], v[108:111]
	v_mfma_f32_16x16x32_bf16 v[104:107], v[160:163], v[196:199], v[104:107]
	v_mfma_f32_16x16x32_bf16 v[92:95], v[144:147], v[204:207], v[92:95]
	v_mfma_f32_16x16x32_bf16 v[88:91], v[160:163], v[204:207], v[88:91]
	v_mfma_f32_16x16x32_bf16 v[76:79], v[144:147], v[212:215], v[76:79]
	v_mfma_f32_16x16x32_bf16 v[72:75], v[160:163], v[212:215], v[72:75]
	v_mfma_f32_16x16x32_bf16 v[124:127], v[156:159], v[192:195], v[124:127]
	v_mfma_f32_16x16x32_bf16 v[120:123], v[164:167], v[192:195], v[120:123]
	v_mfma_f32_16x16x32_bf16 v[108:111], v[156:159], v[200:203], v[108:111]
	v_mfma_f32_16x16x32_bf16 v[104:107], v[164:167], v[200:203], v[104:107]
	v_mfma_f32_16x16x32_bf16 v[92:95], v[156:159], v[208:211], v[92:95]
	v_mfma_f32_16x16x32_bf16 v[88:91], v[164:167], v[208:211], v[88:91]
	v_mfma_f32_16x16x32_bf16 v[76:79], v[156:159], v[216:219], v[76:79]
	v_mfma_f32_16x16x32_bf16 v[72:75], v[164:167], v[216:219], v[72:75]
	s_setprio 0
	s_setprio 1
	v_mfma_f32_16x16x32_bf16 v[116:119], v[168:171], v[188:191], v[116:119]
	v_mfma_f32_16x16x32_bf16 v[112:115], v[180:183], v[188:191], v[112:115]
	v_mfma_f32_16x16x32_bf16 v[100:103], v[168:171], v[196:199], v[100:103]
	v_mfma_f32_16x16x32_bf16 v[96:99], v[180:183], v[196:199], v[96:99]
	v_mfma_f32_16x16x32_bf16 v[84:87], v[168:171], v[204:207], v[84:87]
	v_mfma_f32_16x16x32_bf16 v[80:83], v[180:183], v[204:207], v[80:83]
	v_mfma_f32_16x16x32_bf16 v[68:71], v[168:171], v[212:215], v[68:71]
	v_mfma_f32_16x16x32_bf16 v[64:67], v[180:183], v[212:215], v[64:67]
	v_mfma_f32_16x16x32_bf16 v[116:119], v[176:179], v[192:195], v[116:119]
	v_mfma_f32_16x16x32_bf16 v[112:115], v[184:187], v[192:195], v[112:115]
	v_mfma_f32_16x16x32_bf16 v[100:103], v[176:179], v[200:203], v[100:103]
	v_mfma_f32_16x16x32_bf16 v[96:99], v[184:187], v[200:203], v[96:99]
	v_mfma_f32_16x16x32_bf16 v[84:87], v[176:179], v[208:211], v[84:87]
	v_mfma_f32_16x16x32_bf16 v[80:83], v[184:187], v[208:211], v[80:83]
	v_mfma_f32_16x16x32_bf16 v[68:71], v[176:179], v[216:219], v[68:71]
	v_mfma_f32_16x16x32_bf16 v[64:67], v[184:187], v[216:219], v[64:67]
	s_setprio 0
	s_barrier
	s_add_i32 s26, s43, s15
	v_lshl_add_u64 v[172:173], s[30:31], 0, v[130:131]
	s_mov_b32 m0, s26
	ds_read_b128 v[188:191], v153 offset:16384
	ds_read_b128 v[192:195], v153 offset:17408
	ds_read_b128 v[196:199], v153 offset:18432
	ds_read_b128 v[200:203], v153 offset:19456
	ds_read_b128 v[204:207], v153 offset:20480
	ds_read_b128 v[208:211], v153 offset:21504
	ds_read_b128 v[212:215], v153 offset:22528
	ds_read_b128 v[216:219], v153 offset:23552
	global_load_lds_dwordx4 v[172:173], off
	s_add_i32 m0, s26, 0x2000
	s_add_u32 s26, s30, 0xb0000
	v_lshl_add_u64 v[220:221], s[30:31], 0, v[134:135]
	s_addc_u32 s27, s31, 0
	s_add_i32 s52, s44, s15
	global_load_lds_dwordx4 v[220:221], off
	v_lshl_add_u64 v[222:223], s[26:27], 0, v[130:131]
	s_mov_b32 m0, s52
	v_lshl_add_u64 v[224:225], s[34:35], 0, v[132:133]
	global_load_lds_dwordx4 v[222:223], off
	v_lshl_add_u64 v[222:223], s[26:27], 0, v[134:135]
	s_add_i32 m0, s52, 0x2000
	s_nop 0
	global_load_lds_dwordx4 v[222:223], off
	v_lshl_add_u64 v[222:223], s[34:35], 0, v[128:129]
	s_mov_b32 m0, s16
	s_nop 0
	global_load_lds_dwordx4 v[222:223], off
	s_mov_b32 m0, s17
	s_nop 0
	global_load_lds_dwordx4 v[224:225], off
	s_waitcnt vmcnt(8)
	s_waitcnt lgkmcnt(0)
	s_barrier
	s_setprio 1
	s_waitcnt lgkmcnt(0)
	v_mfma_f32_16x16x32_bf16 v[60:63], v[144:147], v[188:191], v[60:63]
	v_mfma_f32_16x16x32_bf16 v[56:59], v[160:163], v[188:191], v[56:59]
	v_mfma_f32_16x16x32_bf16 v[44:47], v[144:147], v[196:199], v[44:47]
	v_mfma_f32_16x16x32_bf16 v[40:43], v[160:163], v[196:199], v[40:43]
	v_mfma_f32_16x16x32_bf16 v[28:31], v[144:147], v[204:207], v[28:31]
	v_mfma_f32_16x16x32_bf16 v[24:27], v[160:163], v[204:207], v[24:27]
	v_mfma_f32_16x16x32_bf16 v[12:15], v[144:147], v[212:215], v[12:15]
	v_mfma_f32_16x16x32_bf16 v[8:11], v[160:163], v[212:215], v[8:11]
	v_mfma_f32_16x16x32_bf16 v[60:63], v[156:159], v[192:195], v[60:63]
	v_mfma_f32_16x16x32_bf16 v[56:59], v[164:167], v[192:195], v[56:59]
	v_mfma_f32_16x16x32_bf16 v[44:47], v[156:159], v[200:203], v[44:47]
	v_mfma_f32_16x16x32_bf16 v[40:43], v[164:167], v[200:203], v[40:43]
	v_mfma_f32_16x16x32_bf16 v[28:31], v[156:159], v[208:211], v[28:31]
	v_mfma_f32_16x16x32_bf16 v[24:27], v[164:167], v[208:211], v[24:27]
	v_mfma_f32_16x16x32_bf16 v[12:15], v[156:159], v[216:219], v[12:15]
	v_mfma_f32_16x16x32_bf16 v[8:11], v[164:167], v[216:219], v[8:11]
	s_setprio 0
	s_setprio 1
	v_mfma_f32_16x16x32_bf16 v[52:55], v[168:171], v[188:191], v[52:55]
	v_mfma_f32_16x16x32_bf16 v[48:51], v[180:183], v[188:191], v[48:51]
	v_mfma_f32_16x16x32_bf16 v[36:39], v[168:171], v[196:199], v[36:39]
	v_mfma_f32_16x16x32_bf16 v[32:35], v[180:183], v[196:199], v[32:35]
	v_mfma_f32_16x16x32_bf16 v[20:23], v[168:171], v[204:207], v[20:23]
	v_mfma_f32_16x16x32_bf16 v[16:19], v[180:183], v[204:207], v[16:19]
	v_mfma_f32_16x16x32_bf16 v[4:7], v[168:171], v[212:215], v[4:7]
	v_mfma_f32_16x16x32_bf16 v[0:3], v[180:183], v[212:215], v[0:3]
	v_mfma_f32_16x16x32_bf16 v[52:55], v[176:179], v[192:195], v[52:55]
	v_mfma_f32_16x16x32_bf16 v[48:51], v[184:187], v[192:195], v[48:51]
	v_mfma_f32_16x16x32_bf16 v[36:39], v[176:179], v[200:203], v[36:39]
	v_mfma_f32_16x16x32_bf16 v[32:35], v[184:187], v[200:203], v[32:35]
	v_mfma_f32_16x16x32_bf16 v[20:23], v[176:179], v[208:211], v[20:23]
	v_mfma_f32_16x16x32_bf16 v[16:19], v[184:187], v[208:211], v[16:19]
	v_mfma_f32_16x16x32_bf16 v[4:7], v[176:179], v[216:219], v[4:7]
	v_mfma_f32_16x16x32_bf16 v[0:3], v[184:187], v[216:219], v[0:3]
	s_setprio 0
	s_barrier
	s_add_i32 s52, 0, 0x18000
	v_add_u32_e32 v155, s52, v149
	s_add_i32 s53, 0, 0x1c000
	ds_read_b128 v[144:147], v155
	ds_read_b128 v[156:159], v155 offset:1024
	ds_read_b128 v[160:163], v155 offset:2048
	ds_read_b128 v[164:167], v155 offset:3072
	v_add_u32_e32 v155, s53, v149
	ds_read_b128 v[168:171], v155
	ds_read_b128 v[176:179], v155 offset:1024
	ds_read_b128 v[180:183], v155 offset:2048
	ds_read_b128 v[184:187], v155 offset:3072
	s_add_u32 s26, s34, 0xb0000
	s_addc_u32 s27, s35, 0
	s_mov_b32 m0, s36
	v_lshl_add_u64 v[226:227], s[26:27], 0, v[128:129]
	ds_read_b128 v[188:191], v153 offset:32768
	ds_read_b128 v[192:195], v153 offset:33792
	ds_read_b128 v[196:199], v153 offset:34816
	ds_read_b128 v[200:203], v153 offset:35840
	ds_read_b128 v[204:207], v153 offset:36864
	ds_read_b128 v[208:211], v153 offset:37888
	ds_read_b128 v[212:215], v153 offset:38912
	ds_read_b128 v[216:219], v153 offset:39936
	global_load_lds_dwordx4 v[226:227], off
	v_lshl_add_u64 v[226:227], s[26:27], 0, v[132:133]
	s_mov_b32 m0, s37
	s_nop 0
	global_load_lds_dwordx4 v[226:227], off
	s_waitcnt vmcnt(8)
	s_waitcnt lgkmcnt(0)
	s_barrier
	s_setprio 1
	s_waitcnt lgkmcnt(0)
	v_mfma_f32_16x16x32_bf16 v[124:127], v[144:147], v[188:191], v[124:127]
	v_mfma_f32_16x16x32_bf16 v[120:123], v[160:163], v[188:191], v[120:123]
	v_mfma_f32_16x16x32_bf16 v[108:111], v[144:147], v[196:199], v[108:111]
	v_mfma_f32_16x16x32_bf16 v[104:107], v[160:163], v[196:199], v[104:107]
	v_mfma_f32_16x16x32_bf16 v[92:95], v[144:147], v[204:207], v[92:95]
	v_mfma_f32_16x16x32_bf16 v[88:91], v[160:163], v[204:207], v[88:91]
	v_mfma_f32_16x16x32_bf16 v[76:79], v[144:147], v[212:215], v[76:79]
	v_mfma_f32_16x16x32_bf16 v[72:75], v[160:163], v[212:215], v[72:75]
	v_mfma_f32_16x16x32_bf16 v[124:127], v[156:159], v[192:195], v[124:127]
	v_mfma_f32_16x16x32_bf16 v[120:123], v[164:167], v[192:195], v[120:123]
	v_mfma_f32_16x16x32_bf16 v[108:111], v[156:159], v[200:203], v[108:111]
	v_mfma_f32_16x16x32_bf16 v[104:107], v[164:167], v[200:203], v[104:107]
	v_mfma_f32_16x16x32_bf16 v[92:95], v[156:159], v[208:211], v[92:95]
	v_mfma_f32_16x16x32_bf16 v[88:91], v[164:167], v[208:211], v[88:91]
	v_mfma_f32_16x16x32_bf16 v[76:79], v[156:159], v[216:219], v[76:79]
	v_mfma_f32_16x16x32_bf16 v[72:75], v[164:167], v[216:219], v[72:75]
	s_setprio 0
	s_setprio 1
	v_mfma_f32_16x16x32_bf16 v[116:119], v[168:171], v[188:191], v[116:119]
	v_mfma_f32_16x16x32_bf16 v[112:115], v[180:183], v[188:191], v[112:115]
	v_mfma_f32_16x16x32_bf16 v[100:103], v[168:171], v[196:199], v[100:103]
	v_mfma_f32_16x16x32_bf16 v[96:99], v[180:183], v[196:199], v[96:99]
	v_mfma_f32_16x16x32_bf16 v[84:87], v[168:171], v[204:207], v[84:87]
	v_mfma_f32_16x16x32_bf16 v[80:83], v[180:183], v[204:207], v[80:83]
	v_mfma_f32_16x16x32_bf16 v[68:71], v[168:171], v[212:215], v[68:71]
	v_mfma_f32_16x16x32_bf16 v[64:67], v[180:183], v[212:215], v[64:67]
	v_mfma_f32_16x16x32_bf16 v[116:119], v[176:179], v[192:195], v[116:119]
	v_mfma_f32_16x16x32_bf16 v[112:115], v[184:187], v[192:195], v[112:115]
	v_mfma_f32_16x16x32_bf16 v[100:103], v[176:179], v[200:203], v[100:103]
	v_mfma_f32_16x16x32_bf16 v[96:99], v[184:187], v[200:203], v[96:99]
	v_mfma_f32_16x16x32_bf16 v[84:87], v[176:179], v[208:211], v[84:87]
	v_mfma_f32_16x16x32_bf16 v[80:83], v[184:187], v[208:211], v[80:83]
	v_mfma_f32_16x16x32_bf16 v[68:71], v[176:179], v[216:219], v[68:71]
	v_mfma_f32_16x16x32_bf16 v[64:67], v[184:187], v[216:219], v[64:67]
	s_setprio 0
	s_barrier
	s_add_i32 s26, s52, s15
	v_lshl_add_u64 v[172:173], v[172:173], 0, s[20:21]
	s_mov_b32 m0, s26
	ds_read_b128 v[188:191], v153 offset:49152
	ds_read_b128 v[192:195], v153 offset:50176
	ds_read_b128 v[196:199], v153 offset:51200
	ds_read_b128 v[200:203], v153 offset:52224
	ds_read_b128 v[204:207], v153 offset:53248
	ds_read_b128 v[208:211], v153 offset:54272
	ds_read_b128 v[212:215], v153 offset:55296
	ds_read_b128 v[216:219], v153 offset:56320
	global_load_lds_dwordx4 v[172:173], off
	s_add_i32 m0, s26, 0x2000
	s_add_u32 s26, s30, 0xb0080
	v_lshl_add_u64 v[172:173], v[220:221], 0, s[20:21]
	s_addc_u32 s27, s31, 0
	s_add_i32 s30, s53, s15
	global_load_lds_dwordx4 v[172:173], off
	v_lshl_add_u64 v[172:173], s[26:27], 0, v[130:131]
	s_mov_b32 m0, s30
	s_nop 0
	global_load_lds_dwordx4 v[172:173], off
	v_lshl_add_u64 v[172:173], s[26:27], 0, v[134:135]
	s_add_i32 m0, s30, 0x2000
	s_nop 0
	global_load_lds_dwordx4 v[172:173], off
	v_lshl_add_u64 v[172:173], v[222:223], 0, s[20:21]
	s_mov_b32 m0, s39
	s_nop 0
	global_load_lds_dwordx4 v[172:173], off
	v_lshl_add_u64 v[172:173], v[224:225], 0, s[20:21]
	s_mov_b32 m0, s40
	s_nop 0
	global_load_lds_dwordx4 v[172:173], off
	s_waitcnt vmcnt(8)
	s_waitcnt lgkmcnt(0)
	s_barrier
	s_setprio 1
	s_waitcnt lgkmcnt(0)
	v_mfma_f32_16x16x32_bf16 v[60:63], v[144:147], v[188:191], v[60:63]
	v_mfma_f32_16x16x32_bf16 v[56:59], v[160:163], v[188:191], v[56:59]
	v_mfma_f32_16x16x32_bf16 v[44:47], v[144:147], v[196:199], v[44:47]
	v_mfma_f32_16x16x32_bf16 v[40:43], v[160:163], v[196:199], v[40:43]
	v_mfma_f32_16x16x32_bf16 v[28:31], v[144:147], v[204:207], v[28:31]
	v_mfma_f32_16x16x32_bf16 v[24:27], v[160:163], v[204:207], v[24:27]
	v_mfma_f32_16x16x32_bf16 v[12:15], v[144:147], v[212:215], v[12:15]
	v_mfma_f32_16x16x32_bf16 v[8:11], v[160:163], v[212:215], v[8:11]
	v_mfma_f32_16x16x32_bf16 v[60:63], v[156:159], v[192:195], v[60:63]
	v_mfma_f32_16x16x32_bf16 v[56:59], v[164:167], v[192:195], v[56:59]
	v_mfma_f32_16x16x32_bf16 v[44:47], v[156:159], v[200:203], v[44:47]
	v_mfma_f32_16x16x32_bf16 v[40:43], v[164:167], v[200:203], v[40:43]
	v_mfma_f32_16x16x32_bf16 v[28:31], v[156:159], v[208:211], v[28:31]
	v_mfma_f32_16x16x32_bf16 v[24:27], v[164:167], v[208:211], v[24:27]
	v_mfma_f32_16x16x32_bf16 v[12:15], v[156:159], v[216:219], v[12:15]
	v_mfma_f32_16x16x32_bf16 v[8:11], v[164:167], v[216:219], v[8:11]
	s_setprio 0
	s_setprio 1
	v_mfma_f32_16x16x32_bf16 v[52:55], v[168:171], v[188:191], v[52:55]
	v_mfma_f32_16x16x32_bf16 v[48:51], v[180:183], v[188:191], v[48:51]
	v_mfma_f32_16x16x32_bf16 v[36:39], v[168:171], v[196:199], v[36:39]
	v_mfma_f32_16x16x32_bf16 v[32:35], v[180:183], v[196:199], v[32:35]
	v_mfma_f32_16x16x32_bf16 v[20:23], v[168:171], v[204:207], v[20:23]
	v_mfma_f32_16x16x32_bf16 v[16:19], v[180:183], v[204:207], v[16:19]
	v_mfma_f32_16x16x32_bf16 v[4:7], v[168:171], v[212:215], v[4:7]
	v_mfma_f32_16x16x32_bf16 v[0:3], v[180:183], v[212:215], v[0:3]
	v_mfma_f32_16x16x32_bf16 v[52:55], v[176:179], v[192:195], v[52:55]
	v_mfma_f32_16x16x32_bf16 v[48:51], v[184:187], v[192:195], v[48:51]
	v_mfma_f32_16x16x32_bf16 v[36:39], v[176:179], v[200:203], v[36:39]
	v_mfma_f32_16x16x32_bf16 v[32:35], v[184:187], v[200:203], v[32:35]
	v_mfma_f32_16x16x32_bf16 v[20:23], v[176:179], v[208:211], v[20:23]
	v_mfma_f32_16x16x32_bf16 v[16:19], v[184:187], v[208:211], v[16:19]
	v_mfma_f32_16x16x32_bf16 v[4:7], v[176:179], v[216:219], v[4:7]
	v_mfma_f32_16x16x32_bf16 v[0:3], v[184:187], v[216:219], v[0:3]
	s_setprio 0
	s_add_i32 s51, s51, 2
	s_add_u32 s49, s49, 0x100
	s_addc_u32 s50, s50, 0
	s_cmp_gt_u32 s51, 41
	s_mov_b64 s[26:27], s[28:29]
	s_barrier
	s_cbranch_scc0 .LBB0_1684
